# E22 variant: weight-fragment runs of 4 chains, snake order over the activation fragments so every consecutive chain shares one operand pair
# baseline (speedup 1.0000x reference)
;     __device__ __forceinline__ int nt(const Unit& u) const { return (u.pn >> 1) < 2 ? 22 : 20; }
; #define PG8_STAGE(bufoff, gbase, voff) do { _Pragma("unroll") for (int _i = 0; _i < 2; ++_i) \
;         __builtin_amdgcn_global_load_lds((const unsigned*)((const char*)(gbase) + (voff)[_i]), (LAS unsigned*)(lds + (bufoff) + ldsw + _i * 8192), 16, 0, 0); } while (0)
; #define PG8_LDA(dst, b, h) do { _Pragma("unroll") for (int m = 0; m < 4; ++m) _Pragma("unroll") for (int k = 0; k < 2; ++k) dst[m][k] = *(const LAS bf16x8*)(pA + PG8_SA(b, h) + m * 2048 + k * 1024); } while (0)
; #define PG8_LDB(dst, b, h) do { _Pragma("unroll") for (int n = 0; n < 2; ++n) _Pragma("unroll") for (int k = 0; k < 2; ++k) dst[n][k] = *(const LAS bf16x8*)(pB + (PG8_SB(b, h) - 4 * HTB) + n * 2048 + k * 1024); } while (0)
; #define PG8_MMA(ai, bj, At, Bt) do { __builtin_amdgcn_s_setprio(1); _Pragma("unroll") for (int m = 0; m < 4; ++m) _Pragma("unroll") for (int n = 0; n < 2; ++n) _Pragma("unroll") for (int k = 0; k < 2; ++k) \
;         acc[ai][bj][m][n] = __builtin_amdgcn_mfma_f32_16x16x32_bf16(Bt[n][k], At[m][k], acc[ai][bj][m][n], 0, 0, 0); __builtin_amdgcn_s_setprio(0); } while (0)
; #define PG8_WAIT_V(n) asm volatile("s_waitcnt vmcnt(" #n ")" ::: "memory")
; #define PG8_BAR __builtin_amdgcn_s_barrier()
; template <class Desc, class Epi, bool ALIGN_EPI>
; __device__ __forceinline__ void gemm_phase(LAS unsigned char* lds, const Desc& D, const Epi& E, int G, int c) {
;     ...
;         for (int t = 0; t < nt; t += 2) {
;             const bool last = (t == nt - 2);
;             if (last && has_next) PG8_AWAIT(nxt);
;             const char* a1 = cA + (size_t)(t + 1) * kstep;
;             const char* a2 = last ? nA : cA + (size_t)(t + 2) * kstep; const char* b2 = last ? nB : cB + (size_t)(t + 2) * kstep;
;             const char* a3 = a2 + kstep; const char* b3 = b2 + kstep;
;             PG8_LDB(B0, 0, 0); PG8_LDB(B1, 0, 1); PG8_SCHED; PG8_LDA(At, 0, 0); PG8_STAGE(PG8_SA(1, 1), a1 + hstepA, voffA);
;             PG8_WAIT_V(8); PG8_WAIT_L(0); PG8_BAR; PG8_MMA(0, 0, At, B0); PG8_MMA(0, 1, At, B1); PG8_BAR; PG8_SCHED;
;             PG8_LDA(At, 0, 1); PG8_STAGE(PG8_SB(0, 0), b2, voffB); PG8_STAGE(PG8_SB(0, 1), b2 + hstepB, voffB); PG8_STAGE(PG8_SA(0, 0), a2, voffA);
;             PG8_WAIT_V(8); PG8_WAIT_L(0); PG8_BAR; PG8_MMA(1, 0, At, B0); PG8_MMA(1, 1, At, B1); PG8_BAR; PG8_SCHED;
.LBB0_172:
	s_or_b32 s14, s17, 1
	s_lshl_b64 s[26:27], s[14:15], 7
	s_add_i32 s14, s17, 2
	s_lshl_b64 s[40:41], s[14:15], 7
	s_add_u32 s17, s12, s40
	ds_read_b128 v[134:137], v169
	ds_read_b128 v[138:141], v169 offset:1024
	ds_read_b128 v[142:145], v169 offset:2048
	ds_read_b128 v[146:149], v169 offset:3072
	ds_read_b128 v[160:163], v169 offset:16384
	ds_read_b128 v[164:167], v169 offset:17408
	ds_read_b128 v[174:177], v169 offset:18432
	ds_read_b128 v[178:181], v169 offset:19456
	s_addc_u32 s21, s13, s41
	s_and_b64 s[38:39], s[30:31], exec
	s_cselect_b32 s39, s61, s21
	s_cselect_b32 s38, s60, s17
	s_add_u32 s17, s18, s40
	s_addc_u32 s21, s19, s41
	s_and_b64 s[30:31], s[30:31], exec
	s_cselect_b32 s31, s63, s21
	s_cselect_b32 s30, s62, s17
	s_add_u32 s17, s12, s26
	s_addc_u32 s21, s13, s27
	s_add_u32 s26, s17, 0x100000
	s_addc_u32 s27, s21, 0
	s_mov_b32 m0, s50
	v_lshl_add_u64 v[150:151], s[26:27], 0, v[152:153]
	ds_read_b128 v[182:185], v168
	ds_read_b128 v[186:189], v168 offset:1024
	ds_read_b128 v[190:193], v168 offset:2048
	ds_read_b128 v[194:197], v168 offset:3072
	ds_read_b128 v[198:201], v168 offset:4096
	ds_read_b128 v[202:205], v168 offset:5120
	ds_read_b128 v[206:209], v168 offset:6144
	ds_read_b128 v[210:213], v168 offset:7168
	global_load_lds_dwordx4 v[150:151], off
	v_lshl_add_u64 v[150:151], s[26:27], 0, v[156:157]
	s_mov_b32 m0, s51
	s_nop 0
	global_load_lds_dwordx4 v[150:151], off
	s_waitcnt vmcnt(8)
	s_waitcnt lgkmcnt(0)
	s_barrier
	v_mfma_f32_16x16x32_bf16 v[128:131], v[134:137], v[182:185], v[128:131]
	v_mfma_f32_16x16x32_bf16 v[128:131], v[138:141], v[186:189], v[128:131]
	v_mfma_f32_16x16x32_bf16 v[120:123], v[134:137], v[190:193], v[120:123]
	v_mfma_f32_16x16x32_bf16 v[120:123], v[138:141], v[194:197], v[120:123]
	v_mfma_f32_16x16x32_bf16 v[112:115], v[134:137], v[198:201], v[112:115]
	v_mfma_f32_16x16x32_bf16 v[112:115], v[138:141], v[202:205], v[112:115]
	v_mfma_f32_16x16x32_bf16 v[104:107], v[134:137], v[206:209], v[104:107]
	v_mfma_f32_16x16x32_bf16 v[104:107], v[138:141], v[210:213], v[104:107]
	v_mfma_f32_16x16x32_bf16 v[100:103], v[142:145], v[206:209], v[100:103]
	v_mfma_f32_16x16x32_bf16 v[100:103], v[146:149], v[210:213], v[100:103]
	v_mfma_f32_16x16x32_bf16 v[108:111], v[142:145], v[198:201], v[108:111]
	v_mfma_f32_16x16x32_bf16 v[108:111], v[146:149], v[202:205], v[108:111]
	v_mfma_f32_16x16x32_bf16 v[116:119], v[142:145], v[190:193], v[116:119]
	v_mfma_f32_16x16x32_bf16 v[116:119], v[146:149], v[194:197], v[116:119]
	v_mfma_f32_16x16x32_bf16 v[124:127], v[142:145], v[182:185], v[124:127]
	v_mfma_f32_16x16x32_bf16 v[124:127], v[146:149], v[186:189], v[124:127]
	v_mfma_f32_16x16x32_bf16 v[96:99], v[160:163], v[182:185], v[96:99]
	v_mfma_f32_16x16x32_bf16 v[96:99], v[164:167], v[186:189], v[96:99]
	v_mfma_f32_16x16x32_bf16 v[88:91], v[160:163], v[190:193], v[88:91]
	v_mfma_f32_16x16x32_bf16 v[88:91], v[164:167], v[194:197], v[88:91]
	v_mfma_f32_16x16x32_bf16 v[80:83], v[160:163], v[198:201], v[80:83]
	v_mfma_f32_16x16x32_bf16 v[80:83], v[164:167], v[202:205], v[80:83]
	v_mfma_f32_16x16x32_bf16 v[72:75], v[160:163], v[206:209], v[72:75]
	v_mfma_f32_16x16x32_bf16 v[72:75], v[164:167], v[210:213], v[72:75]
	v_mfma_f32_16x16x32_bf16 v[68:71], v[174:177], v[206:209], v[68:71]
	v_mfma_f32_16x16x32_bf16 v[68:71], v[178:181], v[210:213], v[68:71]
	v_mfma_f32_16x16x32_bf16 v[76:79], v[174:177], v[198:201], v[76:79]
	v_mfma_f32_16x16x32_bf16 v[76:79], v[178:181], v[202:205], v[76:79]
	v_mfma_f32_16x16x32_bf16 v[84:87], v[174:177], v[190:193], v[84:87]
	v_mfma_f32_16x16x32_bf16 v[84:87], v[178:181], v[194:197], v[84:87]
	v_mfma_f32_16x16x32_bf16 v[92:95], v[174:177], v[182:185], v[92:95]
	v_mfma_f32_16x16x32_bf16 v[92:95], v[178:181], v[186:189], v[92:95]
	s_barrier
	s_mov_b32 m0, s84
	v_lshl_add_u64 v[150:151], s[30:31], 0, v[154:155]
	s_add_u32 s26, s30, 0x100000
	ds_read_b128 v[182:185], v168 offset:16384
	ds_read_b128 v[186:189], v168 offset:17408
	ds_read_b128 v[190:193], v168 offset:18432
	ds_read_b128 v[194:197], v168 offset:19456
	ds_read_b128 v[198:201], v168 offset:20480
	ds_read_b128 v[202:205], v168 offset:21504
	ds_read_b128 v[206:209], v168 offset:22528
	ds_read_b128 v[210:213], v168 offset:23552
	global_load_lds_dwordx4 v[150:151], off
	v_lshl_add_u64 v[214:215], s[30:31], 0, v[158:159]
	s_mov_b32 m0, s85
	s_addc_u32 s27, s31, 0
	global_load_lds_dwordx4 v[214:215], off
	v_lshl_add_u64 v[216:217], s[26:27], 0, v[154:155]
	s_mov_b32 m0, s86
	v_lshl_add_u64 v[218:219], s[38:39], 0, v[156:157]
	global_load_lds_dwordx4 v[216:217], off
	v_lshl_add_u64 v[216:217], s[26:27], 0, v[158:159]
	s_mov_b32 m0, s87
	s_nop 0
	global_load_lds_dwordx4 v[216:217], off
	v_lshl_add_u64 v[216:217], s[38:39], 0, v[152:153]
	s_mov_b32 m0, s83
	s_nop 0
	global_load_lds_dwordx4 v[216:217], off
	s_mov_b32 m0, s88
	s_nop 0
	global_load_lds_dwordx4 v[218:219], off
	s_waitcnt vmcnt(8)
	s_waitcnt lgkmcnt(0)
	s_barrier
; #define PG8_STAGE(bufoff, gbase, voff) do { _Pragma("unroll") for (int _i = 0; _i < 2; ++_i) \
;         __builtin_amdgcn_global_load_lds((const unsigned*)((const char*)(gbase) + (voff)[_i]), (LAS unsigned*)(lds + (bufoff) + ldsw + _i * 8192), 16, 0, 0); } while (0)
; #define PG8_LDA(dst, b, h) do { _Pragma("unroll") for (int m = 0; m < 4; ++m) _Pragma("unroll") for (int k = 0; k < 2; ++k) dst[m][k] = *(const LAS bf16x8*)(pA + PG8_SA(b, h) + m * 2048 + k * 1024); } while (0)
; #define PG8_LDB(dst, b, h) do { _Pragma("unroll") for (int n = 0; n < 2; ++n) _Pragma("unroll") for (int k = 0; k < 2; ++k) dst[n][k] = *(const LAS bf16x8*)(pB + (PG8_SB(b, h) - 4 * HTB) + n * 2048 + k * 1024); } while (0)
; #define PG8_MMA(ai, bj, At, Bt) do { __builtin_amdgcn_s_setprio(1); _Pragma("unroll") for (int m = 0; m < 4; ++m) _Pragma("unroll") for (int n = 0; n < 2; ++n) _Pragma("unroll") for (int k = 0; k < 2; ++k) \
;         acc[ai][bj][m][n] = __builtin_amdgcn_mfma_f32_16x16x32_bf16(Bt[n][k], At[m][k], acc[ai][bj][m][n], 0, 0, 0); __builtin_amdgcn_s_setprio(0); } while (0)
; #define PG8_WAIT_V(n) asm volatile("s_waitcnt vmcnt(" #n ")" ::: "memory")
; #define PG8_WAIT_L(n) asm volatile("s_waitcnt lgkmcnt(" #n ")" ::: "memory")
; #define PG8_BAR __builtin_amdgcn_s_barrier()
; #define PG8_SCHED __builtin_amdgcn_sched_barrier(0)
; template <class Desc, class Epi, bool ALIGN_EPI>
; __device__ __forceinline__ void gemm_phase(LAS unsigned char* lds, const Desc& D, const Epi& E, int G, int c) {
;     ...
;             PG8_WAIT_V(8); PG8_WAIT_L(0); PG8_BAR; PG8_MMA(1, 0, At, B0); PG8_MMA(1, 1, At, B1); PG8_BAR; PG8_SCHED;
;             PG8_LDB(B0, 1, 0); PG8_LDB(B1, 1, 1); PG8_SCHED; PG8_LDA(At, 1, 0); PG8_STAGE(PG8_SA(0, 1), a2 + hstepA, voffA);
;             PG8_WAIT_V(8); PG8_WAIT_L(0); PG8_BAR; PG8_MMA(0, 0, At, B0); PG8_MMA(0, 1, At, B1); PG8_BAR; PG8_SCHED;
	v_mfma_f32_16x16x32_bf16 v[64:67], v[134:137], v[182:185], v[64:67]
	v_mfma_f32_16x16x32_bf16 v[64:67], v[138:141], v[186:189], v[64:67]
	v_mfma_f32_16x16x32_bf16 v[32:35], v[134:137], v[190:193], v[32:35]
	v_mfma_f32_16x16x32_bf16 v[32:35], v[138:141], v[194:197], v[32:35]
	v_mfma_f32_16x16x32_bf16 v[16:19], v[134:137], v[198:201], v[16:19]
	v_mfma_f32_16x16x32_bf16 v[16:19], v[138:141], v[202:205], v[16:19]
	v_mfma_f32_16x16x32_bf16 v[8:11], v[134:137], v[206:209], v[8:11]
	v_mfma_f32_16x16x32_bf16 v[8:11], v[138:141], v[210:213], v[8:11]
	v_mfma_f32_16x16x32_bf16 v[4:7], v[142:145], v[206:209], v[4:7]
	v_mfma_f32_16x16x32_bf16 v[4:7], v[146:149], v[210:213], v[4:7]
	v_mfma_f32_16x16x32_bf16 v[12:15], v[142:145], v[198:201], v[12:15]
	v_mfma_f32_16x16x32_bf16 v[12:15], v[146:149], v[202:205], v[12:15]
	v_mfma_f32_16x16x32_bf16 v[20:23], v[142:145], v[190:193], v[20:23]
	v_mfma_f32_16x16x32_bf16 v[20:23], v[146:149], v[194:197], v[20:23]
	v_mfma_f32_16x16x32_bf16 v[52:55], v[142:145], v[182:185], v[52:55]
	v_mfma_f32_16x16x32_bf16 v[52:55], v[146:149], v[186:189], v[52:55]
	v_mfma_f32_16x16x32_bf16 v[60:63], v[160:163], v[182:185], v[60:63]
	v_mfma_f32_16x16x32_bf16 v[60:63], v[164:167], v[186:189], v[60:63]
	v_mfma_f32_16x16x32_bf16 v[48:51], v[160:163], v[190:193], v[48:51]
	v_mfma_f32_16x16x32_bf16 v[48:51], v[164:167], v[194:197], v[48:51]
	v_mfma_f32_16x16x32_bf16 v[40:43], v[160:163], v[198:201], v[40:43]
	v_mfma_f32_16x16x32_bf16 v[40:43], v[164:167], v[202:205], v[40:43]
	v_mfma_f32_16x16x32_bf16 v[28:31], v[160:163], v[206:209], v[28:31]
	v_mfma_f32_16x16x32_bf16 v[28:31], v[164:167], v[210:213], v[28:31]
	v_mfma_f32_16x16x32_bf16 v[24:27], v[174:177], v[206:209], v[24:27]
	v_mfma_f32_16x16x32_bf16 v[24:27], v[178:181], v[210:213], v[24:27]
	v_mfma_f32_16x16x32_bf16 v[36:39], v[174:177], v[198:201], v[36:39]
	v_mfma_f32_16x16x32_bf16 v[36:39], v[178:181], v[202:205], v[36:39]
	v_mfma_f32_16x16x32_bf16 v[44:47], v[174:177], v[190:193], v[44:47]
	v_mfma_f32_16x16x32_bf16 v[44:47], v[178:181], v[194:197], v[44:47]
	v_mfma_f32_16x16x32_bf16 v[56:59], v[174:177], v[182:185], v[56:59]
	v_mfma_f32_16x16x32_bf16 v[56:59], v[178:181], v[186:189], v[56:59]
	s_barrier
	ds_read_b128 v[134:137], v169 offset:32768
	ds_read_b128 v[138:141], v169 offset:33792
	ds_read_b128 v[142:145], v169 offset:34816
	ds_read_b128 v[146:149], v169 offset:35840
	ds_read_b128 v[160:163], v169 offset:49152
	ds_read_b128 v[164:167], v169 offset:50176
	ds_read_b128 v[174:177], v169 offset:51200
	ds_read_b128 v[178:181], v169 offset:52224
	s_add_u32 s26, s38, 0x100000
	s_addc_u32 s27, s39, 0
	s_mov_b32 m0, s89
	v_lshl_add_u64 v[220:221], s[26:27], 0, v[152:153]
	ds_read_b128 v[182:185], v168 offset:32768
	ds_read_b128 v[186:189], v168 offset:33792
	ds_read_b128 v[190:193], v168 offset:34816
	ds_read_b128 v[194:197], v168 offset:35840
	ds_read_b128 v[198:201], v168 offset:36864
	ds_read_b128 v[202:205], v168 offset:37888
	ds_read_b128 v[206:209], v168 offset:38912
	ds_read_b128 v[210:213], v168 offset:39936
	global_load_lds_dwordx4 v[220:221], off
	v_lshl_add_u64 v[220:221], s[26:27], 0, v[156:157]
	s_mov_b32 m0, s90
	s_nop 0
	global_load_lds_dwordx4 v[220:221], off
	s_waitcnt vmcnt(8)
	s_waitcnt lgkmcnt(0)
	s_barrier
	v_mfma_f32_16x16x32_bf16 v[128:131], v[134:137], v[182:185], v[128:131]
	v_mfma_f32_16x16x32_bf16 v[128:131], v[138:141], v[186:189], v[128:131]
	v_mfma_f32_16x16x32_bf16 v[120:123], v[134:137], v[190:193], v[120:123]
	v_mfma_f32_16x16x32_bf16 v[120:123], v[138:141], v[194:197], v[120:123]
	v_mfma_f32_16x16x32_bf16 v[112:115], v[134:137], v[198:201], v[112:115]
	v_mfma_f32_16x16x32_bf16 v[112:115], v[138:141], v[202:205], v[112:115]
	v_mfma_f32_16x16x32_bf16 v[104:107], v[134:137], v[206:209], v[104:107]
	v_mfma_f32_16x16x32_bf16 v[104:107], v[138:141], v[210:213], v[104:107]
	v_mfma_f32_16x16x32_bf16 v[100:103], v[142:145], v[206:209], v[100:103]
	v_mfma_f32_16x16x32_bf16 v[100:103], v[146:149], v[210:213], v[100:103]
	v_mfma_f32_16x16x32_bf16 v[108:111], v[142:145], v[198:201], v[108:111]
	v_mfma_f32_16x16x32_bf16 v[108:111], v[146:149], v[202:205], v[108:111]
	v_mfma_f32_16x16x32_bf16 v[116:119], v[142:145], v[190:193], v[116:119]
	v_mfma_f32_16x16x32_bf16 v[116:119], v[146:149], v[194:197], v[116:119]
	v_mfma_f32_16x16x32_bf16 v[124:127], v[142:145], v[182:185], v[124:127]
	v_mfma_f32_16x16x32_bf16 v[124:127], v[146:149], v[186:189], v[124:127]
	v_mfma_f32_16x16x32_bf16 v[96:99], v[160:163], v[182:185], v[96:99]
	v_mfma_f32_16x16x32_bf16 v[96:99], v[164:167], v[186:189], v[96:99]
	v_mfma_f32_16x16x32_bf16 v[88:91], v[160:163], v[190:193], v[88:91]
	v_mfma_f32_16x16x32_bf16 v[88:91], v[164:167], v[194:197], v[88:91]
	v_mfma_f32_16x16x32_bf16 v[80:83], v[160:163], v[198:201], v[80:83]
	v_mfma_f32_16x16x32_bf16 v[80:83], v[164:167], v[202:205], v[80:83]
	v_mfma_f32_16x16x32_bf16 v[72:75], v[160:163], v[206:209], v[72:75]
	v_mfma_f32_16x16x32_bf16 v[72:75], v[164:167], v[210:213], v[72:75]
	v_mfma_f32_16x16x32_bf16 v[68:71], v[174:177], v[206:209], v[68:71]
	v_mfma_f32_16x16x32_bf16 v[68:71], v[178:181], v[210:213], v[68:71]
	v_mfma_f32_16x16x32_bf16 v[76:79], v[174:177], v[198:201], v[76:79]
	v_mfma_f32_16x16x32_bf16 v[76:79], v[178:181], v[202:205], v[76:79]
	v_mfma_f32_16x16x32_bf16 v[84:87], v[174:177], v[190:193], v[84:87]
	v_mfma_f32_16x16x32_bf16 v[84:87], v[178:181], v[194:197], v[84:87]
	v_mfma_f32_16x16x32_bf16 v[92:95], v[174:177], v[182:185], v[92:95]
	v_mfma_f32_16x16x32_bf16 v[92:95], v[178:181], v[186:189], v[92:95]
	s_barrier
;     __device__ __forceinline__ int nt(const Unit& u) const { return (u.pn >> 1) < 2 ? 22 : 20; }
; #define PG8_STAGE(bufoff, gbase, voff) do { _Pragma("unroll") for (int _i = 0; _i < 2; ++_i) \
;         __builtin_amdgcn_global_load_lds((const unsigned*)((const char*)(gbase) + (voff)[_i]), (LAS unsigned*)(lds + (bufoff) + ldsw + _i * 8192), 16, 0, 0); } while (0)
; #define PG8_LDA(dst, b, h) do { _Pragma("unroll") for (int m = 0; m < 4; ++m) _Pragma("unroll") for (int k = 0; k < 2; ++k) dst[m][k] = *(const LAS bf16x8*)(pA + PG8_SA(b, h) + m * 2048 + k * 1024); } while (0)
; #define PG8_MMA(ai, bj, At, Bt) do { __builtin_amdgcn_s_setprio(1); _Pragma("unroll") for (int m = 0; m < 4; ++m) _Pragma("unroll") for (int n = 0; n < 2; ++n) _Pragma("unroll") for (int k = 0; k < 2; ++k) \
;         acc[ai][bj][m][n] = __builtin_amdgcn_mfma_f32_16x16x32_bf16(Bt[n][k], At[m][k], acc[ai][bj][m][n], 0, 0, 0); __builtin_amdgcn_s_setprio(0); } while (0)
; #define PG8_WAIT_V(n) asm volatile("s_waitcnt vmcnt(" #n ")" ::: "memory")
; #define PG8_WAIT_L(n) asm volatile("s_waitcnt lgkmcnt(" #n ")" ::: "memory")
; #define PG8_BAR __builtin_amdgcn_s_barrier()
; #define PG8_SCHED __builtin_amdgcn_sched_barrier(0)
; template <class Desc, class Epi, bool ALIGN_EPI>
; __device__ __forceinline__ void gemm_phase(LAS unsigned char* lds, const Desc& D, const Epi& E, int G, int c) {
;     ...
;         for (int t = 0; t < nt; t += 2) {
;     ...
;             PG8_LDA(At, 1, 1); PG8_STAGE(PG8_SB(1, 0), b3, voffB); PG8_STAGE(PG8_SB(1, 1), b3 + hstepB, voffB); PG8_STAGE(PG8_SA(1, 0), a3, voffA);
;             PG8_WAIT_V(8); PG8_WAIT_L(0); PG8_BAR; PG8_MMA(1, 0, At, B0); PG8_MMA(1, 1, At, B1); PG8_BAR; PG8_SCHED;
;         }
	s_mov_b32 m0, s92
	v_lshl_add_u64 v[150:151], v[150:151], 0, s[76:77]
	s_add_u32 s26, s30, 0x100080
	ds_read_b128 v[182:185], v168 offset:49152
	ds_read_b128 v[186:189], v168 offset:50176
	ds_read_b128 v[190:193], v168 offset:51200
	ds_read_b128 v[194:197], v168 offset:52224
	ds_read_b128 v[198:201], v168 offset:53248
	ds_read_b128 v[202:205], v168 offset:54272
	ds_read_b128 v[206:209], v168 offset:55296
	ds_read_b128 v[210:213], v168 offset:56320
	global_load_lds_dwordx4 v[150:151], off
	v_lshl_add_u64 v[150:151], v[214:215], 0, s[76:77]
	s_mov_b32 m0, s93
	s_addc_u32 s27, s31, 0
	global_load_lds_dwordx4 v[150:151], off
	v_lshl_add_u64 v[150:151], s[26:27], 0, v[154:155]
	s_mov_b32 m0, s97
	s_nop 0
	global_load_lds_dwordx4 v[150:151], off
	v_lshl_add_u64 v[150:151], s[26:27], 0, v[158:159]
	s_mov_b32 m0, s82
	s_nop 0
	global_load_lds_dwordx4 v[150:151], off
	v_lshl_add_u64 v[150:151], v[216:217], 0, s[76:77]
	s_mov_b32 m0, s94
	s_nop 0
	global_load_lds_dwordx4 v[150:151], off
	v_lshl_add_u64 v[150:151], v[218:219], 0, s[76:77]
	s_mov_b32 m0, s95
	s_nop 0
	global_load_lds_dwordx4 v[150:151], off
	s_waitcnt vmcnt(8)
	s_waitcnt lgkmcnt(0)
	s_barrier
	v_mfma_f32_16x16x32_bf16 v[64:67], v[134:137], v[182:185], v[64:67]
	v_mfma_f32_16x16x32_bf16 v[64:67], v[138:141], v[186:189], v[64:67]
	v_mfma_f32_16x16x32_bf16 v[32:35], v[134:137], v[190:193], v[32:35]
	v_mfma_f32_16x16x32_bf16 v[32:35], v[138:141], v[194:197], v[32:35]
	v_mfma_f32_16x16x32_bf16 v[16:19], v[134:137], v[198:201], v[16:19]
	v_mfma_f32_16x16x32_bf16 v[16:19], v[138:141], v[202:205], v[16:19]
	v_mfma_f32_16x16x32_bf16 v[8:11], v[134:137], v[206:209], v[8:11]
	v_mfma_f32_16x16x32_bf16 v[8:11], v[138:141], v[210:213], v[8:11]
	v_mfma_f32_16x16x32_bf16 v[4:7], v[142:145], v[206:209], v[4:7]
	v_mfma_f32_16x16x32_bf16 v[4:7], v[146:149], v[210:213], v[4:7]
	v_mfma_f32_16x16x32_bf16 v[12:15], v[142:145], v[198:201], v[12:15]
	v_mfma_f32_16x16x32_bf16 v[12:15], v[146:149], v[202:205], v[12:15]
	v_mfma_f32_16x16x32_bf16 v[20:23], v[142:145], v[190:193], v[20:23]
	v_mfma_f32_16x16x32_bf16 v[20:23], v[146:149], v[194:197], v[20:23]
	v_mfma_f32_16x16x32_bf16 v[52:55], v[142:145], v[182:185], v[52:55]
	v_mfma_f32_16x16x32_bf16 v[52:55], v[146:149], v[186:189], v[52:55]
	v_mfma_f32_16x16x32_bf16 v[60:63], v[160:163], v[182:185], v[60:63]
	v_mfma_f32_16x16x32_bf16 v[60:63], v[164:167], v[186:189], v[60:63]
	v_mfma_f32_16x16x32_bf16 v[48:51], v[160:163], v[190:193], v[48:51]
	v_mfma_f32_16x16x32_bf16 v[48:51], v[164:167], v[194:197], v[48:51]
	v_mfma_f32_16x16x32_bf16 v[40:43], v[160:163], v[198:201], v[40:43]
	v_mfma_f32_16x16x32_bf16 v[40:43], v[164:167], v[202:205], v[40:43]
	v_mfma_f32_16x16x32_bf16 v[28:31], v[160:163], v[206:209], v[28:31]
	v_mfma_f32_16x16x32_bf16 v[28:31], v[164:167], v[210:213], v[28:31]
	v_mfma_f32_16x16x32_bf16 v[24:27], v[174:177], v[206:209], v[24:27]
	v_mfma_f32_16x16x32_bf16 v[24:27], v[178:181], v[210:213], v[24:27]
	v_mfma_f32_16x16x32_bf16 v[36:39], v[174:177], v[198:201], v[36:39]
	v_mfma_f32_16x16x32_bf16 v[36:39], v[178:181], v[202:205], v[36:39]
	v_mfma_f32_16x16x32_bf16 v[44:47], v[174:177], v[190:193], v[44:47]
	v_mfma_f32_16x16x32_bf16 v[44:47], v[178:181], v[194:197], v[44:47]
	v_mfma_f32_16x16x32_bf16 v[56:59], v[174:177], v[182:185], v[56:59]
	v_mfma_f32_16x16x32_bf16 v[56:59], v[178:181], v[186:189], v[56:59]
	s_barrier
	s_cmp_ge_u32 s14, s3
	s_mov_b32 s17, s14
	s_cbranch_scc1 .LBB0_183

;     __device__ __forceinline__ int nt(const Unit& u) const { return (u.pn >> 1) < 2 ? 22 : 20; }
; #define PG8_STAGE(bufoff, gbase, voff) do { _Pragma("unroll") for (int _i = 0; _i < 2; ++_i) \
;         __builtin_amdgcn_global_load_lds((const unsigned*)((const char*)(gbase) + (voff)[_i]), (LAS unsigned*)(lds + (bufoff) + ldsw + _i * 8192), 16, 0, 0); } while (0)
; #define PG8_LDA(dst, b, h) do { _Pragma("unroll") for (int m = 0; m < 4; ++m) _Pragma("unroll") for (int k = 0; k < 2; ++k) dst[m][k] = *(const LAS bf16x8*)(pA + PG8_SA(b, h) + m * 2048 + k * 1024); } while (0)
; #define PG8_LDB(dst, b, h) do { _Pragma("unroll") for (int n = 0; n < 2; ++n) _Pragma("unroll") for (int k = 0; k < 2; ++k) dst[n][k] = *(const LAS bf16x8*)(pB + (PG8_SB(b, h) - 4 * HTB) + n * 2048 + k * 1024); } while (0)
; #define PG8_MMA(ai, bj, At, Bt) do { __builtin_amdgcn_s_setprio(1); _Pragma("unroll") for (int m = 0; m < 4; ++m) _Pragma("unroll") for (int n = 0; n < 2; ++n) _Pragma("unroll") for (int k = 0; k < 2; ++k) \
;         acc[ai][bj][m][n] = __builtin_amdgcn_mfma_f32_16x16x32_bf16(Bt[n][k], At[m][k], acc[ai][bj][m][n], 0, 0, 0); __builtin_amdgcn_s_setprio(0); } while (0)
; #define PG8_WAIT_V(n) asm volatile("s_waitcnt vmcnt(" #n ")" ::: "memory")
; #define PG8_BAR __builtin_amdgcn_s_barrier()
; template <class Desc, class Epi, bool ALIGN_EPI>
; __device__ __forceinline__ void gemm_phase(LAS unsigned char* lds, const Desc& D, const Epi& E, int G, int c) {
;     ...
;         for (int t = 0; t < nt; t += 2) {
;             const bool last = (t == nt - 2);
;             if (last && has_next) PG8_AWAIT(nxt);
;             const char* a1 = cA + (size_t)(t + 1) * kstep;
;             const char* a2 = last ? nA : cA + (size_t)(t + 2) * kstep; const char* b2 = last ? nB : cB + (size_t)(t + 2) * kstep;
;             const char* a3 = a2 + kstep; const char* b3 = b2 + kstep;
;             PG8_LDB(B0, 0, 0); PG8_LDB(B1, 0, 1); PG8_SCHED; PG8_LDA(At, 0, 0); PG8_STAGE(PG8_SA(1, 1), a1 + hstepA, voffA);
;             PG8_WAIT_V(8); PG8_WAIT_L(0); PG8_BAR; PG8_MMA(0, 0, At, B0); PG8_MMA(0, 1, At, B1); PG8_BAR; PG8_SCHED;
;             PG8_LDA(At, 0, 1); PG8_STAGE(PG8_SB(0, 0), b2, voffB); PG8_STAGE(PG8_SB(0, 1), b2 + hstepB, voffB); PG8_STAGE(PG8_SA(0, 0), a2, voffA);
;             PG8_WAIT_V(8); PG8_WAIT_L(0); PG8_BAR; PG8_MMA(1, 0, At, B0); PG8_MMA(1, 1, At, B1); PG8_BAR; PG8_SCHED;
.LBB0_603:
	ds_read_b128 v[144:147], v149
	ds_read_b128 v[152:155], v149 offset:1024
	ds_read_b128 v[156:159], v149 offset:2048
	ds_read_b128 v[160:163], v149 offset:3072
	ds_read_b128 v[164:167], v149 offset:16384
	ds_read_b128 v[168:171], v149 offset:17408
	ds_read_b128 v[172:175], v149 offset:18432
	ds_read_b128 v[176:179], v149 offset:19456
	s_add_u32 s16, s12, 0xfff80080
	s_addc_u32 s17, s13, -1
	s_cmp_eq_u32 s46, 4
	s_cselect_b32 s19, s9, s17
	s_cselect_b32 s18, s8, s16
	s_cselect_b32 s17, s11, s45
	s_cselect_b32 s16, s10, s7
	v_lshl_add_u64 v[212:213], s[12:13], 0, v[140:141]
	s_add_i32 m0, s20, 0xc000
	ds_read_b128 v[180:183], v148
	ds_read_b128 v[184:187], v148 offset:1024
	ds_read_b128 v[188:191], v148 offset:2048
	ds_read_b128 v[192:195], v148 offset:3072
	ds_read_b128 v[196:199], v148 offset:4096
	ds_read_b128 v[200:203], v148 offset:5120
	ds_read_b128 v[204:207], v148 offset:6144
	ds_read_b128 v[208:211], v148 offset:7168
	global_load_lds_dwordx4 v[212:213], off
	v_lshl_add_u64 v[212:213], s[12:13], 0, v[142:143]
	s_add_i32 m0, s20, 0xe000
	s_nop 0
	global_load_lds_dwordx4 v[212:213], off
	s_waitcnt vmcnt(8)
	s_waitcnt lgkmcnt(0)
	s_barrier
	v_mfma_f32_16x16x32_bf16 v[128:131], v[144:147], v[180:183], v[128:131]
	v_mfma_f32_16x16x32_bf16 v[128:131], v[152:155], v[184:187], v[128:131]
	v_mfma_f32_16x16x32_bf16 v[116:119], v[144:147], v[188:191], v[116:119]
	v_mfma_f32_16x16x32_bf16 v[116:119], v[152:155], v[192:195], v[116:119]
	v_mfma_f32_16x16x32_bf16 v[100:103], v[144:147], v[196:199], v[100:103]
	v_mfma_f32_16x16x32_bf16 v[100:103], v[152:155], v[200:203], v[100:103]
	v_mfma_f32_16x16x32_bf16 v[84:87], v[144:147], v[204:207], v[84:87]
	v_mfma_f32_16x16x32_bf16 v[84:87], v[152:155], v[208:211], v[84:87]
	v_mfma_f32_16x16x32_bf16 v[76:79], v[156:159], v[204:207], v[76:79]
	v_mfma_f32_16x16x32_bf16 v[76:79], v[160:163], v[208:211], v[76:79]
	v_mfma_f32_16x16x32_bf16 v[92:95], v[156:159], v[196:199], v[92:95]
	v_mfma_f32_16x16x32_bf16 v[92:95], v[160:163], v[200:203], v[92:95]
	v_mfma_f32_16x16x32_bf16 v[108:111], v[156:159], v[188:191], v[108:111]
	v_mfma_f32_16x16x32_bf16 v[108:111], v[160:163], v[192:195], v[108:111]
	v_mfma_f32_16x16x32_bf16 v[124:127], v[156:159], v[180:183], v[124:127]
	v_mfma_f32_16x16x32_bf16 v[124:127], v[160:163], v[184:187], v[124:127]
	v_mfma_f32_16x16x32_bf16 v[120:123], v[164:167], v[180:183], v[120:123]
	v_mfma_f32_16x16x32_bf16 v[120:123], v[168:171], v[184:187], v[120:123]
	v_mfma_f32_16x16x32_bf16 v[104:107], v[164:167], v[188:191], v[104:107]
	v_mfma_f32_16x16x32_bf16 v[104:107], v[168:171], v[192:195], v[104:107]
	v_mfma_f32_16x16x32_bf16 v[88:91], v[164:167], v[196:199], v[88:91]
	v_mfma_f32_16x16x32_bf16 v[88:91], v[168:171], v[200:203], v[88:91]
	v_mfma_f32_16x16x32_bf16 v[72:75], v[164:167], v[204:207], v[72:75]
	v_mfma_f32_16x16x32_bf16 v[72:75], v[168:171], v[208:211], v[72:75]
	v_mfma_f32_16x16x32_bf16 v[68:71], v[172:175], v[204:207], v[68:71]
	v_mfma_f32_16x16x32_bf16 v[68:71], v[176:179], v[208:211], v[68:71]
	v_mfma_f32_16x16x32_bf16 v[80:83], v[172:175], v[196:199], v[80:83]
	v_mfma_f32_16x16x32_bf16 v[80:83], v[176:179], v[200:203], v[80:83]
	v_mfma_f32_16x16x32_bf16 v[96:99], v[172:175], v[188:191], v[96:99]
	v_mfma_f32_16x16x32_bf16 v[96:99], v[176:179], v[192:195], v[96:99]
	v_mfma_f32_16x16x32_bf16 v[112:115], v[172:175], v[180:183], v[112:115]
	v_mfma_f32_16x16x32_bf16 v[112:115], v[176:179], v[184:187], v[112:115]
	s_barrier
	s_mov_b32 m0, s21
	v_lshl_add_u64 v[212:213], s[16:17], 0, v[136:137]
	s_add_u32 s48, s16, 0x20000
	ds_read_b128 v[180:183], v148 offset:16384
	ds_read_b128 v[184:187], v148 offset:17408
	ds_read_b128 v[188:191], v148 offset:18432
	ds_read_b128 v[192:195], v148 offset:19456
	ds_read_b128 v[196:199], v148 offset:20480
	ds_read_b128 v[200:203], v148 offset:21504
	ds_read_b128 v[204:207], v148 offset:22528
	ds_read_b128 v[208:211], v148 offset:23552
	global_load_lds_dwordx4 v[212:213], off
	v_lshl_add_u64 v[214:215], s[16:17], 0, v[132:133]
	s_mov_b32 m0, s23
	s_addc_u32 s49, s17, 0
	global_load_lds_dwordx4 v[214:215], off
	v_lshl_add_u64 v[216:217], s[48:49], 0, v[136:137]
	s_mov_b32 m0, s24
	v_lshl_add_u64 v[218:219], s[18:19], 0, v[134:135]
	global_load_lds_dwordx4 v[216:217], off
	v_lshl_add_u64 v[216:217], s[48:49], 0, v[132:133]
	s_mov_b32 m0, s25
	s_nop 0
	global_load_lds_dwordx4 v[216:217], off
	v_lshl_add_u64 v[216:217], s[18:19], 0, v[138:139]
	s_mov_b32 m0, s20
	s_nop 0
	global_load_lds_dwordx4 v[216:217], off
	s_mov_b32 m0, s26
	s_nop 0
	global_load_lds_dwordx4 v[218:219], off
	s_waitcnt vmcnt(8)
	s_waitcnt lgkmcnt(0)
	s_barrier
; #define PG8_STAGE(bufoff, gbase, voff) do { _Pragma("unroll") for (int _i = 0; _i < 2; ++_i) \
;         __builtin_amdgcn_global_load_lds((const unsigned*)((const char*)(gbase) + (voff)[_i]), (LAS unsigned*)(lds + (bufoff) + ldsw + _i * 8192), 16, 0, 0); } while (0)
; #define PG8_LDA(dst, b, h) do { _Pragma("unroll") for (int m = 0; m < 4; ++m) _Pragma("unroll") for (int k = 0; k < 2; ++k) dst[m][k] = *(const LAS bf16x8*)(pA + PG8_SA(b, h) + m * 2048 + k * 1024); } while (0)
; #define PG8_LDB(dst, b, h) do { _Pragma("unroll") for (int n = 0; n < 2; ++n) _Pragma("unroll") for (int k = 0; k < 2; ++k) dst[n][k] = *(const LAS bf16x8*)(pB + (PG8_SB(b, h) - 4 * HTB) + n * 2048 + k * 1024); } while (0)
; #define PG8_MMA(ai, bj, At, Bt) do { __builtin_amdgcn_s_setprio(1); _Pragma("unroll") for (int m = 0; m < 4; ++m) _Pragma("unroll") for (int n = 0; n < 2; ++n) _Pragma("unroll") for (int k = 0; k < 2; ++k) \
;         acc[ai][bj][m][n] = __builtin_amdgcn_mfma_f32_16x16x32_bf16(Bt[n][k], At[m][k], acc[ai][bj][m][n], 0, 0, 0); __builtin_amdgcn_s_setprio(0); } while (0)
; #define PG8_WAIT_V(n) asm volatile("s_waitcnt vmcnt(" #n ")" ::: "memory")
; #define PG8_WAIT_L(n) asm volatile("s_waitcnt lgkmcnt(" #n ")" ::: "memory")
; #define PG8_BAR __builtin_amdgcn_s_barrier()
; #define PG8_SCHED __builtin_amdgcn_sched_barrier(0)
; template <class Desc, class Epi, bool ALIGN_EPI>
; __device__ __forceinline__ void gemm_phase(LAS unsigned char* lds, const Desc& D, const Epi& E, int G, int c) {
;     ...
;             PG8_WAIT_V(8); PG8_WAIT_L(0); PG8_BAR; PG8_MMA(1, 0, At, B0); PG8_MMA(1, 1, At, B1); PG8_BAR; PG8_SCHED;
;             PG8_LDB(B0, 1, 0); PG8_LDB(B1, 1, 1); PG8_SCHED; PG8_LDA(At, 1, 0); PG8_STAGE(PG8_SA(0, 1), a2 + hstepA, voffA);
;             PG8_WAIT_V(8); PG8_WAIT_L(0); PG8_BAR; PG8_MMA(0, 0, At, B0); PG8_MMA(0, 1, At, B1); PG8_BAR; PG8_SCHED;
	v_mfma_f32_16x16x32_bf16 v[64:67], v[144:147], v[180:183], v[64:67]
	v_mfma_f32_16x16x32_bf16 v[64:67], v[152:155], v[184:187], v[64:67]
	v_mfma_f32_16x16x32_bf16 v[52:55], v[144:147], v[188:191], v[52:55]
	v_mfma_f32_16x16x32_bf16 v[52:55], v[152:155], v[192:195], v[52:55]
	v_mfma_f32_16x16x32_bf16 v[36:39], v[144:147], v[196:199], v[36:39]
	v_mfma_f32_16x16x32_bf16 v[36:39], v[152:155], v[200:203], v[36:39]
	v_mfma_f32_16x16x32_bf16 v[20:23], v[144:147], v[204:207], v[20:23]
	v_mfma_f32_16x16x32_bf16 v[20:23], v[152:155], v[208:211], v[20:23]
	v_mfma_f32_16x16x32_bf16 v[12:15], v[156:159], v[204:207], v[12:15]
	v_mfma_f32_16x16x32_bf16 v[12:15], v[160:163], v[208:211], v[12:15]
	v_mfma_f32_16x16x32_bf16 v[28:31], v[156:159], v[196:199], v[28:31]
	v_mfma_f32_16x16x32_bf16 v[28:31], v[160:163], v[200:203], v[28:31]
	v_mfma_f32_16x16x32_bf16 v[44:47], v[156:159], v[188:191], v[44:47]
	v_mfma_f32_16x16x32_bf16 v[44:47], v[160:163], v[192:195], v[44:47]
	v_mfma_f32_16x16x32_bf16 v[60:63], v[156:159], v[180:183], v[60:63]
	v_mfma_f32_16x16x32_bf16 v[60:63], v[160:163], v[184:187], v[60:63]
	v_mfma_f32_16x16x32_bf16 v[56:59], v[164:167], v[180:183], v[56:59]
	v_mfma_f32_16x16x32_bf16 v[56:59], v[168:171], v[184:187], v[56:59]
	v_mfma_f32_16x16x32_bf16 v[40:43], v[164:167], v[188:191], v[40:43]
	v_mfma_f32_16x16x32_bf16 v[40:43], v[168:171], v[192:195], v[40:43]
	v_mfma_f32_16x16x32_bf16 v[24:27], v[164:167], v[196:199], v[24:27]
	v_mfma_f32_16x16x32_bf16 v[24:27], v[168:171], v[200:203], v[24:27]
	v_mfma_f32_16x16x32_bf16 v[8:11], v[164:167], v[204:207], v[8:11]
	v_mfma_f32_16x16x32_bf16 v[8:11], v[168:171], v[208:211], v[8:11]
	v_mfma_f32_16x16x32_bf16 v[4:7], v[172:175], v[204:207], v[4:7]
	v_mfma_f32_16x16x32_bf16 v[4:7], v[176:179], v[208:211], v[4:7]
	v_mfma_f32_16x16x32_bf16 v[16:19], v[172:175], v[196:199], v[16:19]
	v_mfma_f32_16x16x32_bf16 v[16:19], v[176:179], v[200:203], v[16:19]
	v_mfma_f32_16x16x32_bf16 v[32:35], v[172:175], v[188:191], v[32:35]
	v_mfma_f32_16x16x32_bf16 v[32:35], v[176:179], v[192:195], v[32:35]
	v_mfma_f32_16x16x32_bf16 v[48:51], v[172:175], v[180:183], v[48:51]
	v_mfma_f32_16x16x32_bf16 v[48:51], v[176:179], v[184:187], v[48:51]
	s_barrier
	ds_read_b128 v[144:147], v149 offset:32768
	ds_read_b128 v[152:155], v149 offset:33792
	ds_read_b128 v[156:159], v149 offset:34816
	ds_read_b128 v[160:163], v149 offset:35840
	ds_read_b128 v[164:167], v149 offset:49152
	ds_read_b128 v[168:171], v149 offset:50176
	ds_read_b128 v[172:175], v149 offset:51200
	ds_read_b128 v[176:179], v149 offset:52224
	s_add_u32 s18, s18, 0x80000
	s_addc_u32 s19, s19, 0
	s_mov_b32 m0, s27
	v_lshl_add_u64 v[220:221], s[18:19], 0, v[138:139]
	ds_read_b128 v[180:183], v148 offset:32768
	ds_read_b128 v[184:187], v148 offset:33792
	ds_read_b128 v[188:191], v148 offset:34816
	ds_read_b128 v[192:195], v148 offset:35840
	ds_read_b128 v[196:199], v148 offset:36864
	ds_read_b128 v[200:203], v148 offset:37888
	ds_read_b128 v[204:207], v148 offset:38912
	ds_read_b128 v[208:211], v148 offset:39936
	global_load_lds_dwordx4 v[220:221], off
	v_lshl_add_u64 v[220:221], s[18:19], 0, v[134:135]
	s_mov_b32 m0, s30
	s_nop 0
	global_load_lds_dwordx4 v[220:221], off
	s_waitcnt vmcnt(8)
	s_waitcnt lgkmcnt(0)
	s_barrier
	v_mfma_f32_16x16x32_bf16 v[128:131], v[144:147], v[180:183], v[128:131]
	v_mfma_f32_16x16x32_bf16 v[128:131], v[152:155], v[184:187], v[128:131]
	v_mfma_f32_16x16x32_bf16 v[116:119], v[144:147], v[188:191], v[116:119]
	v_mfma_f32_16x16x32_bf16 v[116:119], v[152:155], v[192:195], v[116:119]
	v_mfma_f32_16x16x32_bf16 v[100:103], v[144:147], v[196:199], v[100:103]
	v_mfma_f32_16x16x32_bf16 v[100:103], v[152:155], v[200:203], v[100:103]
	v_mfma_f32_16x16x32_bf16 v[84:87], v[144:147], v[204:207], v[84:87]
	v_mfma_f32_16x16x32_bf16 v[84:87], v[152:155], v[208:211], v[84:87]
	v_mfma_f32_16x16x32_bf16 v[76:79], v[156:159], v[204:207], v[76:79]
	v_mfma_f32_16x16x32_bf16 v[76:79], v[160:163], v[208:211], v[76:79]
	v_mfma_f32_16x16x32_bf16 v[92:95], v[156:159], v[196:199], v[92:95]
	v_mfma_f32_16x16x32_bf16 v[92:95], v[160:163], v[200:203], v[92:95]
	v_mfma_f32_16x16x32_bf16 v[108:111], v[156:159], v[188:191], v[108:111]
	v_mfma_f32_16x16x32_bf16 v[108:111], v[160:163], v[192:195], v[108:111]
	v_mfma_f32_16x16x32_bf16 v[124:127], v[156:159], v[180:183], v[124:127]
	v_mfma_f32_16x16x32_bf16 v[124:127], v[160:163], v[184:187], v[124:127]
	v_mfma_f32_16x16x32_bf16 v[120:123], v[164:167], v[180:183], v[120:123]
	v_mfma_f32_16x16x32_bf16 v[120:123], v[168:171], v[184:187], v[120:123]
	v_mfma_f32_16x16x32_bf16 v[104:107], v[164:167], v[188:191], v[104:107]
	v_mfma_f32_16x16x32_bf16 v[104:107], v[168:171], v[192:195], v[104:107]
	v_mfma_f32_16x16x32_bf16 v[88:91], v[164:167], v[196:199], v[88:91]
	v_mfma_f32_16x16x32_bf16 v[88:91], v[168:171], v[200:203], v[88:91]
	v_mfma_f32_16x16x32_bf16 v[72:75], v[164:167], v[204:207], v[72:75]
	v_mfma_f32_16x16x32_bf16 v[72:75], v[168:171], v[208:211], v[72:75]
	v_mfma_f32_16x16x32_bf16 v[68:71], v[172:175], v[204:207], v[68:71]
	v_mfma_f32_16x16x32_bf16 v[68:71], v[176:179], v[208:211], v[68:71]
	v_mfma_f32_16x16x32_bf16 v[80:83], v[172:175], v[196:199], v[80:83]
	v_mfma_f32_16x16x32_bf16 v[80:83], v[176:179], v[200:203], v[80:83]
	v_mfma_f32_16x16x32_bf16 v[96:99], v[172:175], v[188:191], v[96:99]
	v_mfma_f32_16x16x32_bf16 v[96:99], v[176:179], v[192:195], v[96:99]
	v_mfma_f32_16x16x32_bf16 v[112:115], v[172:175], v[180:183], v[112:115]
	v_mfma_f32_16x16x32_bf16 v[112:115], v[176:179], v[184:187], v[112:115]
	s_barrier
;     __device__ __forceinline__ int nt(const Unit& u) const { return (u.pn >> 1) < 2 ? 22 : 20; }
; #define PG8_STAGE(bufoff, gbase, voff) do { _Pragma("unroll") for (int _i = 0; _i < 2; ++_i) \
;         __builtin_amdgcn_global_load_lds((const unsigned*)((const char*)(gbase) + (voff)[_i]), (LAS unsigned*)(lds + (bufoff) + ldsw + _i * 8192), 16, 0, 0); } while (0)
; #define PG8_LDA(dst, b, h) do { _Pragma("unroll") for (int m = 0; m < 4; ++m) _Pragma("unroll") for (int k = 0; k < 2; ++k) dst[m][k] = *(const LAS bf16x8*)(pA + PG8_SA(b, h) + m * 2048 + k * 1024); } while (0)
; #define PG8_MMA(ai, bj, At, Bt) do { __builtin_amdgcn_s_setprio(1); _Pragma("unroll") for (int m = 0; m < 4; ++m) _Pragma("unroll") for (int n = 0; n < 2; ++n) _Pragma("unroll") for (int k = 0; k < 2; ++k) \
;         acc[ai][bj][m][n] = __builtin_amdgcn_mfma_f32_16x16x32_bf16(Bt[n][k], At[m][k], acc[ai][bj][m][n], 0, 0, 0); __builtin_amdgcn_s_setprio(0); } while (0)
; #define PG8_WAIT_V(n) asm volatile("s_waitcnt vmcnt(" #n ")" ::: "memory")
; #define PG8_WAIT_L(n) asm volatile("s_waitcnt lgkmcnt(" #n ")" ::: "memory")
; #define PG8_BAR __builtin_amdgcn_s_barrier()
; #define PG8_SCHED __builtin_amdgcn_sched_barrier(0)
; template <class Desc, class Epi, bool ALIGN_EPI>
; __device__ __forceinline__ void gemm_phase(LAS unsigned char* lds, const Desc& D, const Epi& E, int G, int c) {
;     ...
;         for (int t = 0; t < nt; t += 2) {
;     ...
;             PG8_LDA(At, 1, 1); PG8_STAGE(PG8_SB(1, 0), b3, voffB); PG8_STAGE(PG8_SB(1, 1), b3 + hstepB, voffB); PG8_STAGE(PG8_SA(1, 0), a3, voffA);
;             PG8_WAIT_V(8); PG8_WAIT_L(0); PG8_BAR; PG8_MMA(1, 0, At, B0); PG8_MMA(1, 1, At, B1); PG8_BAR; PG8_SCHED;
;         }
;         if constexpr (ALIGN_EPI) { if (wr == 0) PG8_BAR; }
	s_mov_b32 m0, s31
	v_lshl_add_u64 v[212:213], v[212:213], 0, s[76:77]
	s_add_u32 s16, s16, 0x20080
	ds_read_b128 v[180:183], v148 offset:49152
	ds_read_b128 v[184:187], v148 offset:50176
	ds_read_b128 v[188:191], v148 offset:51200
	ds_read_b128 v[192:195], v148 offset:52224
	ds_read_b128 v[196:199], v148 offset:53248
	ds_read_b128 v[200:203], v148 offset:54272
	ds_read_b128 v[204:207], v148 offset:55296
	ds_read_b128 v[208:211], v148 offset:56320
	global_load_lds_dwordx4 v[212:213], off
	v_lshl_add_u64 v[212:213], v[214:215], 0, s[76:77]
	s_mov_b32 m0, s33
	s_addc_u32 s17, s17, 0
	global_load_lds_dwordx4 v[212:213], off
	v_lshl_add_u64 v[212:213], s[16:17], 0, v[136:137]
	s_mov_b32 m0, s38
	s_nop 0
	global_load_lds_dwordx4 v[212:213], off
	v_lshl_add_u64 v[212:213], s[16:17], 0, v[132:133]
	s_mov_b32 m0, s39
	s_nop 0
	global_load_lds_dwordx4 v[212:213], off
	v_lshl_add_u64 v[212:213], v[216:217], 0, s[76:77]
	s_mov_b32 m0, s34
	s_nop 0
	global_load_lds_dwordx4 v[212:213], off
	v_lshl_add_u64 v[212:213], v[218:219], 0, s[76:77]
	s_mov_b32 m0, s35
	s_nop 0
	global_load_lds_dwordx4 v[212:213], off
	s_waitcnt vmcnt(8)
	s_waitcnt lgkmcnt(0)
	s_barrier
	v_mfma_f32_16x16x32_bf16 v[64:67], v[144:147], v[180:183], v[64:67]
	v_mfma_f32_16x16x32_bf16 v[64:67], v[152:155], v[184:187], v[64:67]
	v_mfma_f32_16x16x32_bf16 v[52:55], v[144:147], v[188:191], v[52:55]
	v_mfma_f32_16x16x32_bf16 v[52:55], v[152:155], v[192:195], v[52:55]
	v_mfma_f32_16x16x32_bf16 v[36:39], v[144:147], v[196:199], v[36:39]
	v_mfma_f32_16x16x32_bf16 v[36:39], v[152:155], v[200:203], v[36:39]
	v_mfma_f32_16x16x32_bf16 v[20:23], v[144:147], v[204:207], v[20:23]
	v_mfma_f32_16x16x32_bf16 v[20:23], v[152:155], v[208:211], v[20:23]
	v_mfma_f32_16x16x32_bf16 v[12:15], v[156:159], v[204:207], v[12:15]
	v_mfma_f32_16x16x32_bf16 v[12:15], v[160:163], v[208:211], v[12:15]
	v_mfma_f32_16x16x32_bf16 v[28:31], v[156:159], v[196:199], v[28:31]
	v_mfma_f32_16x16x32_bf16 v[28:31], v[160:163], v[200:203], v[28:31]
	v_mfma_f32_16x16x32_bf16 v[44:47], v[156:159], v[188:191], v[44:47]
	v_mfma_f32_16x16x32_bf16 v[44:47], v[160:163], v[192:195], v[44:47]
	v_mfma_f32_16x16x32_bf16 v[60:63], v[156:159], v[180:183], v[60:63]
	v_mfma_f32_16x16x32_bf16 v[60:63], v[160:163], v[184:187], v[60:63]
	v_mfma_f32_16x16x32_bf16 v[56:59], v[164:167], v[180:183], v[56:59]
	v_mfma_f32_16x16x32_bf16 v[56:59], v[168:171], v[184:187], v[56:59]
	v_mfma_f32_16x16x32_bf16 v[40:43], v[164:167], v[188:191], v[40:43]
	v_mfma_f32_16x16x32_bf16 v[40:43], v[168:171], v[192:195], v[40:43]
	v_mfma_f32_16x16x32_bf16 v[24:27], v[164:167], v[196:199], v[24:27]
	v_mfma_f32_16x16x32_bf16 v[24:27], v[168:171], v[200:203], v[24:27]
	v_mfma_f32_16x16x32_bf16 v[8:11], v[164:167], v[204:207], v[8:11]
	v_mfma_f32_16x16x32_bf16 v[8:11], v[168:171], v[208:211], v[8:11]
	v_mfma_f32_16x16x32_bf16 v[4:7], v[172:175], v[204:207], v[4:7]
	v_mfma_f32_16x16x32_bf16 v[4:7], v[176:179], v[208:211], v[4:7]
	v_mfma_f32_16x16x32_bf16 v[16:19], v[172:175], v[196:199], v[16:19]
	v_mfma_f32_16x16x32_bf16 v[16:19], v[176:179], v[200:203], v[16:19]
	v_mfma_f32_16x16x32_bf16 v[32:35], v[172:175], v[188:191], v[32:35]
	v_mfma_f32_16x16x32_bf16 v[32:35], v[176:179], v[192:195], v[32:35]
	v_mfma_f32_16x16x32_bf16 v[48:51], v[172:175], v[180:183], v[48:51]
	v_mfma_f32_16x16x32_bf16 v[48:51], v[176:179], v[184:187], v[48:51]
	s_barrier
	s_add_i32 s46, s46, 2
	s_add_u32 s12, s12, 0x100
	s_addc_u32 s13, s13, 0
	s_add_u32 s7, s7, 0x100
	s_addc_u32 s45, s45, 0
	s_cmp_gt_u32 s46, 5
	s_cbranch_scc0 .LBB0_603
	v_readlane_b32 s46, v255, 36
	s_and_b64 vcc, exec, s[4:5]
	v_readlane_b32 s47, v255, 37
	s_cbranch_vccz .LBB0_606
	s_barrier

;     __device__ __forceinline__ int nt(const Unit& u) const { return (u.pn >> 1) < 2 ? 22 : 20; }
; #define PG8_STAGE(bufoff, gbase, voff) do { _Pragma("unroll") for (int _i = 0; _i < 2; ++_i) \
;         __builtin_amdgcn_global_load_lds((const unsigned*)((const char*)(gbase) + (voff)[_i]), (LAS unsigned*)(lds + (bufoff) + ldsw + _i * 8192), 16, 0, 0); } while (0)
; #define PG8_LDA(dst, b, h) do { _Pragma("unroll") for (int m = 0; m < 4; ++m) _Pragma("unroll") for (int k = 0; k < 2; ++k) dst[m][k] = *(const LAS bf16x8*)(pA + PG8_SA(b, h) + m * 2048 + k * 1024); } while (0)
; #define PG8_LDB(dst, b, h) do { _Pragma("unroll") for (int n = 0; n < 2; ++n) _Pragma("unroll") for (int k = 0; k < 2; ++k) dst[n][k] = *(const LAS bf16x8*)(pB + (PG8_SB(b, h) - 4 * HTB) + n * 2048 + k * 1024); } while (0)
; #define PG8_MMA(ai, bj, At, Bt) do { __builtin_amdgcn_s_setprio(1); _Pragma("unroll") for (int m = 0; m < 4; ++m) _Pragma("unroll") for (int n = 0; n < 2; ++n) _Pragma("unroll") for (int k = 0; k < 2; ++k) \
;         acc[ai][bj][m][n] = __builtin_amdgcn_mfma_f32_16x16x32_bf16(Bt[n][k], At[m][k], acc[ai][bj][m][n], 0, 0, 0); __builtin_amdgcn_s_setprio(0); } while (0)
; #define PG8_WAIT_V(n) asm volatile("s_waitcnt vmcnt(" #n ")" ::: "memory")
; #define PG8_BAR __builtin_amdgcn_s_barrier()
; template <class Desc, class Epi, bool ALIGN_EPI>
; __device__ __forceinline__ void gemm_phase(LAS unsigned char* lds, const Desc& D, const Epi& E, int G, int c) {
;     ...
;         for (int t = 0; t < nt; t += 2) {
;             const bool last = (t == nt - 2);
;             if (last && has_next) PG8_AWAIT(nxt);
;             const char* a1 = cA + (size_t)(t + 1) * kstep;
;             const char* a2 = last ? nA : cA + (size_t)(t + 2) * kstep; const char* b2 = last ? nB : cB + (size_t)(t + 2) * kstep;
;             const char* a3 = a2 + kstep; const char* b3 = b2 + kstep;
;             PG8_LDB(B0, 0, 0); PG8_LDB(B1, 0, 1); PG8_SCHED; PG8_LDA(At, 0, 0); PG8_STAGE(PG8_SA(1, 1), a1 + hstepA, voffA);
;             PG8_WAIT_V(8); PG8_WAIT_L(0); PG8_BAR; PG8_MMA(0, 0, At, B0); PG8_MMA(0, 1, At, B1); PG8_BAR; PG8_SCHED;
;             PG8_LDA(At, 0, 1); PG8_STAGE(PG8_SB(0, 0), b2, voffB); PG8_STAGE(PG8_SB(0, 1), b2 + hstepB, voffB); PG8_STAGE(PG8_SA(0, 0), a2, voffA);
;             PG8_WAIT_V(8); PG8_WAIT_L(0); PG8_BAR; PG8_MMA(1, 0, At, B0); PG8_MMA(1, 1, At, B1); PG8_BAR; PG8_SCHED;
.LBB0_1164:
	s_waitcnt lgkmcnt(0)
	ds_read_b128 v[132:135], v229
	ds_read_b128 v[136:139], v229 offset:1024
	ds_read_b128 v[140:143], v229 offset:2048
	ds_read_b128 v[144:147], v229 offset:3072
	ds_read_b128 v[148:151], v229 offset:16384
	ds_read_b128 v[152:155], v229 offset:17408
	ds_read_b128 v[156:159], v229 offset:18432
	ds_read_b128 v[160:163], v229 offset:19456
	s_add_i32 s20, s14, 2
	s_add_u32 s16, s12, 0xfff00080
	s_addc_u32 s17, s13, -1
	s_cmp_eq_u32 s1, s14
	s_cselect_b32 s19, s39, s17
	s_cselect_b32 s18, s38, s16
	s_cselect_b32 s17, s41, s11
	s_cselect_b32 s16, s40, s3
	v_lshl_add_u64 v[208:209], s[12:13], 0, v[204:205]
	s_add_i32 m0, s35, 0xc000
	ds_read_b128 v[164:167], v228
	ds_read_b128 v[168:171], v228 offset:1024
	ds_read_b128 v[172:175], v228 offset:2048
	ds_read_b128 v[176:179], v228 offset:3072
	ds_read_b128 v[180:183], v228 offset:4096
	ds_read_b128 v[184:187], v228 offset:5120
	ds_read_b128 v[188:191], v228 offset:6144
	ds_read_b128 v[192:195], v228 offset:7168
	global_load_lds_dwordx4 v[208:209], off
	v_lshl_add_u64 v[208:209], s[12:13], 0, v[206:207]
	s_add_i32 m0, s35, 0xe000
	s_nop 0
	global_load_lds_dwordx4 v[208:209], off
	s_waitcnt vmcnt(8)
	s_waitcnt lgkmcnt(0)
	s_barrier
	v_mfma_f32_16x16x32_bf16 v[128:131], v[132:135], v[164:167], v[128:131]
	v_mfma_f32_16x16x32_bf16 v[128:131], v[136:139], v[168:171], v[128:131]
	v_mfma_f32_16x16x32_bf16 v[120:123], v[132:135], v[172:175], v[120:123]
	v_mfma_f32_16x16x32_bf16 v[120:123], v[136:139], v[176:179], v[120:123]
	v_mfma_f32_16x16x32_bf16 v[112:115], v[132:135], v[180:183], v[112:115]
	v_mfma_f32_16x16x32_bf16 v[112:115], v[136:139], v[184:187], v[112:115]
	v_mfma_f32_16x16x32_bf16 v[104:107], v[132:135], v[188:191], v[104:107]
	v_mfma_f32_16x16x32_bf16 v[104:107], v[136:139], v[192:195], v[104:107]
	v_mfma_f32_16x16x32_bf16 v[100:103], v[140:143], v[188:191], v[100:103]
	v_mfma_f32_16x16x32_bf16 v[100:103], v[144:147], v[192:195], v[100:103]
	v_mfma_f32_16x16x32_bf16 v[108:111], v[140:143], v[180:183], v[108:111]
	v_mfma_f32_16x16x32_bf16 v[108:111], v[144:147], v[184:187], v[108:111]
	v_mfma_f32_16x16x32_bf16 v[116:119], v[140:143], v[172:175], v[116:119]
	v_mfma_f32_16x16x32_bf16 v[116:119], v[144:147], v[176:179], v[116:119]
	v_mfma_f32_16x16x32_bf16 v[124:127], v[140:143], v[164:167], v[124:127]
	v_mfma_f32_16x16x32_bf16 v[124:127], v[144:147], v[168:171], v[124:127]
	v_mfma_f32_16x16x32_bf16 v[96:99], v[148:151], v[164:167], v[96:99]
	v_mfma_f32_16x16x32_bf16 v[96:99], v[152:155], v[168:171], v[96:99]
	v_mfma_f32_16x16x32_bf16 v[88:91], v[148:151], v[172:175], v[88:91]
	v_mfma_f32_16x16x32_bf16 v[88:91], v[152:155], v[176:179], v[88:91]
	v_mfma_f32_16x16x32_bf16 v[64:67], v[148:151], v[180:183], v[64:67]
	v_mfma_f32_16x16x32_bf16 v[64:67], v[152:155], v[184:187], v[64:67]
	v_mfma_f32_16x16x32_bf16 v[32:35], v[148:151], v[188:191], v[32:35]
	v_mfma_f32_16x16x32_bf16 v[32:35], v[152:155], v[192:195], v[32:35]
	v_mfma_f32_16x16x32_bf16 v[20:23], v[156:159], v[188:191], v[20:23]
	v_mfma_f32_16x16x32_bf16 v[20:23], v[160:163], v[192:195], v[20:23]
	v_mfma_f32_16x16x32_bf16 v[52:55], v[156:159], v[180:183], v[52:55]
	v_mfma_f32_16x16x32_bf16 v[52:55], v[160:163], v[184:187], v[52:55]
	v_mfma_f32_16x16x32_bf16 v[80:83], v[156:159], v[172:175], v[80:83]
	v_mfma_f32_16x16x32_bf16 v[80:83], v[160:163], v[176:179], v[80:83]
	v_mfma_f32_16x16x32_bf16 v[92:95], v[156:159], v[164:167], v[92:95]
	v_mfma_f32_16x16x32_bf16 v[92:95], v[160:163], v[168:171], v[92:95]
	s_barrier
	s_mov_b32 m0, s44
	v_lshl_add_u64 v[208:209], s[16:17], 0, v[198:199]
	s_add_u32 s62, s16, 0x100000
	ds_read_b128 v[164:167], v228 offset:16384
	ds_read_b128 v[168:171], v228 offset:17408
	ds_read_b128 v[172:175], v228 offset:18432
	ds_read_b128 v[176:179], v228 offset:19456
	ds_read_b128 v[180:183], v228 offset:20480
	ds_read_b128 v[184:187], v228 offset:21504
	ds_read_b128 v[188:191], v228 offset:22528
	ds_read_b128 v[192:195], v228 offset:23552
	global_load_lds_dwordx4 v[208:209], off
	v_lshl_add_u64 v[210:211], s[16:17], 0, v[202:203]
	s_mov_b32 m0, s45
	s_addc_u32 s63, s17, 0
	global_load_lds_dwordx4 v[210:211], off
	v_lshl_add_u64 v[212:213], s[62:63], 0, v[198:199]
	s_mov_b32 m0, s46
	v_lshl_add_u64 v[214:215], s[18:19], 0, v[200:201]
	global_load_lds_dwordx4 v[212:213], off
	v_lshl_add_u64 v[212:213], s[62:63], 0, v[202:203]
	s_mov_b32 m0, s47
	s_nop 0
	global_load_lds_dwordx4 v[212:213], off
	v_lshl_add_u64 v[212:213], s[18:19], 0, v[196:197]
	s_mov_b32 m0, s35
	s_nop 0
	global_load_lds_dwordx4 v[212:213], off
	s_mov_b32 m0, s48
	s_nop 0
	global_load_lds_dwordx4 v[214:215], off
	s_waitcnt vmcnt(8)
	s_waitcnt lgkmcnt(0)
	s_barrier
; #define PG8_STAGE(bufoff, gbase, voff) do { _Pragma("unroll") for (int _i = 0; _i < 2; ++_i) \
;         __builtin_amdgcn_global_load_lds((const unsigned*)((const char*)(gbase) + (voff)[_i]), (LAS unsigned*)(lds + (bufoff) + ldsw + _i * 8192), 16, 0, 0); } while (0)
; #define PG8_LDA(dst, b, h) do { _Pragma("unroll") for (int m = 0; m < 4; ++m) _Pragma("unroll") for (int k = 0; k < 2; ++k) dst[m][k] = *(const LAS bf16x8*)(pA + PG8_SA(b, h) + m * 2048 + k * 1024); } while (0)
; #define PG8_LDB(dst, b, h) do { _Pragma("unroll") for (int n = 0; n < 2; ++n) _Pragma("unroll") for (int k = 0; k < 2; ++k) dst[n][k] = *(const LAS bf16x8*)(pB + (PG8_SB(b, h) - 4 * HTB) + n * 2048 + k * 1024); } while (0)
; #define PG8_MMA(ai, bj, At, Bt) do { __builtin_amdgcn_s_setprio(1); _Pragma("unroll") for (int m = 0; m < 4; ++m) _Pragma("unroll") for (int n = 0; n < 2; ++n) _Pragma("unroll") for (int k = 0; k < 2; ++k) \
;         acc[ai][bj][m][n] = __builtin_amdgcn_mfma_f32_16x16x32_bf16(Bt[n][k], At[m][k], acc[ai][bj][m][n], 0, 0, 0); __builtin_amdgcn_s_setprio(0); } while (0)
; #define PG8_WAIT_V(n) asm volatile("s_waitcnt vmcnt(" #n ")" ::: "memory")
; #define PG8_WAIT_L(n) asm volatile("s_waitcnt lgkmcnt(" #n ")" ::: "memory")
; #define PG8_BAR __builtin_amdgcn_s_barrier()
; #define PG8_SCHED __builtin_amdgcn_sched_barrier(0)
; template <class Desc, class Epi, bool ALIGN_EPI>
; __device__ __forceinline__ void gemm_phase(LAS unsigned char* lds, const Desc& D, const Epi& E, int G, int c) {
;     ...
;             PG8_WAIT_V(8); PG8_WAIT_L(0); PG8_BAR; PG8_MMA(1, 0, At, B0); PG8_MMA(1, 1, At, B1); PG8_BAR; PG8_SCHED;
;             PG8_LDB(B0, 1, 0); PG8_LDB(B1, 1, 1); PG8_SCHED; PG8_LDA(At, 1, 0); PG8_STAGE(PG8_SA(0, 1), a2 + hstepA, voffA);
;             PG8_WAIT_V(8); PG8_WAIT_L(0); PG8_BAR; PG8_MMA(0, 0, At, B0); PG8_MMA(0, 1, At, B1); PG8_BAR; PG8_SCHED;
	v_mfma_f32_16x16x32_bf16 v[84:87], v[132:135], v[164:167], v[84:87]
	v_mfma_f32_16x16x32_bf16 v[84:87], v[136:139], v[168:171], v[84:87]
	v_mfma_f32_16x16x32_bf16 v[72:75], v[132:135], v[172:175], v[72:75]
	v_mfma_f32_16x16x32_bf16 v[72:75], v[136:139], v[176:179], v[72:75]
	v_mfma_f32_16x16x32_bf16 v[60:63], v[132:135], v[180:183], v[60:63]
	v_mfma_f32_16x16x32_bf16 v[60:63], v[136:139], v[184:187], v[60:63]
	v_mfma_f32_16x16x32_bf16 v[48:51], v[132:135], v[188:191], v[48:51]
	v_mfma_f32_16x16x32_bf16 v[48:51], v[136:139], v[192:195], v[48:51]
	v_mfma_f32_16x16x32_bf16 v[44:47], v[140:143], v[188:191], v[44:47]
	v_mfma_f32_16x16x32_bf16 v[44:47], v[144:147], v[192:195], v[44:47]
	v_mfma_f32_16x16x32_bf16 v[56:59], v[140:143], v[180:183], v[56:59]
	v_mfma_f32_16x16x32_bf16 v[56:59], v[144:147], v[184:187], v[56:59]
	v_mfma_f32_16x16x32_bf16 v[68:71], v[140:143], v[172:175], v[68:71]
	v_mfma_f32_16x16x32_bf16 v[68:71], v[144:147], v[176:179], v[68:71]
	v_mfma_f32_16x16x32_bf16 v[76:79], v[140:143], v[164:167], v[76:79]
	v_mfma_f32_16x16x32_bf16 v[76:79], v[144:147], v[168:171], v[76:79]
	v_mfma_f32_16x16x32_bf16 v[40:43], v[148:151], v[164:167], v[40:43]
	v_mfma_f32_16x16x32_bf16 v[40:43], v[152:155], v[168:171], v[40:43]
	v_mfma_f32_16x16x32_bf16 v[28:31], v[148:151], v[172:175], v[28:31]
	v_mfma_f32_16x16x32_bf16 v[28:31], v[152:155], v[176:179], v[28:31]
	v_mfma_f32_16x16x32_bf16 v[16:19], v[148:151], v[180:183], v[16:19]
	v_mfma_f32_16x16x32_bf16 v[16:19], v[152:155], v[184:187], v[16:19]
	v_mfma_f32_16x16x32_bf16 v[8:11], v[148:151], v[188:191], v[8:11]
	v_mfma_f32_16x16x32_bf16 v[8:11], v[152:155], v[192:195], v[8:11]
	v_mfma_f32_16x16x32_bf16 v[4:7], v[156:159], v[188:191], v[4:7]
	v_mfma_f32_16x16x32_bf16 v[4:7], v[160:163], v[192:195], v[4:7]
	v_mfma_f32_16x16x32_bf16 v[12:15], v[156:159], v[180:183], v[12:15]
	v_mfma_f32_16x16x32_bf16 v[12:15], v[160:163], v[184:187], v[12:15]
	v_mfma_f32_16x16x32_bf16 v[24:27], v[156:159], v[172:175], v[24:27]
	v_mfma_f32_16x16x32_bf16 v[24:27], v[160:163], v[176:179], v[24:27]
	v_mfma_f32_16x16x32_bf16 v[36:39], v[156:159], v[164:167], v[36:39]
	v_mfma_f32_16x16x32_bf16 v[36:39], v[160:163], v[168:171], v[36:39]
	s_barrier
	ds_read_b128 v[132:135], v229 offset:32768
	ds_read_b128 v[136:139], v229 offset:33792
	ds_read_b128 v[140:143], v229 offset:34816
	ds_read_b128 v[144:147], v229 offset:35840
	ds_read_b128 v[148:151], v229 offset:49152
	ds_read_b128 v[152:155], v229 offset:50176
	ds_read_b128 v[156:159], v229 offset:51200
	ds_read_b128 v[160:163], v229 offset:52224
	s_add_u32 s18, s18, 0x100000
	s_addc_u32 s19, s19, 0
	s_mov_b32 m0, s49
	v_lshl_add_u64 v[216:217], s[18:19], 0, v[196:197]
	ds_read_b128 v[164:167], v228 offset:32768
	ds_read_b128 v[168:171], v228 offset:33792
	ds_read_b128 v[172:175], v228 offset:34816
	ds_read_b128 v[176:179], v228 offset:35840
	ds_read_b128 v[180:183], v228 offset:36864
	ds_read_b128 v[184:187], v228 offset:37888
	ds_read_b128 v[188:191], v228 offset:38912
	ds_read_b128 v[192:195], v228 offset:39936
	global_load_lds_dwordx4 v[216:217], off
	v_lshl_add_u64 v[216:217], s[18:19], 0, v[200:201]
	s_mov_b32 m0, s50
	s_nop 0
	global_load_lds_dwordx4 v[216:217], off
	s_waitcnt vmcnt(8)
	s_waitcnt lgkmcnt(0)
	s_barrier
	v_mfma_f32_16x16x32_bf16 v[128:131], v[132:135], v[164:167], v[128:131]
	v_mfma_f32_16x16x32_bf16 v[128:131], v[136:139], v[168:171], v[128:131]
	v_mfma_f32_16x16x32_bf16 v[120:123], v[132:135], v[172:175], v[120:123]
	v_mfma_f32_16x16x32_bf16 v[120:123], v[136:139], v[176:179], v[120:123]
	v_mfma_f32_16x16x32_bf16 v[112:115], v[132:135], v[180:183], v[112:115]
	v_mfma_f32_16x16x32_bf16 v[112:115], v[136:139], v[184:187], v[112:115]
	v_mfma_f32_16x16x32_bf16 v[104:107], v[132:135], v[188:191], v[104:107]
	v_mfma_f32_16x16x32_bf16 v[104:107], v[136:139], v[192:195], v[104:107]
	v_mfma_f32_16x16x32_bf16 v[100:103], v[140:143], v[188:191], v[100:103]
	v_mfma_f32_16x16x32_bf16 v[100:103], v[144:147], v[192:195], v[100:103]
	v_mfma_f32_16x16x32_bf16 v[108:111], v[140:143], v[180:183], v[108:111]
	v_mfma_f32_16x16x32_bf16 v[108:111], v[144:147], v[184:187], v[108:111]
	v_mfma_f32_16x16x32_bf16 v[116:119], v[140:143], v[172:175], v[116:119]
	v_mfma_f32_16x16x32_bf16 v[116:119], v[144:147], v[176:179], v[116:119]
	v_mfma_f32_16x16x32_bf16 v[124:127], v[140:143], v[164:167], v[124:127]
	v_mfma_f32_16x16x32_bf16 v[124:127], v[144:147], v[168:171], v[124:127]
	v_mfma_f32_16x16x32_bf16 v[96:99], v[148:151], v[164:167], v[96:99]
	v_mfma_f32_16x16x32_bf16 v[96:99], v[152:155], v[168:171], v[96:99]
	v_mfma_f32_16x16x32_bf16 v[88:91], v[148:151], v[172:175], v[88:91]
	v_mfma_f32_16x16x32_bf16 v[88:91], v[152:155], v[176:179], v[88:91]
	v_mfma_f32_16x16x32_bf16 v[64:67], v[148:151], v[180:183], v[64:67]
	v_mfma_f32_16x16x32_bf16 v[64:67], v[152:155], v[184:187], v[64:67]
	v_mfma_f32_16x16x32_bf16 v[32:35], v[148:151], v[188:191], v[32:35]
	v_mfma_f32_16x16x32_bf16 v[32:35], v[152:155], v[192:195], v[32:35]
	v_mfma_f32_16x16x32_bf16 v[20:23], v[156:159], v[188:191], v[20:23]
	v_mfma_f32_16x16x32_bf16 v[20:23], v[160:163], v[192:195], v[20:23]
	v_mfma_f32_16x16x32_bf16 v[52:55], v[156:159], v[180:183], v[52:55]
	v_mfma_f32_16x16x32_bf16 v[52:55], v[160:163], v[184:187], v[52:55]
	v_mfma_f32_16x16x32_bf16 v[80:83], v[156:159], v[172:175], v[80:83]
	v_mfma_f32_16x16x32_bf16 v[80:83], v[160:163], v[176:179], v[80:83]
	v_mfma_f32_16x16x32_bf16 v[92:95], v[156:159], v[164:167], v[92:95]
	v_mfma_f32_16x16x32_bf16 v[92:95], v[160:163], v[168:171], v[92:95]
	s_barrier
;     __device__ __forceinline__ int nt(const Unit& u) const { return (u.pn >> 1) < 2 ? 22 : 20; }
; #define PG8_STAGE(bufoff, gbase, voff) do { _Pragma("unroll") for (int _i = 0; _i < 2; ++_i) \
;         __builtin_amdgcn_global_load_lds((const unsigned*)((const char*)(gbase) + (voff)[_i]), (LAS unsigned*)(lds + (bufoff) + ldsw + _i * 8192), 16, 0, 0); } while (0)
; #define PG8_LDA(dst, b, h) do { _Pragma("unroll") for (int m = 0; m < 4; ++m) _Pragma("unroll") for (int k = 0; k < 2; ++k) dst[m][k] = *(const LAS bf16x8*)(pA + PG8_SA(b, h) + m * 2048 + k * 1024); } while (0)
; #define PG8_MMA(ai, bj, At, Bt) do { __builtin_amdgcn_s_setprio(1); _Pragma("unroll") for (int m = 0; m < 4; ++m) _Pragma("unroll") for (int n = 0; n < 2; ++n) _Pragma("unroll") for (int k = 0; k < 2; ++k) \
;         acc[ai][bj][m][n] = __builtin_amdgcn_mfma_f32_16x16x32_bf16(Bt[n][k], At[m][k], acc[ai][bj][m][n], 0, 0, 0); __builtin_amdgcn_s_setprio(0); } while (0)
; #define PG8_WAIT_V(n) asm volatile("s_waitcnt vmcnt(" #n ")" ::: "memory")
; #define PG8_WAIT_L(n) asm volatile("s_waitcnt lgkmcnt(" #n ")" ::: "memory")
; #define PG8_BAR __builtin_amdgcn_s_barrier()
; #define PG8_SCHED __builtin_amdgcn_sched_barrier(0)
; template <class Desc, class Epi, bool ALIGN_EPI>
; __device__ __forceinline__ void gemm_phase(LAS unsigned char* lds, const Desc& D, const Epi& E, int G, int c) {
;     ...
;         for (int t = 0; t < nt; t += 2) {
;     ...
;             PG8_LDA(At, 1, 1); PG8_STAGE(PG8_SB(1, 0), b3, voffB); PG8_STAGE(PG8_SB(1, 1), b3 + hstepB, voffB); PG8_STAGE(PG8_SA(1, 0), a3, voffA);
;             PG8_WAIT_V(8); PG8_WAIT_L(0); PG8_BAR; PG8_MMA(1, 0, At, B0); PG8_MMA(1, 1, At, B1); PG8_BAR; PG8_SCHED;
;         }
;         if constexpr (ALIGN_EPI) { if (wr == 0) PG8_BAR; }
	s_mov_b32 m0, s52
	v_lshl_add_u64 v[208:209], v[208:209], 0, s[76:77]
	s_add_u32 s16, s16, 0x100080
	ds_read_b128 v[164:167], v228 offset:49152
	ds_read_b128 v[168:171], v228 offset:50176
	ds_read_b128 v[172:175], v228 offset:51200
	ds_read_b128 v[176:179], v228 offset:52224
	ds_read_b128 v[180:183], v228 offset:53248
	ds_read_b128 v[184:187], v228 offset:54272
	ds_read_b128 v[188:191], v228 offset:55296
	ds_read_b128 v[192:195], v228 offset:56320
	global_load_lds_dwordx4 v[208:209], off
	v_lshl_add_u64 v[208:209], v[210:211], 0, s[76:77]
	s_mov_b32 m0, s53
	s_addc_u32 s17, s17, 0
	global_load_lds_dwordx4 v[208:209], off
	v_lshl_add_u64 v[208:209], s[16:17], 0, v[198:199]
	s_mov_b32 m0, s56
	s_nop 0
	global_load_lds_dwordx4 v[208:209], off
	v_lshl_add_u64 v[208:209], s[16:17], 0, v[202:203]
	s_mov_b32 m0, s57
	s_nop 0
	global_load_lds_dwordx4 v[208:209], off
	v_lshl_add_u64 v[208:209], v[212:213], 0, s[76:77]
	s_mov_b32 m0, s54
	s_nop 0
	global_load_lds_dwordx4 v[208:209], off
	v_lshl_add_u64 v[208:209], v[214:215], 0, s[76:77]
	s_mov_b32 m0, s55
	s_nop 0
	global_load_lds_dwordx4 v[208:209], off
	s_waitcnt vmcnt(8)
	s_waitcnt lgkmcnt(0)
	s_barrier
	v_mfma_f32_16x16x32_bf16 v[84:87], v[132:135], v[164:167], v[84:87]
	v_mfma_f32_16x16x32_bf16 v[84:87], v[136:139], v[168:171], v[84:87]
	v_mfma_f32_16x16x32_bf16 v[72:75], v[132:135], v[172:175], v[72:75]
	v_mfma_f32_16x16x32_bf16 v[72:75], v[136:139], v[176:179], v[72:75]
	v_mfma_f32_16x16x32_bf16 v[60:63], v[132:135], v[180:183], v[60:63]
	v_mfma_f32_16x16x32_bf16 v[60:63], v[136:139], v[184:187], v[60:63]
	v_mfma_f32_16x16x32_bf16 v[48:51], v[132:135], v[188:191], v[48:51]
	v_mfma_f32_16x16x32_bf16 v[48:51], v[136:139], v[192:195], v[48:51]
	v_mfma_f32_16x16x32_bf16 v[44:47], v[140:143], v[188:191], v[44:47]
	v_mfma_f32_16x16x32_bf16 v[44:47], v[144:147], v[192:195], v[44:47]
	v_mfma_f32_16x16x32_bf16 v[56:59], v[140:143], v[180:183], v[56:59]
	v_mfma_f32_16x16x32_bf16 v[56:59], v[144:147], v[184:187], v[56:59]
	v_mfma_f32_16x16x32_bf16 v[68:71], v[140:143], v[172:175], v[68:71]
	v_mfma_f32_16x16x32_bf16 v[68:71], v[144:147], v[176:179], v[68:71]
	v_mfma_f32_16x16x32_bf16 v[76:79], v[140:143], v[164:167], v[76:79]
	v_mfma_f32_16x16x32_bf16 v[76:79], v[144:147], v[168:171], v[76:79]
	v_mfma_f32_16x16x32_bf16 v[40:43], v[148:151], v[164:167], v[40:43]
	v_mfma_f32_16x16x32_bf16 v[40:43], v[152:155], v[168:171], v[40:43]
	v_mfma_f32_16x16x32_bf16 v[28:31], v[148:151], v[172:175], v[28:31]
	v_mfma_f32_16x16x32_bf16 v[28:31], v[152:155], v[176:179], v[28:31]
	v_mfma_f32_16x16x32_bf16 v[16:19], v[148:151], v[180:183], v[16:19]
	v_mfma_f32_16x16x32_bf16 v[16:19], v[152:155], v[184:187], v[16:19]
	v_mfma_f32_16x16x32_bf16 v[8:11], v[148:151], v[188:191], v[8:11]
	v_mfma_f32_16x16x32_bf16 v[8:11], v[152:155], v[192:195], v[8:11]
	v_mfma_f32_16x16x32_bf16 v[4:7], v[156:159], v[188:191], v[4:7]
	v_mfma_f32_16x16x32_bf16 v[4:7], v[160:163], v[192:195], v[4:7]
	v_mfma_f32_16x16x32_bf16 v[12:15], v[156:159], v[180:183], v[12:15]
	v_mfma_f32_16x16x32_bf16 v[12:15], v[160:163], v[184:187], v[12:15]
	v_mfma_f32_16x16x32_bf16 v[24:27], v[156:159], v[172:175], v[24:27]
	v_mfma_f32_16x16x32_bf16 v[24:27], v[160:163], v[176:179], v[24:27]
	v_mfma_f32_16x16x32_bf16 v[36:39], v[156:159], v[164:167], v[36:39]
	v_mfma_f32_16x16x32_bf16 v[36:39], v[160:163], v[168:171], v[36:39]
	s_barrier
	s_add_u32 s12, s12, 0x100
	s_addc_u32 s13, s13, 0
	s_add_u32 s3, s3, 0x100
	s_addc_u32 s11, s11, 0
	s_cmp_ge_u32 s20, s2
	s_mov_b32 s14, s20
	s_cbranch_scc0 .LBB0_1164
	s_and_b64 vcc, exec, s[8:9]
	s_cbranch_vccz .LBB0_1167
	s_barrier

;     __device__ __forceinline__ int nt(const Unit& u) const { return (u.pn >> 1) < 2 ? 22 : 20; }
; #define PG8_STAGE(bufoff, gbase, voff) do { _Pragma("unroll") for (int _i = 0; _i < 2; ++_i) \
;         __builtin_amdgcn_global_load_lds((const unsigned*)((const char*)(gbase) + (voff)[_i]), (LAS unsigned*)(lds + (bufoff) + ldsw + _i * 8192), 16, 0, 0); } while (0)
; #define PG8_LDA(dst, b, h) do { _Pragma("unroll") for (int m = 0; m < 4; ++m) _Pragma("unroll") for (int k = 0; k < 2; ++k) dst[m][k] = *(const LAS bf16x8*)(pA + PG8_SA(b, h) + m * 2048 + k * 1024); } while (0)
; #define PG8_LDB(dst, b, h) do { _Pragma("unroll") for (int n = 0; n < 2; ++n) _Pragma("unroll") for (int k = 0; k < 2; ++k) dst[n][k] = *(const LAS bf16x8*)(pB + (PG8_SB(b, h) - 4 * HTB) + n * 2048 + k * 1024); } while (0)
; #define PG8_MMA(ai, bj, At, Bt) do { __builtin_amdgcn_s_setprio(1); _Pragma("unroll") for (int m = 0; m < 4; ++m) _Pragma("unroll") for (int n = 0; n < 2; ++n) _Pragma("unroll") for (int k = 0; k < 2; ++k) \
;         acc[ai][bj][m][n] = __builtin_amdgcn_mfma_f32_16x16x32_bf16(Bt[n][k], At[m][k], acc[ai][bj][m][n], 0, 0, 0); __builtin_amdgcn_s_setprio(0); } while (0)
; #define PG8_WAIT_V(n) asm volatile("s_waitcnt vmcnt(" #n ")" ::: "memory")
; #define PG8_BAR __builtin_amdgcn_s_barrier()
; template <class Desc, class Epi, bool ALIGN_EPI>
; __device__ __forceinline__ void gemm_phase(LAS unsigned char* lds, const Desc& D, const Epi& E, int G, int c) {
;     ...
;         for (int t = 0; t < nt; t += 2) {
;             const bool last = (t == nt - 2);
;             if (last && has_next) PG8_AWAIT(nxt);
;             const char* a1 = cA + (size_t)(t + 1) * kstep;
;             const char* a2 = last ? nA : cA + (size_t)(t + 2) * kstep; const char* b2 = last ? nB : cB + (size_t)(t + 2) * kstep;
;             const char* a3 = a2 + kstep; const char* b3 = b2 + kstep;
;             PG8_LDB(B0, 0, 0); PG8_LDB(B1, 0, 1); PG8_SCHED; PG8_LDA(At, 0, 0); PG8_STAGE(PG8_SA(1, 1), a1 + hstepA, voffA);
;             PG8_WAIT_V(8); PG8_WAIT_L(0); PG8_BAR; PG8_MMA(0, 0, At, B0); PG8_MMA(0, 1, At, B1); PG8_BAR; PG8_SCHED;
;             PG8_LDA(At, 0, 1); PG8_STAGE(PG8_SB(0, 0), b2, voffB); PG8_STAGE(PG8_SB(0, 1), b2 + hstepB, voffB); PG8_STAGE(PG8_SA(0, 0), a2, voffA);
;             PG8_WAIT_V(8); PG8_WAIT_L(0); PG8_BAR; PG8_MMA(1, 0, At, B0); PG8_MMA(1, 1, At, B1); PG8_BAR; PG8_SCHED;
.LBB0_1324:
	ds_read_b128 v[144:147], v149
	ds_read_b128 v[152:155], v149 offset:1024
	ds_read_b128 v[156:159], v149 offset:2048
	ds_read_b128 v[160:163], v149 offset:3072
	ds_read_b128 v[164:167], v149 offset:16384
	ds_read_b128 v[168:171], v149 offset:17408
	ds_read_b128 v[172:175], v149 offset:18432
	ds_read_b128 v[176:179], v149 offset:19456
	s_add_i32 s50, s18, 2
	s_add_u32 s19, s16, 0xfff00080
	s_addc_u32 s20, s17, -1
	s_cmp_eq_u32 s9, s18
	s_cselect_b32 s18, s12, s48
	s_cselect_b32 s21, s11, s20
	s_cselect_b32 s20, s10, s19
	s_cselect_b32 s19, s13, s49
	v_lshl_add_u64 v[212:213], s[16:17], 0, v[140:141]
	s_add_i32 m0, s24, 0xc000
	ds_read_b128 v[180:183], v148
	ds_read_b128 v[184:187], v148 offset:1024
	ds_read_b128 v[188:191], v148 offset:2048
	ds_read_b128 v[192:195], v148 offset:3072
	ds_read_b128 v[196:199], v148 offset:4096
	ds_read_b128 v[200:203], v148 offset:5120
	ds_read_b128 v[204:207], v148 offset:6144
	ds_read_b128 v[208:211], v148 offset:7168
	global_load_lds_dwordx4 v[212:213], off
	v_lshl_add_u64 v[212:213], s[16:17], 0, v[142:143]
	s_add_i32 m0, s24, 0xe000
	s_nop 0
	global_load_lds_dwordx4 v[212:213], off
	s_waitcnt vmcnt(8)
	s_waitcnt lgkmcnt(0)
	s_barrier
	v_mfma_f32_16x16x32_bf16 v[128:131], v[144:147], v[180:183], v[128:131]
	v_mfma_f32_16x16x32_bf16 v[128:131], v[152:155], v[184:187], v[128:131]
	v_mfma_f32_16x16x32_bf16 v[120:123], v[144:147], v[188:191], v[120:123]
	v_mfma_f32_16x16x32_bf16 v[120:123], v[152:155], v[192:195], v[120:123]
	v_mfma_f32_16x16x32_bf16 v[104:107], v[144:147], v[196:199], v[104:107]
	v_mfma_f32_16x16x32_bf16 v[104:107], v[152:155], v[200:203], v[104:107]
	v_mfma_f32_16x16x32_bf16 v[88:91], v[144:147], v[204:207], v[88:91]
	v_mfma_f32_16x16x32_bf16 v[88:91], v[152:155], v[208:211], v[88:91]
	v_mfma_f32_16x16x32_bf16 v[80:83], v[156:159], v[204:207], v[80:83]
	v_mfma_f32_16x16x32_bf16 v[80:83], v[160:163], v[208:211], v[80:83]
	v_mfma_f32_16x16x32_bf16 v[96:99], v[156:159], v[196:199], v[96:99]
	v_mfma_f32_16x16x32_bf16 v[96:99], v[160:163], v[200:203], v[96:99]
	v_mfma_f32_16x16x32_bf16 v[112:115], v[156:159], v[188:191], v[112:115]
	v_mfma_f32_16x16x32_bf16 v[112:115], v[160:163], v[192:195], v[112:115]
	v_mfma_f32_16x16x32_bf16 v[124:127], v[156:159], v[180:183], v[124:127]
	v_mfma_f32_16x16x32_bf16 v[124:127], v[160:163], v[184:187], v[124:127]
	v_mfma_f32_16x16x32_bf16 v[116:119], v[164:167], v[180:183], v[116:119]
	v_mfma_f32_16x16x32_bf16 v[116:119], v[168:171], v[184:187], v[116:119]
	v_mfma_f32_16x16x32_bf16 v[100:103], v[164:167], v[188:191], v[100:103]
	v_mfma_f32_16x16x32_bf16 v[100:103], v[168:171], v[192:195], v[100:103]
	v_mfma_f32_16x16x32_bf16 v[84:87], v[164:167], v[196:199], v[84:87]
	v_mfma_f32_16x16x32_bf16 v[84:87], v[168:171], v[200:203], v[84:87]
	v_mfma_f32_16x16x32_bf16 v[72:75], v[164:167], v[204:207], v[72:75]
	v_mfma_f32_16x16x32_bf16 v[72:75], v[168:171], v[208:211], v[72:75]
	v_mfma_f32_16x16x32_bf16 v[68:71], v[172:175], v[204:207], v[68:71]
	v_mfma_f32_16x16x32_bf16 v[68:71], v[176:179], v[208:211], v[68:71]
	v_mfma_f32_16x16x32_bf16 v[76:79], v[172:175], v[196:199], v[76:79]
	v_mfma_f32_16x16x32_bf16 v[76:79], v[176:179], v[200:203], v[76:79]
	v_mfma_f32_16x16x32_bf16 v[92:95], v[172:175], v[188:191], v[92:95]
	v_mfma_f32_16x16x32_bf16 v[92:95], v[176:179], v[192:195], v[92:95]
	v_mfma_f32_16x16x32_bf16 v[108:111], v[172:175], v[180:183], v[108:111]
	v_mfma_f32_16x16x32_bf16 v[108:111], v[176:179], v[184:187], v[108:111]
	s_barrier
	s_mov_b32 m0, s25
	v_lshl_add_u64 v[212:213], s[18:19], 0, v[136:137]
	s_add_u32 s52, s18, 0x100000
	ds_read_b128 v[180:183], v148 offset:16384
	ds_read_b128 v[184:187], v148 offset:17408
	ds_read_b128 v[188:191], v148 offset:18432
	ds_read_b128 v[192:195], v148 offset:19456
	ds_read_b128 v[196:199], v148 offset:20480
	ds_read_b128 v[200:203], v148 offset:21504
	ds_read_b128 v[204:207], v148 offset:22528
	ds_read_b128 v[208:211], v148 offset:23552
	global_load_lds_dwordx4 v[212:213], off
	v_lshl_add_u64 v[214:215], s[18:19], 0, v[132:133]
	s_mov_b32 m0, s26
	s_addc_u32 s53, s19, 0
	global_load_lds_dwordx4 v[214:215], off
	v_lshl_add_u64 v[216:217], s[52:53], 0, v[136:137]
	s_mov_b32 m0, s27
	v_lshl_add_u64 v[218:219], s[20:21], 0, v[134:135]
	global_load_lds_dwordx4 v[216:217], off
	v_lshl_add_u64 v[216:217], s[52:53], 0, v[132:133]
	s_mov_b32 m0, s30
	s_nop 0
	global_load_lds_dwordx4 v[216:217], off
	v_lshl_add_u64 v[216:217], s[20:21], 0, v[138:139]
	s_mov_b32 m0, s24
	s_nop 0
	global_load_lds_dwordx4 v[216:217], off
	s_mov_b32 m0, s31
	s_nop 0
	global_load_lds_dwordx4 v[218:219], off
	s_waitcnt vmcnt(8)
	s_waitcnt lgkmcnt(0)
	s_barrier
; #define PG8_STAGE(bufoff, gbase, voff) do { _Pragma("unroll") for (int _i = 0; _i < 2; ++_i) \
;         __builtin_amdgcn_global_load_lds((const unsigned*)((const char*)(gbase) + (voff)[_i]), (LAS unsigned*)(lds + (bufoff) + ldsw + _i * 8192), 16, 0, 0); } while (0)
; #define PG8_LDA(dst, b, h) do { _Pragma("unroll") for (int m = 0; m < 4; ++m) _Pragma("unroll") for (int k = 0; k < 2; ++k) dst[m][k] = *(const LAS bf16x8*)(pA + PG8_SA(b, h) + m * 2048 + k * 1024); } while (0)
; #define PG8_LDB(dst, b, h) do { _Pragma("unroll") for (int n = 0; n < 2; ++n) _Pragma("unroll") for (int k = 0; k < 2; ++k) dst[n][k] = *(const LAS bf16x8*)(pB + (PG8_SB(b, h) - 4 * HTB) + n * 2048 + k * 1024); } while (0)
; #define PG8_MMA(ai, bj, At, Bt) do { __builtin_amdgcn_s_setprio(1); _Pragma("unroll") for (int m = 0; m < 4; ++m) _Pragma("unroll") for (int n = 0; n < 2; ++n) _Pragma("unroll") for (int k = 0; k < 2; ++k) \
;         acc[ai][bj][m][n] = __builtin_amdgcn_mfma_f32_16x16x32_bf16(Bt[n][k], At[m][k], acc[ai][bj][m][n], 0, 0, 0); __builtin_amdgcn_s_setprio(0); } while (0)
; #define PG8_WAIT_V(n) asm volatile("s_waitcnt vmcnt(" #n ")" ::: "memory")
; #define PG8_WAIT_L(n) asm volatile("s_waitcnt lgkmcnt(" #n ")" ::: "memory")
; #define PG8_BAR __builtin_amdgcn_s_barrier()
; #define PG8_SCHED __builtin_amdgcn_sched_barrier(0)
; template <class Desc, class Epi, bool ALIGN_EPI>
; __device__ __forceinline__ void gemm_phase(LAS unsigned char* lds, const Desc& D, const Epi& E, int G, int c) {
;     ...
;             PG8_WAIT_V(8); PG8_WAIT_L(0); PG8_BAR; PG8_MMA(1, 0, At, B0); PG8_MMA(1, 1, At, B1); PG8_BAR; PG8_SCHED;
;             PG8_LDB(B0, 1, 0); PG8_LDB(B1, 1, 1); PG8_SCHED; PG8_LDA(At, 1, 0); PG8_STAGE(PG8_SA(0, 1), a2 + hstepA, voffA);
;             PG8_WAIT_V(8); PG8_WAIT_L(0); PG8_BAR; PG8_MMA(0, 0, At, B0); PG8_MMA(0, 1, At, B1); PG8_BAR; PG8_SCHED;
	v_mfma_f32_16x16x32_bf16 v[64:67], v[144:147], v[180:183], v[64:67]
	v_mfma_f32_16x16x32_bf16 v[64:67], v[152:155], v[184:187], v[64:67]
	v_mfma_f32_16x16x32_bf16 v[56:59], v[144:147], v[188:191], v[56:59]
	v_mfma_f32_16x16x32_bf16 v[56:59], v[152:155], v[192:195], v[56:59]
	v_mfma_f32_16x16x32_bf16 v[40:43], v[144:147], v[196:199], v[40:43]
	v_mfma_f32_16x16x32_bf16 v[40:43], v[152:155], v[200:203], v[40:43]
	v_mfma_f32_16x16x32_bf16 v[24:27], v[144:147], v[204:207], v[24:27]
	v_mfma_f32_16x16x32_bf16 v[24:27], v[152:155], v[208:211], v[24:27]
	v_mfma_f32_16x16x32_bf16 v[16:19], v[156:159], v[204:207], v[16:19]
	v_mfma_f32_16x16x32_bf16 v[16:19], v[160:163], v[208:211], v[16:19]
	v_mfma_f32_16x16x32_bf16 v[32:35], v[156:159], v[196:199], v[32:35]
	v_mfma_f32_16x16x32_bf16 v[32:35], v[160:163], v[200:203], v[32:35]
	v_mfma_f32_16x16x32_bf16 v[48:51], v[156:159], v[188:191], v[48:51]
	v_mfma_f32_16x16x32_bf16 v[48:51], v[160:163], v[192:195], v[48:51]
	v_mfma_f32_16x16x32_bf16 v[60:63], v[156:159], v[180:183], v[60:63]
	v_mfma_f32_16x16x32_bf16 v[60:63], v[160:163], v[184:187], v[60:63]
	v_mfma_f32_16x16x32_bf16 v[52:55], v[164:167], v[180:183], v[52:55]
	v_mfma_f32_16x16x32_bf16 v[52:55], v[168:171], v[184:187], v[52:55]
	v_mfma_f32_16x16x32_bf16 v[36:39], v[164:167], v[188:191], v[36:39]
	v_mfma_f32_16x16x32_bf16 v[36:39], v[168:171], v[192:195], v[36:39]
	v_mfma_f32_16x16x32_bf16 v[20:23], v[164:167], v[196:199], v[20:23]
	v_mfma_f32_16x16x32_bf16 v[20:23], v[168:171], v[200:203], v[20:23]
	v_mfma_f32_16x16x32_bf16 v[8:11], v[164:167], v[204:207], v[8:11]
	v_mfma_f32_16x16x32_bf16 v[8:11], v[168:171], v[208:211], v[8:11]
	v_mfma_f32_16x16x32_bf16 v[4:7], v[172:175], v[204:207], v[4:7]
	v_mfma_f32_16x16x32_bf16 v[4:7], v[176:179], v[208:211], v[4:7]
	v_mfma_f32_16x16x32_bf16 v[12:15], v[172:175], v[196:199], v[12:15]
	v_mfma_f32_16x16x32_bf16 v[12:15], v[176:179], v[200:203], v[12:15]
	v_mfma_f32_16x16x32_bf16 v[28:31], v[172:175], v[188:191], v[28:31]
	v_mfma_f32_16x16x32_bf16 v[28:31], v[176:179], v[192:195], v[28:31]
	v_mfma_f32_16x16x32_bf16 v[44:47], v[172:175], v[180:183], v[44:47]
	v_mfma_f32_16x16x32_bf16 v[44:47], v[176:179], v[184:187], v[44:47]
	s_barrier
	ds_read_b128 v[144:147], v149 offset:32768
	ds_read_b128 v[152:155], v149 offset:33792
	ds_read_b128 v[156:159], v149 offset:34816
	ds_read_b128 v[160:163], v149 offset:35840
	ds_read_b128 v[164:167], v149 offset:49152
	ds_read_b128 v[168:171], v149 offset:50176
	ds_read_b128 v[172:175], v149 offset:51200
	ds_read_b128 v[176:179], v149 offset:52224
	s_add_u32 s20, s20, 0x100000
	s_addc_u32 s21, s21, 0
	s_mov_b32 m0, s33
	v_lshl_add_u64 v[220:221], s[20:21], 0, v[138:139]
	ds_read_b128 v[180:183], v148 offset:32768
	ds_read_b128 v[184:187], v148 offset:33792
	ds_read_b128 v[188:191], v148 offset:34816
	ds_read_b128 v[192:195], v148 offset:35840
	ds_read_b128 v[196:199], v148 offset:36864
	ds_read_b128 v[200:203], v148 offset:37888
	ds_read_b128 v[204:207], v148 offset:38912
	ds_read_b128 v[208:211], v148 offset:39936
	global_load_lds_dwordx4 v[220:221], off
	v_lshl_add_u64 v[220:221], s[20:21], 0, v[134:135]
	s_mov_b32 m0, s34
	s_nop 0
	global_load_lds_dwordx4 v[220:221], off
	s_waitcnt vmcnt(8)
	s_waitcnt lgkmcnt(0)
	s_barrier
	v_mfma_f32_16x16x32_bf16 v[128:131], v[144:147], v[180:183], v[128:131]
	v_mfma_f32_16x16x32_bf16 v[128:131], v[152:155], v[184:187], v[128:131]
	v_mfma_f32_16x16x32_bf16 v[120:123], v[144:147], v[188:191], v[120:123]
	v_mfma_f32_16x16x32_bf16 v[120:123], v[152:155], v[192:195], v[120:123]
	v_mfma_f32_16x16x32_bf16 v[104:107], v[144:147], v[196:199], v[104:107]
	v_mfma_f32_16x16x32_bf16 v[104:107], v[152:155], v[200:203], v[104:107]
	v_mfma_f32_16x16x32_bf16 v[88:91], v[144:147], v[204:207], v[88:91]
	v_mfma_f32_16x16x32_bf16 v[88:91], v[152:155], v[208:211], v[88:91]
	v_mfma_f32_16x16x32_bf16 v[80:83], v[156:159], v[204:207], v[80:83]
	v_mfma_f32_16x16x32_bf16 v[80:83], v[160:163], v[208:211], v[80:83]
	v_mfma_f32_16x16x32_bf16 v[96:99], v[156:159], v[196:199], v[96:99]
	v_mfma_f32_16x16x32_bf16 v[96:99], v[160:163], v[200:203], v[96:99]
	v_mfma_f32_16x16x32_bf16 v[112:115], v[156:159], v[188:191], v[112:115]
	v_mfma_f32_16x16x32_bf16 v[112:115], v[160:163], v[192:195], v[112:115]
	v_mfma_f32_16x16x32_bf16 v[124:127], v[156:159], v[180:183], v[124:127]
	v_mfma_f32_16x16x32_bf16 v[124:127], v[160:163], v[184:187], v[124:127]
	v_mfma_f32_16x16x32_bf16 v[116:119], v[164:167], v[180:183], v[116:119]
	v_mfma_f32_16x16x32_bf16 v[116:119], v[168:171], v[184:187], v[116:119]
	v_mfma_f32_16x16x32_bf16 v[100:103], v[164:167], v[188:191], v[100:103]
	v_mfma_f32_16x16x32_bf16 v[100:103], v[168:171], v[192:195], v[100:103]
	v_mfma_f32_16x16x32_bf16 v[84:87], v[164:167], v[196:199], v[84:87]
	v_mfma_f32_16x16x32_bf16 v[84:87], v[168:171], v[200:203], v[84:87]
	v_mfma_f32_16x16x32_bf16 v[72:75], v[164:167], v[204:207], v[72:75]
	v_mfma_f32_16x16x32_bf16 v[72:75], v[168:171], v[208:211], v[72:75]
	v_mfma_f32_16x16x32_bf16 v[68:71], v[172:175], v[204:207], v[68:71]
	v_mfma_f32_16x16x32_bf16 v[68:71], v[176:179], v[208:211], v[68:71]
	v_mfma_f32_16x16x32_bf16 v[76:79], v[172:175], v[196:199], v[76:79]
	v_mfma_f32_16x16x32_bf16 v[76:79], v[176:179], v[200:203], v[76:79]
	v_mfma_f32_16x16x32_bf16 v[92:95], v[172:175], v[188:191], v[92:95]
	v_mfma_f32_16x16x32_bf16 v[92:95], v[176:179], v[192:195], v[92:95]
	v_mfma_f32_16x16x32_bf16 v[108:111], v[172:175], v[180:183], v[108:111]
	v_mfma_f32_16x16x32_bf16 v[108:111], v[176:179], v[184:187], v[108:111]
	s_barrier
;     __device__ __forceinline__ int nt(const Unit& u) const { return (u.pn >> 1) < 2 ? 22 : 20; }
; #define PG8_STAGE(bufoff, gbase, voff) do { _Pragma("unroll") for (int _i = 0; _i < 2; ++_i) \
;         __builtin_amdgcn_global_load_lds((const unsigned*)((const char*)(gbase) + (voff)[_i]), (LAS unsigned*)(lds + (bufoff) + ldsw + _i * 8192), 16, 0, 0); } while (0)
; #define PG8_LDA(dst, b, h) do { _Pragma("unroll") for (int m = 0; m < 4; ++m) _Pragma("unroll") for (int k = 0; k < 2; ++k) dst[m][k] = *(const LAS bf16x8*)(pA + PG8_SA(b, h) + m * 2048 + k * 1024); } while (0)
; #define PG8_MMA(ai, bj, At, Bt) do { __builtin_amdgcn_s_setprio(1); _Pragma("unroll") for (int m = 0; m < 4; ++m) _Pragma("unroll") for (int n = 0; n < 2; ++n) _Pragma("unroll") for (int k = 0; k < 2; ++k) \
;         acc[ai][bj][m][n] = __builtin_amdgcn_mfma_f32_16x16x32_bf16(Bt[n][k], At[m][k], acc[ai][bj][m][n], 0, 0, 0); __builtin_amdgcn_s_setprio(0); } while (0)
; #define PG8_WAIT_V(n) asm volatile("s_waitcnt vmcnt(" #n ")" ::: "memory")
; #define PG8_WAIT_L(n) asm volatile("s_waitcnt lgkmcnt(" #n ")" ::: "memory")
; #define PG8_BAR __builtin_amdgcn_s_barrier()
; #define PG8_SCHED __builtin_amdgcn_sched_barrier(0)
; template <class Desc, class Epi, bool ALIGN_EPI>
; __device__ __forceinline__ void gemm_phase(LAS unsigned char* lds, const Desc& D, const Epi& E, int G, int c) {
;     ...
;         for (int t = 0; t < nt; t += 2) {
;     ...
;             PG8_LDA(At, 1, 1); PG8_STAGE(PG8_SB(1, 0), b3, voffB); PG8_STAGE(PG8_SB(1, 1), b3 + hstepB, voffB); PG8_STAGE(PG8_SA(1, 0), a3, voffA);
;             PG8_WAIT_V(8); PG8_WAIT_L(0); PG8_BAR; PG8_MMA(1, 0, At, B0); PG8_MMA(1, 1, At, B1); PG8_BAR; PG8_SCHED;
;         }
;         if constexpr (ALIGN_EPI) { if (wr == 0) PG8_BAR; }
	s_mov_b32 m0, s35
	v_lshl_add_u64 v[212:213], v[212:213], 0, s[76:77]
	s_add_u32 s18, s18, 0x100080
	ds_read_b128 v[180:183], v148 offset:49152
	ds_read_b128 v[184:187], v148 offset:50176
	ds_read_b128 v[188:191], v148 offset:51200
	ds_read_b128 v[192:195], v148 offset:52224
	ds_read_b128 v[196:199], v148 offset:53248
	ds_read_b128 v[200:203], v148 offset:54272
	ds_read_b128 v[204:207], v148 offset:55296
	ds_read_b128 v[208:211], v148 offset:56320
	global_load_lds_dwordx4 v[212:213], off
	v_lshl_add_u64 v[212:213], v[214:215], 0, s[76:77]
	s_mov_b32 m0, s38
	s_addc_u32 s19, s19, 0
	global_load_lds_dwordx4 v[212:213], off
	v_lshl_add_u64 v[212:213], s[18:19], 0, v[136:137]
	s_mov_b32 m0, s41
	s_nop 0
	global_load_lds_dwordx4 v[212:213], off
	v_lshl_add_u64 v[212:213], s[18:19], 0, v[132:133]
	s_mov_b32 m0, s42
	s_nop 0
	global_load_lds_dwordx4 v[212:213], off
	v_lshl_add_u64 v[212:213], v[216:217], 0, s[76:77]
	s_mov_b32 m0, s39
	s_nop 0
	global_load_lds_dwordx4 v[212:213], off
	v_lshl_add_u64 v[212:213], v[218:219], 0, s[76:77]
	s_mov_b32 m0, s40
	s_nop 0
	global_load_lds_dwordx4 v[212:213], off
	s_waitcnt vmcnt(8)
	s_waitcnt lgkmcnt(0)
	s_barrier
	v_mfma_f32_16x16x32_bf16 v[64:67], v[144:147], v[180:183], v[64:67]
	v_mfma_f32_16x16x32_bf16 v[64:67], v[152:155], v[184:187], v[64:67]
	v_mfma_f32_16x16x32_bf16 v[56:59], v[144:147], v[188:191], v[56:59]
	v_mfma_f32_16x16x32_bf16 v[56:59], v[152:155], v[192:195], v[56:59]
	v_mfma_f32_16x16x32_bf16 v[40:43], v[144:147], v[196:199], v[40:43]
	v_mfma_f32_16x16x32_bf16 v[40:43], v[152:155], v[200:203], v[40:43]
	v_mfma_f32_16x16x32_bf16 v[24:27], v[144:147], v[204:207], v[24:27]
	v_mfma_f32_16x16x32_bf16 v[24:27], v[152:155], v[208:211], v[24:27]
	v_mfma_f32_16x16x32_bf16 v[16:19], v[156:159], v[204:207], v[16:19]
	v_mfma_f32_16x16x32_bf16 v[16:19], v[160:163], v[208:211], v[16:19]
	v_mfma_f32_16x16x32_bf16 v[32:35], v[156:159], v[196:199], v[32:35]
	v_mfma_f32_16x16x32_bf16 v[32:35], v[160:163], v[200:203], v[32:35]
	v_mfma_f32_16x16x32_bf16 v[48:51], v[156:159], v[188:191], v[48:51]
	v_mfma_f32_16x16x32_bf16 v[48:51], v[160:163], v[192:195], v[48:51]
	v_mfma_f32_16x16x32_bf16 v[60:63], v[156:159], v[180:183], v[60:63]
	v_mfma_f32_16x16x32_bf16 v[60:63], v[160:163], v[184:187], v[60:63]
	v_mfma_f32_16x16x32_bf16 v[52:55], v[164:167], v[180:183], v[52:55]
	v_mfma_f32_16x16x32_bf16 v[52:55], v[168:171], v[184:187], v[52:55]
	v_mfma_f32_16x16x32_bf16 v[36:39], v[164:167], v[188:191], v[36:39]
	v_mfma_f32_16x16x32_bf16 v[36:39], v[168:171], v[192:195], v[36:39]
	v_mfma_f32_16x16x32_bf16 v[20:23], v[164:167], v[196:199], v[20:23]
	v_mfma_f32_16x16x32_bf16 v[20:23], v[168:171], v[200:203], v[20:23]
	v_mfma_f32_16x16x32_bf16 v[8:11], v[164:167], v[204:207], v[8:11]
	v_mfma_f32_16x16x32_bf16 v[8:11], v[168:171], v[208:211], v[8:11]
	v_mfma_f32_16x16x32_bf16 v[4:7], v[172:175], v[204:207], v[4:7]
	v_mfma_f32_16x16x32_bf16 v[4:7], v[176:179], v[208:211], v[4:7]
	v_mfma_f32_16x16x32_bf16 v[12:15], v[172:175], v[196:199], v[12:15]
	v_mfma_f32_16x16x32_bf16 v[12:15], v[176:179], v[200:203], v[12:15]
	v_mfma_f32_16x16x32_bf16 v[28:31], v[172:175], v[188:191], v[28:31]
	v_mfma_f32_16x16x32_bf16 v[28:31], v[176:179], v[192:195], v[28:31]
	v_mfma_f32_16x16x32_bf16 v[44:47], v[172:175], v[180:183], v[44:47]
	v_mfma_f32_16x16x32_bf16 v[44:47], v[176:179], v[184:187], v[44:47]
	s_barrier
	s_add_u32 s16, s16, 0x100
	s_addc_u32 s17, s17, 0
	s_add_u32 s48, s48, 0x100
	s_addc_u32 s49, s49, 0
	s_cmp_ge_u32 s50, s46
	s_mov_b32 s18, s50
	s_cbranch_scc0 .LBB0_1324
	s_and_b64 vcc, exec, s[6:7]
	s_cbranch_vccz .LBB0_1327
	s_barrier

;     __device__ __forceinline__ int nt(const Unit& u) const { return (u.pn >> 1) < 2 ? 22 : 20; }
; #define PG8_STAGE(bufoff, gbase, voff) do { _Pragma("unroll") for (int _i = 0; _i < 2; ++_i) \
;         __builtin_amdgcn_global_load_lds((const unsigned*)((const char*)(gbase) + (voff)[_i]), (LAS unsigned*)(lds + (bufoff) + ldsw + _i * 8192), 16, 0, 0); } while (0)
; #define PG8_LDA(dst, b, h) do { _Pragma("unroll") for (int m = 0; m < 4; ++m) _Pragma("unroll") for (int k = 0; k < 2; ++k) dst[m][k] = *(const LAS bf16x8*)(pA + PG8_SA(b, h) + m * 2048 + k * 1024); } while (0)
; #define PG8_LDB(dst, b, h) do { _Pragma("unroll") for (int n = 0; n < 2; ++n) _Pragma("unroll") for (int k = 0; k < 2; ++k) dst[n][k] = *(const LAS bf16x8*)(pB + (PG8_SB(b, h) - 4 * HTB) + n * 2048 + k * 1024); } while (0)
; #define PG8_MMA(ai, bj, At, Bt) do { __builtin_amdgcn_s_setprio(1); _Pragma("unroll") for (int m = 0; m < 4; ++m) _Pragma("unroll") for (int n = 0; n < 2; ++n) _Pragma("unroll") for (int k = 0; k < 2; ++k) \
;         acc[ai][bj][m][n] = __builtin_amdgcn_mfma_f32_16x16x32_bf16(Bt[n][k], At[m][k], acc[ai][bj][m][n], 0, 0, 0); __builtin_amdgcn_s_setprio(0); } while (0)
; #define PG8_WAIT_V(n) asm volatile("s_waitcnt vmcnt(" #n ")" ::: "memory")
; #define PG8_BAR __builtin_amdgcn_s_barrier()
; template <class Desc, class Epi, bool ALIGN_EPI>
; __device__ __forceinline__ void gemm_phase(LAS unsigned char* lds, const Desc& D, const Epi& E, int G, int c) {
;     ...
;         for (int t = 0; t < nt; t += 2) {
;             const bool last = (t == nt - 2);
;             if (last && has_next) PG8_AWAIT(nxt);
;             const char* a1 = cA + (size_t)(t + 1) * kstep;
;             const char* a2 = last ? nA : cA + (size_t)(t + 2) * kstep; const char* b2 = last ? nB : cB + (size_t)(t + 2) * kstep;
;             const char* a3 = a2 + kstep; const char* b3 = b2 + kstep;
;             PG8_LDB(B0, 0, 0); PG8_LDB(B1, 0, 1); PG8_SCHED; PG8_LDA(At, 0, 0); PG8_STAGE(PG8_SA(1, 1), a1 + hstepA, voffA);
;             PG8_WAIT_V(8); PG8_WAIT_L(0); PG8_BAR; PG8_MMA(0, 0, At, B0); PG8_MMA(0, 1, At, B1); PG8_BAR; PG8_SCHED;
;             PG8_LDA(At, 0, 1); PG8_STAGE(PG8_SB(0, 0), b2, voffB); PG8_STAGE(PG8_SB(0, 1), b2 + hstepB, voffB); PG8_STAGE(PG8_SA(0, 0), a2, voffA);
;             PG8_WAIT_V(8); PG8_WAIT_L(0); PG8_BAR; PG8_MMA(1, 0, At, B0); PG8_MMA(1, 1, At, B1); PG8_BAR; PG8_SCHED;
.LBB0_1479:
	ds_read_b128 v[116:119], v225
	ds_read_b128 v[128:131], v225 offset:1024
	ds_read_b128 v[132:135], v225 offset:2048
	ds_read_b128 v[136:139], v225 offset:3072
	ds_read_b128 v[140:143], v225 offset:16384
	ds_read_b128 v[144:147], v225 offset:17408
	ds_read_b128 v[148:151], v225 offset:18432
	ds_read_b128 v[152:155], v225 offset:19456
	s_add_u32 s12, s0, 0xfffe0080
	s_addc_u32 s13, s1, -1
	s_cmp_eq_u32 s52, 4
	s_cselect_b32 s17, s37, s13
	s_cselect_b32 s16, s36, s12
	s_cselect_b32 s13, s21, s33
	s_cselect_b32 s12, s24, s27
	v_lshl_add_u64 v[208:209], s[0:1], 0, v[200:201]
	s_add_i32 m0, s31, 0xc000
	ds_read_b128 v[164:167], v224
	ds_read_b128 v[168:171], v224 offset:1024
	ds_read_b128 v[172:175], v224 offset:2048
	ds_read_b128 v[176:179], v224 offset:3072
	ds_read_b128 v[180:183], v224 offset:4096
	ds_read_b128 v[184:187], v224 offset:5120
	ds_read_b128 v[188:191], v224 offset:6144
	ds_read_b128 v[204:207], v224 offset:7168
	global_load_lds_dwordx4 v[208:209], off
	v_lshl_add_u64 v[208:209], s[0:1], 0, v[202:203]
	s_add_i32 m0, s31, 0xe000
	s_nop 0
	global_load_lds_dwordx4 v[208:209], off
	s_waitcnt vmcnt(8)
	s_waitcnt lgkmcnt(0)
	s_barrier
	v_mfma_f32_16x16x32_bf16 v[160:163], v[116:119], v[164:167], v[160:163]
	v_mfma_f32_16x16x32_bf16 v[160:163], v[128:131], v[168:171], v[160:163]
	v_mfma_f32_16x16x32_bf16 v[112:115], v[116:119], v[172:175], v[112:115]
	v_mfma_f32_16x16x32_bf16 v[112:115], v[128:131], v[176:179], v[112:115]
	v_mfma_f32_16x16x32_bf16 v[96:99], v[116:119], v[180:183], v[96:99]
	v_mfma_f32_16x16x32_bf16 v[96:99], v[128:131], v[184:187], v[96:99]
	v_mfma_f32_16x16x32_bf16 v[80:83], v[116:119], v[188:191], v[80:83]
	v_mfma_f32_16x16x32_bf16 v[80:83], v[128:131], v[204:207], v[80:83]
	v_mfma_f32_16x16x32_bf16 v[76:79], v[132:135], v[188:191], v[76:79]
	v_mfma_f32_16x16x32_bf16 v[76:79], v[136:139], v[204:207], v[76:79]
	v_mfma_f32_16x16x32_bf16 v[92:95], v[132:135], v[180:183], v[92:95]
	v_mfma_f32_16x16x32_bf16 v[92:95], v[136:139], v[184:187], v[92:95]
	v_mfma_f32_16x16x32_bf16 v[108:111], v[132:135], v[172:175], v[108:111]
	v_mfma_f32_16x16x32_bf16 v[108:111], v[136:139], v[176:179], v[108:111]
	v_mfma_f32_16x16x32_bf16 v[156:159], v[132:135], v[164:167], v[156:159]
	v_mfma_f32_16x16x32_bf16 v[156:159], v[136:139], v[168:171], v[156:159]
	v_mfma_f32_16x16x32_bf16 v[124:127], v[140:143], v[164:167], v[124:127]
	v_mfma_f32_16x16x32_bf16 v[124:127], v[144:147], v[168:171], v[124:127]
	v_mfma_f32_16x16x32_bf16 v[104:107], v[140:143], v[172:175], v[104:107]
	v_mfma_f32_16x16x32_bf16 v[104:107], v[144:147], v[176:179], v[104:107]
	v_mfma_f32_16x16x32_bf16 v[88:91], v[140:143], v[180:183], v[88:91]
	v_mfma_f32_16x16x32_bf16 v[88:91], v[144:147], v[184:187], v[88:91]
	v_mfma_f32_16x16x32_bf16 v[72:75], v[140:143], v[188:191], v[72:75]
	v_mfma_f32_16x16x32_bf16 v[72:75], v[144:147], v[204:207], v[72:75]
	v_mfma_f32_16x16x32_bf16 v[68:71], v[148:151], v[188:191], v[68:71]
	v_mfma_f32_16x16x32_bf16 v[68:71], v[152:155], v[204:207], v[68:71]
	v_mfma_f32_16x16x32_bf16 v[84:87], v[148:151], v[180:183], v[84:87]
	v_mfma_f32_16x16x32_bf16 v[84:87], v[152:155], v[184:187], v[84:87]
	v_mfma_f32_16x16x32_bf16 v[100:103], v[148:151], v[172:175], v[100:103]
	v_mfma_f32_16x16x32_bf16 v[100:103], v[152:155], v[176:179], v[100:103]
	v_mfma_f32_16x16x32_bf16 v[120:123], v[148:151], v[164:167], v[120:123]
	v_mfma_f32_16x16x32_bf16 v[120:123], v[152:155], v[168:171], v[120:123]
	s_barrier
	s_mov_b32 m0, s34
	v_lshl_add_u64 v[208:209], s[12:13], 0, v[196:197]
	s_add_u32 s54, s12, 0x20000
	ds_read_b128 v[164:167], v224 offset:16384
	ds_read_b128 v[168:171], v224 offset:17408
	ds_read_b128 v[172:175], v224 offset:18432
	ds_read_b128 v[176:179], v224 offset:19456
	ds_read_b128 v[180:183], v224 offset:20480
	ds_read_b128 v[184:187], v224 offset:21504
	ds_read_b128 v[188:191], v224 offset:22528
	ds_read_b128 v[204:207], v224 offset:23552
	global_load_lds_dwordx4 v[208:209], off
	v_lshl_add_u64 v[210:211], s[12:13], 0, v[192:193]
	s_mov_b32 m0, s35
	s_addc_u32 s55, s13, 0
	global_load_lds_dwordx4 v[210:211], off
	v_lshl_add_u64 v[212:213], s[54:55], 0, v[196:197]
	s_mov_b32 m0, s40
	v_lshl_add_u64 v[214:215], s[16:17], 0, v[194:195]
	global_load_lds_dwordx4 v[212:213], off
	v_lshl_add_u64 v[212:213], s[54:55], 0, v[192:193]
	s_mov_b32 m0, s41
	s_nop 0
	global_load_lds_dwordx4 v[212:213], off
	v_lshl_add_u64 v[212:213], s[16:17], 0, v[198:199]
	s_mov_b32 m0, s31
	s_nop 0
	global_load_lds_dwordx4 v[212:213], off
	s_mov_b32 m0, s42
	s_nop 0
	global_load_lds_dwordx4 v[214:215], off
	s_waitcnt vmcnt(8)
	s_waitcnt lgkmcnt(0)
	s_barrier
; #define PG8_STAGE(bufoff, gbase, voff) do { _Pragma("unroll") for (int _i = 0; _i < 2; ++_i) \
;         __builtin_amdgcn_global_load_lds((const unsigned*)((const char*)(gbase) + (voff)[_i]), (LAS unsigned*)(lds + (bufoff) + ldsw + _i * 8192), 16, 0, 0); } while (0)
; #define PG8_LDA(dst, b, h) do { _Pragma("unroll") for (int m = 0; m < 4; ++m) _Pragma("unroll") for (int k = 0; k < 2; ++k) dst[m][k] = *(const LAS bf16x8*)(pA + PG8_SA(b, h) + m * 2048 + k * 1024); } while (0)
; #define PG8_LDB(dst, b, h) do { _Pragma("unroll") for (int n = 0; n < 2; ++n) _Pragma("unroll") for (int k = 0; k < 2; ++k) dst[n][k] = *(const LAS bf16x8*)(pB + (PG8_SB(b, h) - 4 * HTB) + n * 2048 + k * 1024); } while (0)
; #define PG8_MMA(ai, bj, At, Bt) do { __builtin_amdgcn_s_setprio(1); _Pragma("unroll") for (int m = 0; m < 4; ++m) _Pragma("unroll") for (int n = 0; n < 2; ++n) _Pragma("unroll") for (int k = 0; k < 2; ++k) \
;         acc[ai][bj][m][n] = __builtin_amdgcn_mfma_f32_16x16x32_bf16(Bt[n][k], At[m][k], acc[ai][bj][m][n], 0, 0, 0); __builtin_amdgcn_s_setprio(0); } while (0)
; #define PG8_WAIT_V(n) asm volatile("s_waitcnt vmcnt(" #n ")" ::: "memory")
; #define PG8_WAIT_L(n) asm volatile("s_waitcnt lgkmcnt(" #n ")" ::: "memory")
; #define PG8_BAR __builtin_amdgcn_s_barrier()
; #define PG8_SCHED __builtin_amdgcn_sched_barrier(0)
; template <class Desc, class Epi, bool ALIGN_EPI>
; __device__ __forceinline__ void gemm_phase(LAS unsigned char* lds, const Desc& D, const Epi& E, int G, int c) {
;     ...
;             PG8_WAIT_V(8); PG8_WAIT_L(0); PG8_BAR; PG8_MMA(1, 0, At, B0); PG8_MMA(1, 1, At, B1); PG8_BAR; PG8_SCHED;
;             PG8_LDB(B0, 1, 0); PG8_LDB(B1, 1, 1); PG8_SCHED; PG8_LDA(At, 1, 0); PG8_STAGE(PG8_SA(0, 1), a2 + hstepA, voffA);
;             PG8_WAIT_V(8); PG8_WAIT_L(0); PG8_BAR; PG8_MMA(0, 0, At, B0); PG8_MMA(0, 1, At, B1); PG8_BAR; PG8_SCHED;
	v_mfma_f32_16x16x32_bf16 v[64:67], v[116:119], v[164:167], v[64:67]
	v_mfma_f32_16x16x32_bf16 v[64:67], v[128:131], v[168:171], v[64:67]
	v_mfma_f32_16x16x32_bf16 v[48:51], v[116:119], v[172:175], v[48:51]
	v_mfma_f32_16x16x32_bf16 v[48:51], v[128:131], v[176:179], v[48:51]
	v_mfma_f32_16x16x32_bf16 v[32:35], v[116:119], v[180:183], v[32:35]
	v_mfma_f32_16x16x32_bf16 v[32:35], v[128:131], v[184:187], v[32:35]
	v_mfma_f32_16x16x32_bf16 v[16:19], v[116:119], v[188:191], v[16:19]
	v_mfma_f32_16x16x32_bf16 v[16:19], v[128:131], v[204:207], v[16:19]
	v_mfma_f32_16x16x32_bf16 v[12:15], v[132:135], v[188:191], v[12:15]
	v_mfma_f32_16x16x32_bf16 v[12:15], v[136:139], v[204:207], v[12:15]
	v_mfma_f32_16x16x32_bf16 v[28:31], v[132:135], v[180:183], v[28:31]
	v_mfma_f32_16x16x32_bf16 v[28:31], v[136:139], v[184:187], v[28:31]
	v_mfma_f32_16x16x32_bf16 v[44:47], v[132:135], v[172:175], v[44:47]
	v_mfma_f32_16x16x32_bf16 v[44:47], v[136:139], v[176:179], v[44:47]
	v_mfma_f32_16x16x32_bf16 v[60:63], v[132:135], v[164:167], v[60:63]
	v_mfma_f32_16x16x32_bf16 v[60:63], v[136:139], v[168:171], v[60:63]
	v_mfma_f32_16x16x32_bf16 v[56:59], v[140:143], v[164:167], v[56:59]
	v_mfma_f32_16x16x32_bf16 v[56:59], v[144:147], v[168:171], v[56:59]
	v_mfma_f32_16x16x32_bf16 v[40:43], v[140:143], v[172:175], v[40:43]
	v_mfma_f32_16x16x32_bf16 v[40:43], v[144:147], v[176:179], v[40:43]
	v_mfma_f32_16x16x32_bf16 v[24:27], v[140:143], v[180:183], v[24:27]
	v_mfma_f32_16x16x32_bf16 v[24:27], v[144:147], v[184:187], v[24:27]
	v_mfma_f32_16x16x32_bf16 v[8:11], v[140:143], v[188:191], v[8:11]
	v_mfma_f32_16x16x32_bf16 v[8:11], v[144:147], v[204:207], v[8:11]
	v_mfma_f32_16x16x32_bf16 v[4:7], v[148:151], v[188:191], v[4:7]
	v_mfma_f32_16x16x32_bf16 v[4:7], v[152:155], v[204:207], v[4:7]
	v_mfma_f32_16x16x32_bf16 v[20:23], v[148:151], v[180:183], v[20:23]
	v_mfma_f32_16x16x32_bf16 v[20:23], v[152:155], v[184:187], v[20:23]
	v_mfma_f32_16x16x32_bf16 v[36:39], v[148:151], v[172:175], v[36:39]
	v_mfma_f32_16x16x32_bf16 v[36:39], v[152:155], v[176:179], v[36:39]
	v_mfma_f32_16x16x32_bf16 v[52:55], v[148:151], v[164:167], v[52:55]
	v_mfma_f32_16x16x32_bf16 v[52:55], v[152:155], v[168:171], v[52:55]
	s_barrier
	ds_read_b128 v[116:119], v225 offset:32768
	ds_read_b128 v[128:131], v225 offset:33792
	ds_read_b128 v[132:135], v225 offset:34816
	ds_read_b128 v[136:139], v225 offset:35840
	ds_read_b128 v[140:143], v225 offset:49152
	ds_read_b128 v[144:147], v225 offset:50176
	ds_read_b128 v[148:151], v225 offset:51200
	ds_read_b128 v[152:155], v225 offset:52224
	s_add_u32 s16, s16, 0x20000
	s_addc_u32 s17, s17, 0
	s_mov_b32 m0, s43
	v_lshl_add_u64 v[216:217], s[16:17], 0, v[198:199]
	ds_read_b128 v[164:167], v224 offset:32768
	ds_read_b128 v[168:171], v224 offset:33792
	ds_read_b128 v[172:175], v224 offset:34816
	ds_read_b128 v[176:179], v224 offset:35840
	ds_read_b128 v[180:183], v224 offset:36864
	ds_read_b128 v[184:187], v224 offset:37888
	ds_read_b128 v[188:191], v224 offset:38912
	ds_read_b128 v[204:207], v224 offset:39936
	global_load_lds_dwordx4 v[216:217], off
	v_lshl_add_u64 v[216:217], s[16:17], 0, v[194:195]
	s_mov_b32 m0, s44
	s_nop 0
	global_load_lds_dwordx4 v[216:217], off
	s_waitcnt vmcnt(8)
	s_waitcnt lgkmcnt(0)
	s_barrier
	v_mfma_f32_16x16x32_bf16 v[160:163], v[116:119], v[164:167], v[160:163]
	v_mfma_f32_16x16x32_bf16 v[160:163], v[128:131], v[168:171], v[160:163]
	v_mfma_f32_16x16x32_bf16 v[112:115], v[116:119], v[172:175], v[112:115]
	v_mfma_f32_16x16x32_bf16 v[112:115], v[128:131], v[176:179], v[112:115]
	v_mfma_f32_16x16x32_bf16 v[96:99], v[116:119], v[180:183], v[96:99]
	v_mfma_f32_16x16x32_bf16 v[96:99], v[128:131], v[184:187], v[96:99]
	v_mfma_f32_16x16x32_bf16 v[80:83], v[116:119], v[188:191], v[80:83]
	v_mfma_f32_16x16x32_bf16 v[80:83], v[128:131], v[204:207], v[80:83]
	v_mfma_f32_16x16x32_bf16 v[76:79], v[132:135], v[188:191], v[76:79]
	v_mfma_f32_16x16x32_bf16 v[76:79], v[136:139], v[204:207], v[76:79]
	v_mfma_f32_16x16x32_bf16 v[92:95], v[132:135], v[180:183], v[92:95]
	v_mfma_f32_16x16x32_bf16 v[92:95], v[136:139], v[184:187], v[92:95]
	v_mfma_f32_16x16x32_bf16 v[108:111], v[132:135], v[172:175], v[108:111]
	v_mfma_f32_16x16x32_bf16 v[108:111], v[136:139], v[176:179], v[108:111]
	v_mfma_f32_16x16x32_bf16 v[156:159], v[132:135], v[164:167], v[156:159]
	v_mfma_f32_16x16x32_bf16 v[156:159], v[136:139], v[168:171], v[156:159]
	v_mfma_f32_16x16x32_bf16 v[124:127], v[140:143], v[164:167], v[124:127]
	v_mfma_f32_16x16x32_bf16 v[124:127], v[144:147], v[168:171], v[124:127]
	v_mfma_f32_16x16x32_bf16 v[104:107], v[140:143], v[172:175], v[104:107]
	v_mfma_f32_16x16x32_bf16 v[104:107], v[144:147], v[176:179], v[104:107]
	v_mfma_f32_16x16x32_bf16 v[88:91], v[140:143], v[180:183], v[88:91]
	v_mfma_f32_16x16x32_bf16 v[88:91], v[144:147], v[184:187], v[88:91]
	v_mfma_f32_16x16x32_bf16 v[72:75], v[140:143], v[188:191], v[72:75]
	v_mfma_f32_16x16x32_bf16 v[72:75], v[144:147], v[204:207], v[72:75]
	v_mfma_f32_16x16x32_bf16 v[68:71], v[148:151], v[188:191], v[68:71]
	v_mfma_f32_16x16x32_bf16 v[68:71], v[152:155], v[204:207], v[68:71]
	v_mfma_f32_16x16x32_bf16 v[84:87], v[148:151], v[180:183], v[84:87]
	v_mfma_f32_16x16x32_bf16 v[84:87], v[152:155], v[184:187], v[84:87]
	v_mfma_f32_16x16x32_bf16 v[100:103], v[148:151], v[172:175], v[100:103]
	v_mfma_f32_16x16x32_bf16 v[100:103], v[152:155], v[176:179], v[100:103]
	v_mfma_f32_16x16x32_bf16 v[120:123], v[148:151], v[164:167], v[120:123]
	v_mfma_f32_16x16x32_bf16 v[120:123], v[152:155], v[168:171], v[120:123]
	s_barrier
;     __device__ __forceinline__ int nt(const Unit& u) const { return (u.pn >> 1) < 2 ? 22 : 20; }
; #define PG8_STAGE(bufoff, gbase, voff) do { _Pragma("unroll") for (int _i = 0; _i < 2; ++_i) \
;         __builtin_amdgcn_global_load_lds((const unsigned*)((const char*)(gbase) + (voff)[_i]), (LAS unsigned*)(lds + (bufoff) + ldsw + _i * 8192), 16, 0, 0); } while (0)
; #define PG8_LDA(dst, b, h) do { _Pragma("unroll") for (int m = 0; m < 4; ++m) _Pragma("unroll") for (int k = 0; k < 2; ++k) dst[m][k] = *(const LAS bf16x8*)(pA + PG8_SA(b, h) + m * 2048 + k * 1024); } while (0)
; #define PG8_MMA(ai, bj, At, Bt) do { __builtin_amdgcn_s_setprio(1); _Pragma("unroll") for (int m = 0; m < 4; ++m) _Pragma("unroll") for (int n = 0; n < 2; ++n) _Pragma("unroll") for (int k = 0; k < 2; ++k) \
;         acc[ai][bj][m][n] = __builtin_amdgcn_mfma_f32_16x16x32_bf16(Bt[n][k], At[m][k], acc[ai][bj][m][n], 0, 0, 0); __builtin_amdgcn_s_setprio(0); } while (0)
; #define PG8_WAIT_V(n) asm volatile("s_waitcnt vmcnt(" #n ")" ::: "memory")
; #define PG8_WAIT_L(n) asm volatile("s_waitcnt lgkmcnt(" #n ")" ::: "memory")
; #define PG8_BAR __builtin_amdgcn_s_barrier()
; #define PG8_SCHED __builtin_amdgcn_sched_barrier(0)
; template <class Desc, class Epi, bool ALIGN_EPI>
; __device__ __forceinline__ void gemm_phase(LAS unsigned char* lds, const Desc& D, const Epi& E, int G, int c) {
;     ...
;         for (int t = 0; t < nt; t += 2) {
;     ...
;             PG8_LDA(At, 1, 1); PG8_STAGE(PG8_SB(1, 0), b3, voffB); PG8_STAGE(PG8_SB(1, 1), b3 + hstepB, voffB); PG8_STAGE(PG8_SA(1, 0), a3, voffA);
;             PG8_WAIT_V(8); PG8_WAIT_L(0); PG8_BAR; PG8_MMA(1, 0, At, B0); PG8_MMA(1, 1, At, B1); PG8_BAR; PG8_SCHED;
;         }
;         if constexpr (ALIGN_EPI) { if (wr == 0) PG8_BAR; }
	s_mov_b32 m0, s45
	v_lshl_add_u64 v[208:209], v[208:209], 0, s[76:77]
	s_add_u32 s12, s12, 0x20080
	ds_read_b128 v[164:167], v224 offset:49152
	ds_read_b128 v[168:171], v224 offset:50176
	ds_read_b128 v[172:175], v224 offset:51200
	ds_read_b128 v[176:179], v224 offset:52224
	ds_read_b128 v[180:183], v224 offset:53248
	ds_read_b128 v[184:187], v224 offset:54272
	ds_read_b128 v[188:191], v224 offset:55296
	ds_read_b128 v[204:207], v224 offset:56320
	global_load_lds_dwordx4 v[208:209], off
	v_lshl_add_u64 v[208:209], v[210:211], 0, s[76:77]
	s_mov_b32 m0, s46
	s_addc_u32 s13, s13, 0
	global_load_lds_dwordx4 v[208:209], off
	v_lshl_add_u64 v[208:209], s[12:13], 0, v[196:197]
	s_mov_b32 m0, s49
	s_nop 0
	global_load_lds_dwordx4 v[208:209], off
	v_lshl_add_u64 v[208:209], s[12:13], 0, v[192:193]
	s_mov_b32 m0, s50
	s_nop 0
	global_load_lds_dwordx4 v[208:209], off
	v_lshl_add_u64 v[208:209], v[212:213], 0, s[76:77]
	s_mov_b32 m0, s47
	s_nop 0
	global_load_lds_dwordx4 v[208:209], off
	v_lshl_add_u64 v[208:209], v[214:215], 0, s[76:77]
	s_mov_b32 m0, s48
	s_nop 0
	global_load_lds_dwordx4 v[208:209], off
	s_waitcnt vmcnt(8)
	s_waitcnt lgkmcnt(0)
	s_barrier
	v_mfma_f32_16x16x32_bf16 v[64:67], v[116:119], v[164:167], v[64:67]
	v_mfma_f32_16x16x32_bf16 v[64:67], v[128:131], v[168:171], v[64:67]
	v_mfma_f32_16x16x32_bf16 v[48:51], v[116:119], v[172:175], v[48:51]
	v_mfma_f32_16x16x32_bf16 v[48:51], v[128:131], v[176:179], v[48:51]
	v_mfma_f32_16x16x32_bf16 v[32:35], v[116:119], v[180:183], v[32:35]
	v_mfma_f32_16x16x32_bf16 v[32:35], v[128:131], v[184:187], v[32:35]
	v_mfma_f32_16x16x32_bf16 v[16:19], v[116:119], v[188:191], v[16:19]
	v_mfma_f32_16x16x32_bf16 v[16:19], v[128:131], v[204:207], v[16:19]
	v_mfma_f32_16x16x32_bf16 v[12:15], v[132:135], v[188:191], v[12:15]
	v_mfma_f32_16x16x32_bf16 v[12:15], v[136:139], v[204:207], v[12:15]
	v_mfma_f32_16x16x32_bf16 v[28:31], v[132:135], v[180:183], v[28:31]
	v_mfma_f32_16x16x32_bf16 v[28:31], v[136:139], v[184:187], v[28:31]
	v_mfma_f32_16x16x32_bf16 v[44:47], v[132:135], v[172:175], v[44:47]
	v_mfma_f32_16x16x32_bf16 v[44:47], v[136:139], v[176:179], v[44:47]
	v_mfma_f32_16x16x32_bf16 v[60:63], v[132:135], v[164:167], v[60:63]
	v_mfma_f32_16x16x32_bf16 v[60:63], v[136:139], v[168:171], v[60:63]
	v_mfma_f32_16x16x32_bf16 v[56:59], v[140:143], v[164:167], v[56:59]
	v_mfma_f32_16x16x32_bf16 v[56:59], v[144:147], v[168:171], v[56:59]
	v_mfma_f32_16x16x32_bf16 v[40:43], v[140:143], v[172:175], v[40:43]
	v_mfma_f32_16x16x32_bf16 v[40:43], v[144:147], v[176:179], v[40:43]
	v_mfma_f32_16x16x32_bf16 v[24:27], v[140:143], v[180:183], v[24:27]
	v_mfma_f32_16x16x32_bf16 v[24:27], v[144:147], v[184:187], v[24:27]
	v_mfma_f32_16x16x32_bf16 v[8:11], v[140:143], v[188:191], v[8:11]
	v_mfma_f32_16x16x32_bf16 v[8:11], v[144:147], v[204:207], v[8:11]
	v_mfma_f32_16x16x32_bf16 v[4:7], v[148:151], v[188:191], v[4:7]
	v_mfma_f32_16x16x32_bf16 v[4:7], v[152:155], v[204:207], v[4:7]
	v_mfma_f32_16x16x32_bf16 v[20:23], v[148:151], v[180:183], v[20:23]
	v_mfma_f32_16x16x32_bf16 v[20:23], v[152:155], v[184:187], v[20:23]
	v_mfma_f32_16x16x32_bf16 v[36:39], v[148:151], v[172:175], v[36:39]
	v_mfma_f32_16x16x32_bf16 v[36:39], v[152:155], v[176:179], v[36:39]
	v_mfma_f32_16x16x32_bf16 v[52:55], v[148:151], v[164:167], v[52:55]
	v_mfma_f32_16x16x32_bf16 v[52:55], v[152:155], v[168:171], v[52:55]
	s_barrier
	s_add_i32 s52, s52, 2
	s_add_u32 s0, s0, 0x100
	s_addc_u32 s1, s1, 0
	s_add_u32 s27, s27, 0x100
	s_addc_u32 s33, s33, 0
	s_cmp_gt_u32 s52, 5
	s_cbranch_scc0 .LBB0_1479
	s_and_b64 vcc, exec, s[8:9]
	s_cbranch_vccz .LBB0_1482
	s_barrier

;     __device__ __forceinline__ int nt(const Unit& u) const { return (u.pn >> 1) < 2 ? 22 : 20; }
; #define PG8_STAGE(bufoff, gbase, voff) do { _Pragma("unroll") for (int _i = 0; _i < 2; ++_i) \
;         __builtin_amdgcn_global_load_lds((const unsigned*)((const char*)(gbase) + (voff)[_i]), (LAS unsigned*)(lds + (bufoff) + ldsw + _i * 8192), 16, 0, 0); } while (0)
; #define PG8_LDA(dst, b, h) do { _Pragma("unroll") for (int m = 0; m < 4; ++m) _Pragma("unroll") for (int k = 0; k < 2; ++k) dst[m][k] = *(const LAS bf16x8*)(pA + PG8_SA(b, h) + m * 2048 + k * 1024); } while (0)
; #define PG8_LDB(dst, b, h) do { _Pragma("unroll") for (int n = 0; n < 2; ++n) _Pragma("unroll") for (int k = 0; k < 2; ++k) dst[n][k] = *(const LAS bf16x8*)(pB + (PG8_SB(b, h) - 4 * HTB) + n * 2048 + k * 1024); } while (0)
; #define PG8_MMA(ai, bj, At, Bt) do { __builtin_amdgcn_s_setprio(1); _Pragma("unroll") for (int m = 0; m < 4; ++m) _Pragma("unroll") for (int n = 0; n < 2; ++n) _Pragma("unroll") for (int k = 0; k < 2; ++k) \
;         acc[ai][bj][m][n] = __builtin_amdgcn_mfma_f32_16x16x32_bf16(Bt[n][k], At[m][k], acc[ai][bj][m][n], 0, 0, 0); __builtin_amdgcn_s_setprio(0); } while (0)
; #define PG8_WAIT_V(n) asm volatile("s_waitcnt vmcnt(" #n ")" ::: "memory")
; #define PG8_BAR __builtin_amdgcn_s_barrier()
; template <class Desc, class Epi, bool ALIGN_EPI>
; __device__ __forceinline__ void gemm_phase(LAS unsigned char* lds, const Desc& D, const Epi& E, int G, int c) {
;     ...
;         for (int t = 0; t < nt; t += 2) {
;             const bool last = (t == nt - 2);
;             if (last && has_next) PG8_AWAIT(nxt);
;             const char* a1 = cA + (size_t)(t + 1) * kstep;
;             const char* a2 = last ? nA : cA + (size_t)(t + 2) * kstep; const char* b2 = last ? nB : cB + (size_t)(t + 2) * kstep;
;             const char* a3 = a2 + kstep; const char* b3 = b2 + kstep;
;             PG8_LDB(B0, 0, 0); PG8_LDB(B1, 0, 1); PG8_SCHED; PG8_LDA(At, 0, 0); PG8_STAGE(PG8_SA(1, 1), a1 + hstepA, voffA);
;             PG8_WAIT_V(8); PG8_WAIT_L(0); PG8_BAR; PG8_MMA(0, 0, At, B0); PG8_MMA(0, 1, At, B1); PG8_BAR; PG8_SCHED;
;             PG8_LDA(At, 0, 1); PG8_STAGE(PG8_SB(0, 0), b2, voffB); PG8_STAGE(PG8_SB(0, 1), b2 + hstepB, voffB); PG8_STAGE(PG8_SA(0, 0), a2, voffA);
;             PG8_WAIT_V(8); PG8_WAIT_L(0); PG8_BAR; PG8_MMA(1, 0, At, B0); PG8_MMA(1, 1, At, B1); PG8_BAR; PG8_SCHED;
.LBB0_1517:
	ds_read_b128 v[116:119], v225
	ds_read_b128 v[128:131], v225 offset:1024
	ds_read_b128 v[132:135], v225 offset:2048
	ds_read_b128 v[136:139], v225 offset:3072
	ds_read_b128 v[140:143], v225 offset:16384
	ds_read_b128 v[144:147], v225 offset:17408
	ds_read_b128 v[148:151], v225 offset:18432
	ds_read_b128 v[152:155], v225 offset:19456
	s_add_u32 s12, s0, 0xfffe0080
	s_addc_u32 s13, s1, -1
	s_cmp_eq_u32 s54, 4
	s_cselect_b32 s17, s37, s13
	s_cselect_b32 s16, s36, s12
	s_cselect_b32 s13, s21, s33
	s_cselect_b32 s12, s24, s27
	v_lshl_add_u64 v[208:209], s[0:1], 0, v[200:201]
	s_add_i32 m0, s31, 0xc000
	ds_read_b128 v[164:167], v224
	ds_read_b128 v[168:171], v224 offset:1024
	ds_read_b128 v[172:175], v224 offset:2048
	ds_read_b128 v[176:179], v224 offset:3072
	ds_read_b128 v[180:183], v224 offset:4096
	ds_read_b128 v[184:187], v224 offset:5120
	ds_read_b128 v[188:191], v224 offset:6144
	ds_read_b128 v[204:207], v224 offset:7168
	global_load_lds_dwordx4 v[208:209], off
	v_lshl_add_u64 v[208:209], s[0:1], 0, v[202:203]
	s_add_i32 m0, s31, 0xe000
	s_nop 0
	global_load_lds_dwordx4 v[208:209], off
	s_waitcnt vmcnt(8)
	s_waitcnt lgkmcnt(0)
	s_barrier
	v_mfma_f32_16x16x32_bf16 v[160:163], v[116:119], v[164:167], v[160:163]
	v_mfma_f32_16x16x32_bf16 v[160:163], v[128:131], v[168:171], v[160:163]
	v_mfma_f32_16x16x32_bf16 v[112:115], v[116:119], v[172:175], v[112:115]
	v_mfma_f32_16x16x32_bf16 v[112:115], v[128:131], v[176:179], v[112:115]
	v_mfma_f32_16x16x32_bf16 v[96:99], v[116:119], v[180:183], v[96:99]
	v_mfma_f32_16x16x32_bf16 v[96:99], v[128:131], v[184:187], v[96:99]
	v_mfma_f32_16x16x32_bf16 v[80:83], v[116:119], v[188:191], v[80:83]
	v_mfma_f32_16x16x32_bf16 v[80:83], v[128:131], v[204:207], v[80:83]
	v_mfma_f32_16x16x32_bf16 v[76:79], v[132:135], v[188:191], v[76:79]
	v_mfma_f32_16x16x32_bf16 v[76:79], v[136:139], v[204:207], v[76:79]
	v_mfma_f32_16x16x32_bf16 v[92:95], v[132:135], v[180:183], v[92:95]
	v_mfma_f32_16x16x32_bf16 v[92:95], v[136:139], v[184:187], v[92:95]
	v_mfma_f32_16x16x32_bf16 v[108:111], v[132:135], v[172:175], v[108:111]
	v_mfma_f32_16x16x32_bf16 v[108:111], v[136:139], v[176:179], v[108:111]
	v_mfma_f32_16x16x32_bf16 v[156:159], v[132:135], v[164:167], v[156:159]
	v_mfma_f32_16x16x32_bf16 v[156:159], v[136:139], v[168:171], v[156:159]
	v_mfma_f32_16x16x32_bf16 v[124:127], v[140:143], v[164:167], v[124:127]
	v_mfma_f32_16x16x32_bf16 v[124:127], v[144:147], v[168:171], v[124:127]
	v_mfma_f32_16x16x32_bf16 v[104:107], v[140:143], v[172:175], v[104:107]
	v_mfma_f32_16x16x32_bf16 v[104:107], v[144:147], v[176:179], v[104:107]
	v_mfma_f32_16x16x32_bf16 v[88:91], v[140:143], v[180:183], v[88:91]
	v_mfma_f32_16x16x32_bf16 v[88:91], v[144:147], v[184:187], v[88:91]
	v_mfma_f32_16x16x32_bf16 v[72:75], v[140:143], v[188:191], v[72:75]
	v_mfma_f32_16x16x32_bf16 v[72:75], v[144:147], v[204:207], v[72:75]
	v_mfma_f32_16x16x32_bf16 v[68:71], v[148:151], v[188:191], v[68:71]
	v_mfma_f32_16x16x32_bf16 v[68:71], v[152:155], v[204:207], v[68:71]
	v_mfma_f32_16x16x32_bf16 v[84:87], v[148:151], v[180:183], v[84:87]
	v_mfma_f32_16x16x32_bf16 v[84:87], v[152:155], v[184:187], v[84:87]
	v_mfma_f32_16x16x32_bf16 v[100:103], v[148:151], v[172:175], v[100:103]
	v_mfma_f32_16x16x32_bf16 v[100:103], v[152:155], v[176:179], v[100:103]
	v_mfma_f32_16x16x32_bf16 v[120:123], v[148:151], v[164:167], v[120:123]
	v_mfma_f32_16x16x32_bf16 v[120:123], v[152:155], v[168:171], v[120:123]
	s_barrier
	s_mov_b32 m0, s34
	v_lshl_add_u64 v[208:209], s[12:13], 0, v[196:197]
	s_add_u32 s56, s12, 0x20000
	ds_read_b128 v[164:167], v224 offset:16384
	ds_read_b128 v[168:171], v224 offset:17408
	ds_read_b128 v[172:175], v224 offset:18432
	ds_read_b128 v[176:179], v224 offset:19456
	ds_read_b128 v[180:183], v224 offset:20480
	ds_read_b128 v[184:187], v224 offset:21504
	ds_read_b128 v[188:191], v224 offset:22528
	ds_read_b128 v[204:207], v224 offset:23552
	global_load_lds_dwordx4 v[208:209], off
	v_lshl_add_u64 v[210:211], s[12:13], 0, v[192:193]
	s_mov_b32 m0, s35
	s_addc_u32 s57, s13, 0
	global_load_lds_dwordx4 v[210:211], off
	v_lshl_add_u64 v[212:213], s[56:57], 0, v[196:197]
	s_mov_b32 m0, s42
	v_lshl_add_u64 v[214:215], s[16:17], 0, v[194:195]
	global_load_lds_dwordx4 v[212:213], off
	v_lshl_add_u64 v[212:213], s[56:57], 0, v[192:193]
	s_mov_b32 m0, s43
	s_nop 0
	global_load_lds_dwordx4 v[212:213], off
	v_lshl_add_u64 v[212:213], s[16:17], 0, v[198:199]
	s_mov_b32 m0, s31
	s_nop 0
	global_load_lds_dwordx4 v[212:213], off
	s_mov_b32 m0, s44
	s_nop 0
	global_load_lds_dwordx4 v[214:215], off
	s_waitcnt vmcnt(8)
	s_waitcnt lgkmcnt(0)
	s_barrier
; #define PG8_STAGE(bufoff, gbase, voff) do { _Pragma("unroll") for (int _i = 0; _i < 2; ++_i) \
;         __builtin_amdgcn_global_load_lds((const unsigned*)((const char*)(gbase) + (voff)[_i]), (LAS unsigned*)(lds + (bufoff) + ldsw + _i * 8192), 16, 0, 0); } while (0)
; #define PG8_LDA(dst, b, h) do { _Pragma("unroll") for (int m = 0; m < 4; ++m) _Pragma("unroll") for (int k = 0; k < 2; ++k) dst[m][k] = *(const LAS bf16x8*)(pA + PG8_SA(b, h) + m * 2048 + k * 1024); } while (0)
; #define PG8_LDB(dst, b, h) do { _Pragma("unroll") for (int n = 0; n < 2; ++n) _Pragma("unroll") for (int k = 0; k < 2; ++k) dst[n][k] = *(const LAS bf16x8*)(pB + (PG8_SB(b, h) - 4 * HTB) + n * 2048 + k * 1024); } while (0)
; #define PG8_MMA(ai, bj, At, Bt) do { __builtin_amdgcn_s_setprio(1); _Pragma("unroll") for (int m = 0; m < 4; ++m) _Pragma("unroll") for (int n = 0; n < 2; ++n) _Pragma("unroll") for (int k = 0; k < 2; ++k) \
;         acc[ai][bj][m][n] = __builtin_amdgcn_mfma_f32_16x16x32_bf16(Bt[n][k], At[m][k], acc[ai][bj][m][n], 0, 0, 0); __builtin_amdgcn_s_setprio(0); } while (0)
; #define PG8_WAIT_V(n) asm volatile("s_waitcnt vmcnt(" #n ")" ::: "memory")
; #define PG8_WAIT_L(n) asm volatile("s_waitcnt lgkmcnt(" #n ")" ::: "memory")
; #define PG8_BAR __builtin_amdgcn_s_barrier()
; #define PG8_SCHED __builtin_amdgcn_sched_barrier(0)
; template <class Desc, class Epi, bool ALIGN_EPI>
; __device__ __forceinline__ void gemm_phase(LAS unsigned char* lds, const Desc& D, const Epi& E, int G, int c) {
;     ...
;             PG8_WAIT_V(8); PG8_WAIT_L(0); PG8_BAR; PG8_MMA(1, 0, At, B0); PG8_MMA(1, 1, At, B1); PG8_BAR; PG8_SCHED;
;             PG8_LDB(B0, 1, 0); PG8_LDB(B1, 1, 1); PG8_SCHED; PG8_LDA(At, 1, 0); PG8_STAGE(PG8_SA(0, 1), a2 + hstepA, voffA);
;             PG8_WAIT_V(8); PG8_WAIT_L(0); PG8_BAR; PG8_MMA(0, 0, At, B0); PG8_MMA(0, 1, At, B1); PG8_BAR; PG8_SCHED;
	v_mfma_f32_16x16x32_bf16 v[64:67], v[116:119], v[164:167], v[64:67]
	v_mfma_f32_16x16x32_bf16 v[64:67], v[128:131], v[168:171], v[64:67]
	v_mfma_f32_16x16x32_bf16 v[48:51], v[116:119], v[172:175], v[48:51]
	v_mfma_f32_16x16x32_bf16 v[48:51], v[128:131], v[176:179], v[48:51]
	v_mfma_f32_16x16x32_bf16 v[32:35], v[116:119], v[180:183], v[32:35]
	v_mfma_f32_16x16x32_bf16 v[32:35], v[128:131], v[184:187], v[32:35]
	v_mfma_f32_16x16x32_bf16 v[16:19], v[116:119], v[188:191], v[16:19]
	v_mfma_f32_16x16x32_bf16 v[16:19], v[128:131], v[204:207], v[16:19]
	v_mfma_f32_16x16x32_bf16 v[12:15], v[132:135], v[188:191], v[12:15]
	v_mfma_f32_16x16x32_bf16 v[12:15], v[136:139], v[204:207], v[12:15]
	v_mfma_f32_16x16x32_bf16 v[28:31], v[132:135], v[180:183], v[28:31]
	v_mfma_f32_16x16x32_bf16 v[28:31], v[136:139], v[184:187], v[28:31]
	v_mfma_f32_16x16x32_bf16 v[44:47], v[132:135], v[172:175], v[44:47]
	v_mfma_f32_16x16x32_bf16 v[44:47], v[136:139], v[176:179], v[44:47]
	v_mfma_f32_16x16x32_bf16 v[60:63], v[132:135], v[164:167], v[60:63]
	v_mfma_f32_16x16x32_bf16 v[60:63], v[136:139], v[168:171], v[60:63]
	v_mfma_f32_16x16x32_bf16 v[56:59], v[140:143], v[164:167], v[56:59]
	v_mfma_f32_16x16x32_bf16 v[56:59], v[144:147], v[168:171], v[56:59]
	v_mfma_f32_16x16x32_bf16 v[40:43], v[140:143], v[172:175], v[40:43]
	v_mfma_f32_16x16x32_bf16 v[40:43], v[144:147], v[176:179], v[40:43]
	v_mfma_f32_16x16x32_bf16 v[24:27], v[140:143], v[180:183], v[24:27]
	v_mfma_f32_16x16x32_bf16 v[24:27], v[144:147], v[184:187], v[24:27]
	v_mfma_f32_16x16x32_bf16 v[8:11], v[140:143], v[188:191], v[8:11]
	v_mfma_f32_16x16x32_bf16 v[8:11], v[144:147], v[204:207], v[8:11]
	v_mfma_f32_16x16x32_bf16 v[4:7], v[148:151], v[188:191], v[4:7]
	v_mfma_f32_16x16x32_bf16 v[4:7], v[152:155], v[204:207], v[4:7]
	v_mfma_f32_16x16x32_bf16 v[20:23], v[148:151], v[180:183], v[20:23]
	v_mfma_f32_16x16x32_bf16 v[20:23], v[152:155], v[184:187], v[20:23]
	v_mfma_f32_16x16x32_bf16 v[36:39], v[148:151], v[172:175], v[36:39]
	v_mfma_f32_16x16x32_bf16 v[36:39], v[152:155], v[176:179], v[36:39]
	v_mfma_f32_16x16x32_bf16 v[52:55], v[148:151], v[164:167], v[52:55]
	v_mfma_f32_16x16x32_bf16 v[52:55], v[152:155], v[168:171], v[52:55]
	s_barrier
	ds_read_b128 v[116:119], v225 offset:32768
	ds_read_b128 v[128:131], v225 offset:33792
	ds_read_b128 v[132:135], v225 offset:34816
	ds_read_b128 v[136:139], v225 offset:35840
	ds_read_b128 v[140:143], v225 offset:49152
	ds_read_b128 v[144:147], v225 offset:50176
	ds_read_b128 v[148:151], v225 offset:51200
	ds_read_b128 v[152:155], v225 offset:52224
	s_add_u32 s16, s16, 0x20000
	s_addc_u32 s17, s17, 0
	s_mov_b32 m0, s45
	v_lshl_add_u64 v[216:217], s[16:17], 0, v[198:199]
	ds_read_b128 v[164:167], v224 offset:32768
	ds_read_b128 v[168:171], v224 offset:33792
	ds_read_b128 v[172:175], v224 offset:34816
	ds_read_b128 v[176:179], v224 offset:35840
	ds_read_b128 v[180:183], v224 offset:36864
	ds_read_b128 v[184:187], v224 offset:37888
	ds_read_b128 v[188:191], v224 offset:38912
	ds_read_b128 v[204:207], v224 offset:39936
	global_load_lds_dwordx4 v[216:217], off
	v_lshl_add_u64 v[216:217], s[16:17], 0, v[194:195]
	s_mov_b32 m0, s46
	s_nop 0
	global_load_lds_dwordx4 v[216:217], off
	s_waitcnt vmcnt(8)
	s_waitcnt lgkmcnt(0)
	s_barrier
	v_mfma_f32_16x16x32_bf16 v[160:163], v[116:119], v[164:167], v[160:163]
	v_mfma_f32_16x16x32_bf16 v[160:163], v[128:131], v[168:171], v[160:163]
	v_mfma_f32_16x16x32_bf16 v[112:115], v[116:119], v[172:175], v[112:115]
	v_mfma_f32_16x16x32_bf16 v[112:115], v[128:131], v[176:179], v[112:115]
	v_mfma_f32_16x16x32_bf16 v[96:99], v[116:119], v[180:183], v[96:99]
	v_mfma_f32_16x16x32_bf16 v[96:99], v[128:131], v[184:187], v[96:99]
	v_mfma_f32_16x16x32_bf16 v[80:83], v[116:119], v[188:191], v[80:83]
	v_mfma_f32_16x16x32_bf16 v[80:83], v[128:131], v[204:207], v[80:83]
	v_mfma_f32_16x16x32_bf16 v[76:79], v[132:135], v[188:191], v[76:79]
	v_mfma_f32_16x16x32_bf16 v[76:79], v[136:139], v[204:207], v[76:79]
	v_mfma_f32_16x16x32_bf16 v[92:95], v[132:135], v[180:183], v[92:95]
	v_mfma_f32_16x16x32_bf16 v[92:95], v[136:139], v[184:187], v[92:95]
	v_mfma_f32_16x16x32_bf16 v[108:111], v[132:135], v[172:175], v[108:111]
	v_mfma_f32_16x16x32_bf16 v[108:111], v[136:139], v[176:179], v[108:111]
	v_mfma_f32_16x16x32_bf16 v[156:159], v[132:135], v[164:167], v[156:159]
	v_mfma_f32_16x16x32_bf16 v[156:159], v[136:139], v[168:171], v[156:159]
	v_mfma_f32_16x16x32_bf16 v[124:127], v[140:143], v[164:167], v[124:127]
	v_mfma_f32_16x16x32_bf16 v[124:127], v[144:147], v[168:171], v[124:127]
	v_mfma_f32_16x16x32_bf16 v[104:107], v[140:143], v[172:175], v[104:107]
	v_mfma_f32_16x16x32_bf16 v[104:107], v[144:147], v[176:179], v[104:107]
	v_mfma_f32_16x16x32_bf16 v[88:91], v[140:143], v[180:183], v[88:91]
	v_mfma_f32_16x16x32_bf16 v[88:91], v[144:147], v[184:187], v[88:91]
	v_mfma_f32_16x16x32_bf16 v[72:75], v[140:143], v[188:191], v[72:75]
	v_mfma_f32_16x16x32_bf16 v[72:75], v[144:147], v[204:207], v[72:75]
	v_mfma_f32_16x16x32_bf16 v[68:71], v[148:151], v[188:191], v[68:71]
	v_mfma_f32_16x16x32_bf16 v[68:71], v[152:155], v[204:207], v[68:71]
	v_mfma_f32_16x16x32_bf16 v[84:87], v[148:151], v[180:183], v[84:87]
	v_mfma_f32_16x16x32_bf16 v[84:87], v[152:155], v[184:187], v[84:87]
	v_mfma_f32_16x16x32_bf16 v[100:103], v[148:151], v[172:175], v[100:103]
	v_mfma_f32_16x16x32_bf16 v[100:103], v[152:155], v[176:179], v[100:103]
	v_mfma_f32_16x16x32_bf16 v[120:123], v[148:151], v[164:167], v[120:123]
	v_mfma_f32_16x16x32_bf16 v[120:123], v[152:155], v[168:171], v[120:123]
	s_barrier
;     __device__ __forceinline__ int nt(const Unit& u) const { return (u.pn >> 1) < 2 ? 22 : 20; }
; #define PG8_STAGE(bufoff, gbase, voff) do { _Pragma("unroll") for (int _i = 0; _i < 2; ++_i) \
;         __builtin_amdgcn_global_load_lds((const unsigned*)((const char*)(gbase) + (voff)[_i]), (LAS unsigned*)(lds + (bufoff) + ldsw + _i * 8192), 16, 0, 0); } while (0)
; #define PG8_LDA(dst, b, h) do { _Pragma("unroll") for (int m = 0; m < 4; ++m) _Pragma("unroll") for (int k = 0; k < 2; ++k) dst[m][k] = *(const LAS bf16x8*)(pA + PG8_SA(b, h) + m * 2048 + k * 1024); } while (0)
; #define PG8_MMA(ai, bj, At, Bt) do { __builtin_amdgcn_s_setprio(1); _Pragma("unroll") for (int m = 0; m < 4; ++m) _Pragma("unroll") for (int n = 0; n < 2; ++n) _Pragma("unroll") for (int k = 0; k < 2; ++k) \
;         acc[ai][bj][m][n] = __builtin_amdgcn_mfma_f32_16x16x32_bf16(Bt[n][k], At[m][k], acc[ai][bj][m][n], 0, 0, 0); __builtin_amdgcn_s_setprio(0); } while (0)
; #define PG8_WAIT_V(n) asm volatile("s_waitcnt vmcnt(" #n ")" ::: "memory")
; #define PG8_WAIT_L(n) asm volatile("s_waitcnt lgkmcnt(" #n ")" ::: "memory")
; #define PG8_BAR __builtin_amdgcn_s_barrier()
; #define PG8_SCHED __builtin_amdgcn_sched_barrier(0)
; template <class Desc, class Epi, bool ALIGN_EPI>
; __device__ __forceinline__ void gemm_phase(LAS unsigned char* lds, const Desc& D, const Epi& E, int G, int c) {
;     ...
;         for (int t = 0; t < nt; t += 2) {
;     ...
;             PG8_LDA(At, 1, 1); PG8_STAGE(PG8_SB(1, 0), b3, voffB); PG8_STAGE(PG8_SB(1, 1), b3 + hstepB, voffB); PG8_STAGE(PG8_SA(1, 0), a3, voffA);
;             PG8_WAIT_V(8); PG8_WAIT_L(0); PG8_BAR; PG8_MMA(1, 0, At, B0); PG8_MMA(1, 1, At, B1); PG8_BAR; PG8_SCHED;
;         }
;         if constexpr (ALIGN_EPI) { if (wr == 0) PG8_BAR; }
	s_mov_b32 m0, s47
	v_lshl_add_u64 v[208:209], v[208:209], 0, s[76:77]
	s_add_u32 s12, s12, 0x20080
	ds_read_b128 v[164:167], v224 offset:49152
	ds_read_b128 v[168:171], v224 offset:50176
	ds_read_b128 v[172:175], v224 offset:51200
	ds_read_b128 v[176:179], v224 offset:52224
	ds_read_b128 v[180:183], v224 offset:53248
	ds_read_b128 v[184:187], v224 offset:54272
	ds_read_b128 v[188:191], v224 offset:55296
	ds_read_b128 v[204:207], v224 offset:56320
	global_load_lds_dwordx4 v[208:209], off
	v_lshl_add_u64 v[208:209], v[210:211], 0, s[76:77]
	s_mov_b32 m0, s48
	s_addc_u32 s13, s13, 0
	global_load_lds_dwordx4 v[208:209], off
	v_lshl_add_u64 v[208:209], s[12:13], 0, v[196:197]
	s_mov_b32 m0, s51
	s_nop 0
	global_load_lds_dwordx4 v[208:209], off
	v_lshl_add_u64 v[208:209], s[12:13], 0, v[192:193]
	s_mov_b32 m0, s52
	s_nop 0
	global_load_lds_dwordx4 v[208:209], off
	v_lshl_add_u64 v[208:209], v[212:213], 0, s[76:77]
	s_mov_b32 m0, s49
	s_nop 0
	global_load_lds_dwordx4 v[208:209], off
	v_lshl_add_u64 v[208:209], v[214:215], 0, s[76:77]
	s_mov_b32 m0, s50
	s_nop 0
	global_load_lds_dwordx4 v[208:209], off
	s_waitcnt vmcnt(8)
	s_waitcnt lgkmcnt(0)
	s_barrier
	v_mfma_f32_16x16x32_bf16 v[64:67], v[116:119], v[164:167], v[64:67]
	v_mfma_f32_16x16x32_bf16 v[64:67], v[128:131], v[168:171], v[64:67]
	v_mfma_f32_16x16x32_bf16 v[48:51], v[116:119], v[172:175], v[48:51]
	v_mfma_f32_16x16x32_bf16 v[48:51], v[128:131], v[176:179], v[48:51]
	v_mfma_f32_16x16x32_bf16 v[32:35], v[116:119], v[180:183], v[32:35]
	v_mfma_f32_16x16x32_bf16 v[32:35], v[128:131], v[184:187], v[32:35]
	v_mfma_f32_16x16x32_bf16 v[16:19], v[116:119], v[188:191], v[16:19]
	v_mfma_f32_16x16x32_bf16 v[16:19], v[128:131], v[204:207], v[16:19]
	v_mfma_f32_16x16x32_bf16 v[12:15], v[132:135], v[188:191], v[12:15]
	v_mfma_f32_16x16x32_bf16 v[12:15], v[136:139], v[204:207], v[12:15]
	v_mfma_f32_16x16x32_bf16 v[28:31], v[132:135], v[180:183], v[28:31]
	v_mfma_f32_16x16x32_bf16 v[28:31], v[136:139], v[184:187], v[28:31]
	v_mfma_f32_16x16x32_bf16 v[44:47], v[132:135], v[172:175], v[44:47]
	v_mfma_f32_16x16x32_bf16 v[44:47], v[136:139], v[176:179], v[44:47]
	v_mfma_f32_16x16x32_bf16 v[60:63], v[132:135], v[164:167], v[60:63]
	v_mfma_f32_16x16x32_bf16 v[60:63], v[136:139], v[168:171], v[60:63]
	v_mfma_f32_16x16x32_bf16 v[56:59], v[140:143], v[164:167], v[56:59]
	v_mfma_f32_16x16x32_bf16 v[56:59], v[144:147], v[168:171], v[56:59]
	v_mfma_f32_16x16x32_bf16 v[40:43], v[140:143], v[172:175], v[40:43]
	v_mfma_f32_16x16x32_bf16 v[40:43], v[144:147], v[176:179], v[40:43]
	v_mfma_f32_16x16x32_bf16 v[24:27], v[140:143], v[180:183], v[24:27]
	v_mfma_f32_16x16x32_bf16 v[24:27], v[144:147], v[184:187], v[24:27]
	v_mfma_f32_16x16x32_bf16 v[8:11], v[140:143], v[188:191], v[8:11]
	v_mfma_f32_16x16x32_bf16 v[8:11], v[144:147], v[204:207], v[8:11]
	v_mfma_f32_16x16x32_bf16 v[4:7], v[148:151], v[188:191], v[4:7]
	v_mfma_f32_16x16x32_bf16 v[4:7], v[152:155], v[204:207], v[4:7]
	v_mfma_f32_16x16x32_bf16 v[20:23], v[148:151], v[180:183], v[20:23]
	v_mfma_f32_16x16x32_bf16 v[20:23], v[152:155], v[184:187], v[20:23]
	v_mfma_f32_16x16x32_bf16 v[36:39], v[148:151], v[172:175], v[36:39]
	v_mfma_f32_16x16x32_bf16 v[36:39], v[152:155], v[176:179], v[36:39]
	v_mfma_f32_16x16x32_bf16 v[52:55], v[148:151], v[164:167], v[52:55]
	v_mfma_f32_16x16x32_bf16 v[52:55], v[152:155], v[168:171], v[52:55]
	s_barrier
	s_add_i32 s54, s54, 2
	s_add_u32 s0, s0, 0x100
	s_addc_u32 s1, s1, 0
	s_add_u32 s27, s27, 0x100
	s_addc_u32 s33, s33, 0
	s_cmp_gt_u32 s54, 5
	s_cbranch_scc0 .LBB0_1517
	s_and_b64 vcc, exec, s[10:11]
	s_cbranch_vccz .LBB0_1520
	s_barrier

;     __device__ __forceinline__ int nt(const Unit& u) const { return (u.pn >> 1) < 2 ? 22 : 20; }
; #define PG8_STAGE(bufoff, gbase, voff) do { _Pragma("unroll") for (int _i = 0; _i < 2; ++_i) \
;         __builtin_amdgcn_global_load_lds((const unsigned*)((const char*)(gbase) + (voff)[_i]), (LAS unsigned*)(lds + (bufoff) + ldsw + _i * 8192), 16, 0, 0); } while (0)
; #define PG8_LDA(dst, b, h) do { _Pragma("unroll") for (int m = 0; m < 4; ++m) _Pragma("unroll") for (int k = 0; k < 2; ++k) dst[m][k] = *(const LAS bf16x8*)(pA + PG8_SA(b, h) + m * 2048 + k * 1024); } while (0)
; #define PG8_LDB(dst, b, h) do { _Pragma("unroll") for (int n = 0; n < 2; ++n) _Pragma("unroll") for (int k = 0; k < 2; ++k) dst[n][k] = *(const LAS bf16x8*)(pB + (PG8_SB(b, h) - 4 * HTB) + n * 2048 + k * 1024); } while (0)
; #define PG8_MMA(ai, bj, At, Bt) do { __builtin_amdgcn_s_setprio(1); _Pragma("unroll") for (int m = 0; m < 4; ++m) _Pragma("unroll") for (int n = 0; n < 2; ++n) _Pragma("unroll") for (int k = 0; k < 2; ++k) \
;         acc[ai][bj][m][n] = __builtin_amdgcn_mfma_f32_16x16x32_bf16(Bt[n][k], At[m][k], acc[ai][bj][m][n], 0, 0, 0); __builtin_amdgcn_s_setprio(0); } while (0)
; #define PG8_WAIT_V(n) asm volatile("s_waitcnt vmcnt(" #n ")" ::: "memory")
; #define PG8_BAR __builtin_amdgcn_s_barrier()
; template <class Desc, class Epi, bool ALIGN_EPI>
; __device__ __forceinline__ void gemm_phase(LAS unsigned char* lds, const Desc& D, const Epi& E, int G, int c) {
;     ...
;         for (int t = 0; t < nt; t += 2) {
;             const bool last = (t == nt - 2);
;             if (last && has_next) PG8_AWAIT(nxt);
;             const char* a1 = cA + (size_t)(t + 1) * kstep;
;             const char* a2 = last ? nA : cA + (size_t)(t + 2) * kstep; const char* b2 = last ? nB : cB + (size_t)(t + 2) * kstep;
;             const char* a3 = a2 + kstep; const char* b3 = b2 + kstep;
;             PG8_LDB(B0, 0, 0); PG8_LDB(B1, 0, 1); PG8_SCHED; PG8_LDA(At, 0, 0); PG8_STAGE(PG8_SA(1, 1), a1 + hstepA, voffA);
;             PG8_WAIT_V(8); PG8_WAIT_L(0); PG8_BAR; PG8_MMA(0, 0, At, B0); PG8_MMA(0, 1, At, B1); PG8_BAR; PG8_SCHED;
;             PG8_LDA(At, 0, 1); PG8_STAGE(PG8_SB(0, 0), b2, voffB); PG8_STAGE(PG8_SB(0, 1), b2 + hstepB, voffB); PG8_STAGE(PG8_SA(0, 0), a2, voffA);
;             PG8_WAIT_V(8); PG8_WAIT_L(0); PG8_BAR; PG8_MMA(1, 0, At, B0); PG8_MMA(1, 1, At, B1); PG8_BAR; PG8_SCHED;
.LBB0_1580:
	s_or_b32 s14, s30, 1
	s_add_i32 s30, s30, 2
	s_mov_b32 s31, s15
	s_lshl_b64 s[72:73], s[14:15], 7
	s_lshl_b64 s[74:75], s[30:31], 7
	s_add_u32 s14, s18, s74
	ds_read_b128 v[140:143], v163
	ds_read_b128 v[144:147], v163 offset:1024
	ds_read_b128 v[148:151], v163 offset:2048
	ds_read_b128 v[152:155], v163 offset:3072
	ds_read_b128 v[156:159], v163 offset:16384
	ds_read_b128 v[166:169], v163 offset:17408
	ds_read_b128 v[170:173], v163 offset:18432
	ds_read_b128 v[174:177], v163 offset:19456
	s_addc_u32 s31, s19, s75
	s_and_b64 s[46:47], s[34:35], exec
	s_cselect_b32 s47, s43, s31
	s_cselect_b32 s46, s42, s14
	s_add_u32 s14, s20, s74
	s_addc_u32 s31, s21, s75
	s_and_b64 s[34:35], s[34:35], exec
	s_cselect_b32 s35, s3, s31
	s_cselect_b32 s34, s13, s14
	s_add_u32 s14, s18, s72
	s_addc_u32 s31, s19, s73
	s_add_u32 s72, s14, 0x100000
	s_addc_u32 s73, s31, 0
	s_add_i32 m0, s52, 0xc000
	ds_read_b128 v[178:181], v162
	ds_read_b128 v[182:185], v162 offset:1024
	ds_read_b128 v[186:189], v162 offset:2048
	ds_read_b128 v[190:193], v162 offset:3072
	ds_read_b128 v[194:197], v162 offset:4096
	ds_read_b128 v[198:201], v162 offset:5120
	ds_read_b128 v[202:205], v162 offset:6144
	ds_read_b128 v[206:209], v162 offset:7168
	global_load_lds_dwordx4 v132, s[72:73]
	s_add_i32 m0, s52, 0xe000
	s_nop 0
	global_load_lds_dwordx4 v136, s[72:73]
	s_waitcnt vmcnt(8)
	s_waitcnt lgkmcnt(0)
	s_barrier
	v_mfma_f32_16x16x32_bf16 v[128:131], v[140:143], v[178:181], v[128:131]
	v_mfma_f32_16x16x32_bf16 v[128:131], v[144:147], v[182:185], v[128:131]
	v_mfma_f32_16x16x32_bf16 v[120:123], v[140:143], v[186:189], v[120:123]
	v_mfma_f32_16x16x32_bf16 v[120:123], v[144:147], v[190:193], v[120:123]
	v_mfma_f32_16x16x32_bf16 v[112:115], v[140:143], v[194:197], v[112:115]
	v_mfma_f32_16x16x32_bf16 v[112:115], v[144:147], v[198:201], v[112:115]
	v_mfma_f32_16x16x32_bf16 v[104:107], v[140:143], v[202:205], v[104:107]
	v_mfma_f32_16x16x32_bf16 v[104:107], v[144:147], v[206:209], v[104:107]
	v_mfma_f32_16x16x32_bf16 v[100:103], v[148:151], v[202:205], v[100:103]
	v_mfma_f32_16x16x32_bf16 v[100:103], v[152:155], v[206:209], v[100:103]
	v_mfma_f32_16x16x32_bf16 v[108:111], v[148:151], v[194:197], v[108:111]
	v_mfma_f32_16x16x32_bf16 v[108:111], v[152:155], v[198:201], v[108:111]
	v_mfma_f32_16x16x32_bf16 v[116:119], v[148:151], v[186:189], v[116:119]
	v_mfma_f32_16x16x32_bf16 v[116:119], v[152:155], v[190:193], v[116:119]
	v_mfma_f32_16x16x32_bf16 v[124:127], v[148:151], v[178:181], v[124:127]
	v_mfma_f32_16x16x32_bf16 v[124:127], v[152:155], v[182:185], v[124:127]
	v_mfma_f32_16x16x32_bf16 v[96:99], v[156:159], v[178:181], v[96:99]
	v_mfma_f32_16x16x32_bf16 v[96:99], v[166:169], v[182:185], v[96:99]
	v_mfma_f32_16x16x32_bf16 v[88:91], v[156:159], v[186:189], v[88:91]
	v_mfma_f32_16x16x32_bf16 v[88:91], v[166:169], v[190:193], v[88:91]
	v_mfma_f32_16x16x32_bf16 v[80:83], v[156:159], v[194:197], v[80:83]
	v_mfma_f32_16x16x32_bf16 v[80:83], v[166:169], v[198:201], v[80:83]
	v_mfma_f32_16x16x32_bf16 v[72:75], v[156:159], v[202:205], v[72:75]
	v_mfma_f32_16x16x32_bf16 v[72:75], v[166:169], v[206:209], v[72:75]
	v_mfma_f32_16x16x32_bf16 v[68:71], v[170:173], v[202:205], v[68:71]
	v_mfma_f32_16x16x32_bf16 v[68:71], v[174:177], v[206:209], v[68:71]
	v_mfma_f32_16x16x32_bf16 v[76:79], v[170:173], v[194:197], v[76:79]
	v_mfma_f32_16x16x32_bf16 v[76:79], v[174:177], v[198:201], v[76:79]
	v_mfma_f32_16x16x32_bf16 v[84:87], v[170:173], v[186:189], v[84:87]
	v_mfma_f32_16x16x32_bf16 v[84:87], v[174:177], v[190:193], v[84:87]
	v_mfma_f32_16x16x32_bf16 v[92:95], v[170:173], v[178:181], v[92:95]
	v_mfma_f32_16x16x32_bf16 v[92:95], v[174:177], v[182:185], v[92:95]
	s_barrier
	s_mov_b32 m0, s53
	s_add_u32 s72, s34, 0x100000
	s_addc_u32 s73, s35, 0
	ds_read_b128 v[178:181], v162 offset:16384
	ds_read_b128 v[182:185], v162 offset:17408
	ds_read_b128 v[186:189], v162 offset:18432
	ds_read_b128 v[190:193], v162 offset:19456
	ds_read_b128 v[194:197], v162 offset:20480
	ds_read_b128 v[198:201], v162 offset:21504
	ds_read_b128 v[202:205], v162 offset:22528
	ds_read_b128 v[206:209], v162 offset:23552
	global_load_lds_dwordx4 v134, s[34:35]
	s_mov_b32 m0, s54
	s_nop 0
	global_load_lds_dwordx4 v138, s[34:35]
	s_mov_b32 m0, s55
	s_nop 0
	global_load_lds_dwordx4 v134, s[72:73]
	s_mov_b32 m0, s56
	s_nop 0
	global_load_lds_dwordx4 v138, s[72:73]
	s_mov_b32 m0, s52
	s_nop 0
	global_load_lds_dwordx4 v132, s[46:47]
	s_mov_b32 m0, s57
	s_nop 0
	global_load_lds_dwordx4 v136, s[46:47]
	s_waitcnt vmcnt(8)
	s_waitcnt lgkmcnt(0)
	s_barrier
; #define PG8_STAGE(bufoff, gbase, voff) do { _Pragma("unroll") for (int _i = 0; _i < 2; ++_i) \
;         __builtin_amdgcn_global_load_lds((const unsigned*)((const char*)(gbase) + (voff)[_i]), (LAS unsigned*)(lds + (bufoff) + ldsw + _i * 8192), 16, 0, 0); } while (0)
; #define PG8_LDA(dst, b, h) do { _Pragma("unroll") for (int m = 0; m < 4; ++m) _Pragma("unroll") for (int k = 0; k < 2; ++k) dst[m][k] = *(const LAS bf16x8*)(pA + PG8_SA(b, h) + m * 2048 + k * 1024); } while (0)
; #define PG8_LDB(dst, b, h) do { _Pragma("unroll") for (int n = 0; n < 2; ++n) _Pragma("unroll") for (int k = 0; k < 2; ++k) dst[n][k] = *(const LAS bf16x8*)(pB + (PG8_SB(b, h) - 4 * HTB) + n * 2048 + k * 1024); } while (0)
; #define PG8_MMA(ai, bj, At, Bt) do { __builtin_amdgcn_s_setprio(1); _Pragma("unroll") for (int m = 0; m < 4; ++m) _Pragma("unroll") for (int n = 0; n < 2; ++n) _Pragma("unroll") for (int k = 0; k < 2; ++k) \
;         acc[ai][bj][m][n] = __builtin_amdgcn_mfma_f32_16x16x32_bf16(Bt[n][k], At[m][k], acc[ai][bj][m][n], 0, 0, 0); __builtin_amdgcn_s_setprio(0); } while (0)
; #define PG8_WAIT_V(n) asm volatile("s_waitcnt vmcnt(" #n ")" ::: "memory")
; #define PG8_WAIT_L(n) asm volatile("s_waitcnt lgkmcnt(" #n ")" ::: "memory")
; #define PG8_BAR __builtin_amdgcn_s_barrier()
; #define PG8_SCHED __builtin_amdgcn_sched_barrier(0)
; template <class Desc, class Epi, bool ALIGN_EPI>
; __device__ __forceinline__ void gemm_phase(LAS unsigned char* lds, const Desc& D, const Epi& E, int G, int c) {
;     ...
;             PG8_WAIT_V(8); PG8_WAIT_L(0); PG8_BAR; PG8_MMA(1, 0, At, B0); PG8_MMA(1, 1, At, B1); PG8_BAR; PG8_SCHED;
;             PG8_LDB(B0, 1, 0); PG8_LDB(B1, 1, 1); PG8_SCHED; PG8_LDA(At, 1, 0); PG8_STAGE(PG8_SA(0, 1), a2 + hstepA, voffA);
;             PG8_WAIT_V(8); PG8_WAIT_L(0); PG8_BAR; PG8_MMA(0, 0, At, B0); PG8_MMA(0, 1, At, B1); PG8_BAR; PG8_SCHED;
	v_mfma_f32_16x16x32_bf16 v[64:67], v[140:143], v[178:181], v[64:67]
	v_mfma_f32_16x16x32_bf16 v[64:67], v[144:147], v[182:185], v[64:67]
	v_mfma_f32_16x16x32_bf16 v[32:35], v[140:143], v[186:189], v[32:35]
	v_mfma_f32_16x16x32_bf16 v[32:35], v[144:147], v[190:193], v[32:35]
	v_mfma_f32_16x16x32_bf16 v[16:19], v[140:143], v[194:197], v[16:19]
	v_mfma_f32_16x16x32_bf16 v[16:19], v[144:147], v[198:201], v[16:19]
	v_mfma_f32_16x16x32_bf16 v[8:11], v[140:143], v[202:205], v[8:11]
	v_mfma_f32_16x16x32_bf16 v[8:11], v[144:147], v[206:209], v[8:11]
	v_mfma_f32_16x16x32_bf16 v[4:7], v[148:151], v[202:205], v[4:7]
	v_mfma_f32_16x16x32_bf16 v[4:7], v[152:155], v[206:209], v[4:7]
	v_mfma_f32_16x16x32_bf16 v[12:15], v[148:151], v[194:197], v[12:15]
	v_mfma_f32_16x16x32_bf16 v[12:15], v[152:155], v[198:201], v[12:15]
	v_mfma_f32_16x16x32_bf16 v[20:23], v[148:151], v[186:189], v[20:23]
	v_mfma_f32_16x16x32_bf16 v[20:23], v[152:155], v[190:193], v[20:23]
	v_mfma_f32_16x16x32_bf16 v[52:55], v[148:151], v[178:181], v[52:55]
	v_mfma_f32_16x16x32_bf16 v[52:55], v[152:155], v[182:185], v[52:55]
	v_mfma_f32_16x16x32_bf16 v[60:63], v[156:159], v[178:181], v[60:63]
	v_mfma_f32_16x16x32_bf16 v[60:63], v[166:169], v[182:185], v[60:63]
	v_mfma_f32_16x16x32_bf16 v[48:51], v[156:159], v[186:189], v[48:51]
	v_mfma_f32_16x16x32_bf16 v[48:51], v[166:169], v[190:193], v[48:51]
	v_mfma_f32_16x16x32_bf16 v[40:43], v[156:159], v[194:197], v[40:43]
	v_mfma_f32_16x16x32_bf16 v[40:43], v[166:169], v[198:201], v[40:43]
	v_mfma_f32_16x16x32_bf16 v[28:31], v[156:159], v[202:205], v[28:31]
	v_mfma_f32_16x16x32_bf16 v[28:31], v[166:169], v[206:209], v[28:31]
	v_mfma_f32_16x16x32_bf16 v[24:27], v[170:173], v[202:205], v[24:27]
	v_mfma_f32_16x16x32_bf16 v[24:27], v[174:177], v[206:209], v[24:27]
	v_mfma_f32_16x16x32_bf16 v[36:39], v[170:173], v[194:197], v[36:39]
	v_mfma_f32_16x16x32_bf16 v[36:39], v[174:177], v[198:201], v[36:39]
	v_mfma_f32_16x16x32_bf16 v[44:47], v[170:173], v[186:189], v[44:47]
	v_mfma_f32_16x16x32_bf16 v[44:47], v[174:177], v[190:193], v[44:47]
	v_mfma_f32_16x16x32_bf16 v[56:59], v[170:173], v[178:181], v[56:59]
	v_mfma_f32_16x16x32_bf16 v[56:59], v[174:177], v[182:185], v[56:59]
	s_barrier
	ds_read_b128 v[140:143], v163 offset:32768
	ds_read_b128 v[144:147], v163 offset:33792
	ds_read_b128 v[148:151], v163 offset:34816
	ds_read_b128 v[152:155], v163 offset:35840
	ds_read_b128 v[156:159], v163 offset:49152
	ds_read_b128 v[166:169], v163 offset:50176
	ds_read_b128 v[170:173], v163 offset:51200
	ds_read_b128 v[174:177], v163 offset:52224
	s_add_u32 s46, s46, 0x100000
	s_addc_u32 s47, s47, 0
	s_mov_b32 m0, s58
	ds_read_b128 v[178:181], v162 offset:32768
	ds_read_b128 v[182:185], v162 offset:33792
	ds_read_b128 v[186:189], v162 offset:34816
	ds_read_b128 v[190:193], v162 offset:35840
	ds_read_b128 v[194:197], v162 offset:36864
	ds_read_b128 v[198:201], v162 offset:37888
	ds_read_b128 v[202:205], v162 offset:38912
	ds_read_b128 v[206:209], v162 offset:39936
	global_load_lds_dwordx4 v132, s[46:47]
	s_mov_b32 m0, s59
	s_nop 0
	global_load_lds_dwordx4 v136, s[46:47]
	s_waitcnt vmcnt(8)
	s_waitcnt lgkmcnt(0)
	s_barrier
	v_mfma_f32_16x16x32_bf16 v[128:131], v[140:143], v[178:181], v[128:131]
	v_mfma_f32_16x16x32_bf16 v[128:131], v[144:147], v[182:185], v[128:131]
	v_mfma_f32_16x16x32_bf16 v[120:123], v[140:143], v[186:189], v[120:123]
	v_mfma_f32_16x16x32_bf16 v[120:123], v[144:147], v[190:193], v[120:123]
	v_mfma_f32_16x16x32_bf16 v[112:115], v[140:143], v[194:197], v[112:115]
	v_mfma_f32_16x16x32_bf16 v[112:115], v[144:147], v[198:201], v[112:115]
	v_mfma_f32_16x16x32_bf16 v[104:107], v[140:143], v[202:205], v[104:107]
	v_mfma_f32_16x16x32_bf16 v[104:107], v[144:147], v[206:209], v[104:107]
	v_mfma_f32_16x16x32_bf16 v[100:103], v[148:151], v[202:205], v[100:103]
	v_mfma_f32_16x16x32_bf16 v[100:103], v[152:155], v[206:209], v[100:103]
	v_mfma_f32_16x16x32_bf16 v[108:111], v[148:151], v[194:197], v[108:111]
	v_mfma_f32_16x16x32_bf16 v[108:111], v[152:155], v[198:201], v[108:111]
	v_mfma_f32_16x16x32_bf16 v[116:119], v[148:151], v[186:189], v[116:119]
	v_mfma_f32_16x16x32_bf16 v[116:119], v[152:155], v[190:193], v[116:119]
	v_mfma_f32_16x16x32_bf16 v[124:127], v[148:151], v[178:181], v[124:127]
	v_mfma_f32_16x16x32_bf16 v[124:127], v[152:155], v[182:185], v[124:127]
	v_mfma_f32_16x16x32_bf16 v[96:99], v[156:159], v[178:181], v[96:99]
	v_mfma_f32_16x16x32_bf16 v[96:99], v[166:169], v[182:185], v[96:99]
	v_mfma_f32_16x16x32_bf16 v[88:91], v[156:159], v[186:189], v[88:91]
	v_mfma_f32_16x16x32_bf16 v[88:91], v[166:169], v[190:193], v[88:91]
	v_mfma_f32_16x16x32_bf16 v[80:83], v[156:159], v[194:197], v[80:83]
	v_mfma_f32_16x16x32_bf16 v[80:83], v[166:169], v[198:201], v[80:83]
	v_mfma_f32_16x16x32_bf16 v[72:75], v[156:159], v[202:205], v[72:75]
	v_mfma_f32_16x16x32_bf16 v[72:75], v[166:169], v[206:209], v[72:75]
	v_mfma_f32_16x16x32_bf16 v[68:71], v[170:173], v[202:205], v[68:71]
	v_mfma_f32_16x16x32_bf16 v[68:71], v[174:177], v[206:209], v[68:71]
	v_mfma_f32_16x16x32_bf16 v[76:79], v[170:173], v[194:197], v[76:79]
	v_mfma_f32_16x16x32_bf16 v[76:79], v[174:177], v[198:201], v[76:79]
	v_mfma_f32_16x16x32_bf16 v[84:87], v[170:173], v[186:189], v[84:87]
	v_mfma_f32_16x16x32_bf16 v[84:87], v[174:177], v[190:193], v[84:87]
	v_mfma_f32_16x16x32_bf16 v[92:95], v[170:173], v[178:181], v[92:95]
	v_mfma_f32_16x16x32_bf16 v[92:95], v[174:177], v[182:185], v[92:95]
	s_barrier
; #define PG8_STAGE(bufoff, gbase, voff) do { _Pragma("unroll") for (int _i = 0; _i < 2; ++_i) \
;         __builtin_amdgcn_global_load_lds((const unsigned*)((const char*)(gbase) + (voff)[_i]), (LAS unsigned*)(lds + (bufoff) + ldsw + _i * 8192), 16, 0, 0); } while (0)
; #define PG8_LDA(dst, b, h) do { _Pragma("unroll") for (int m = 0; m < 4; ++m) _Pragma("unroll") for (int k = 0; k < 2; ++k) dst[m][k] = *(const LAS bf16x8*)(pA + PG8_SA(b, h) + m * 2048 + k * 1024); } while (0)
; #define PG8_MMA(ai, bj, At, Bt) do { __builtin_amdgcn_s_setprio(1); _Pragma("unroll") for (int m = 0; m < 4; ++m) _Pragma("unroll") for (int n = 0; n < 2; ++n) _Pragma("unroll") for (int k = 0; k < 2; ++k) \
;         acc[ai][bj][m][n] = __builtin_amdgcn_mfma_f32_16x16x32_bf16(Bt[n][k], At[m][k], acc[ai][bj][m][n], 0, 0, 0); __builtin_amdgcn_s_setprio(0); } while (0)
; #define PG8_WAIT_V(n) asm volatile("s_waitcnt vmcnt(" #n ")" ::: "memory")
; #define PG8_WAIT_L(n) asm volatile("s_waitcnt lgkmcnt(" #n ")" ::: "memory")
; #define PG8_BAR __builtin_amdgcn_s_barrier()
; #define PG8_SCHED __builtin_amdgcn_sched_barrier(0)
; template <class Desc, class Epi, bool ALIGN_EPI>
; __device__ __forceinline__ void gemm_phase(LAS unsigned char* lds, const Desc& D, const Epi& E, int G, int c) {
;     ...
;             PG8_LDA(At, 1, 1); PG8_STAGE(PG8_SB(1, 0), b3, voffB); PG8_STAGE(PG8_SB(1, 1), b3 + hstepB, voffB); PG8_STAGE(PG8_SA(1, 0), a3, voffA);
;             PG8_WAIT_V(8); PG8_WAIT_L(0); PG8_BAR; PG8_MMA(1, 0, At, B0); PG8_MMA(1, 1, At, B1); PG8_BAR; PG8_SCHED;
;         }
	s_mov_b32 m0, s61
	s_add_u32 s74, s34, 0x80
	s_addc_u32 s75, s35, 0
	s_add_u32 s34, s34, 0x100080
	s_addc_u32 s35, s35, 0
	ds_read_b128 v[178:181], v162 offset:49152
	ds_read_b128 v[182:185], v162 offset:50176
	ds_read_b128 v[186:189], v162 offset:51200
	ds_read_b128 v[190:193], v162 offset:52224
	ds_read_b128 v[194:197], v162 offset:53248
	ds_read_b128 v[198:201], v162 offset:54272
	ds_read_b128 v[202:205], v162 offset:55296
	ds_read_b128 v[206:209], v162 offset:56320
	global_load_lds_dwordx4 v134, s[74:75]
	s_mov_b32 m0, s62
	s_nop 0
	global_load_lds_dwordx4 v138, s[74:75]
	s_mov_b32 m0, s65
	s_nop 0
	global_load_lds_dwordx4 v134, s[34:35]
	s_mov_b32 m0, s67
	s_nop 0
	global_load_lds_dwordx4 v138, s[34:35]
	s_sub_u32 s74, s46, 0xfff80
	s_subb_u32 s75, s47, 0
	s_mov_b32 m0, s63
	s_nop 0
	global_load_lds_dwordx4 v132, s[74:75]
	s_mov_b32 m0, s64
	s_nop 0
	global_load_lds_dwordx4 v136, s[74:75]
	s_waitcnt vmcnt(8)
	s_waitcnt lgkmcnt(0)
	s_barrier
	v_mfma_f32_16x16x32_bf16 v[64:67], v[140:143], v[178:181], v[64:67]
	v_mfma_f32_16x16x32_bf16 v[64:67], v[144:147], v[182:185], v[64:67]
	v_mfma_f32_16x16x32_bf16 v[32:35], v[140:143], v[186:189], v[32:35]
	v_mfma_f32_16x16x32_bf16 v[32:35], v[144:147], v[190:193], v[32:35]
	v_mfma_f32_16x16x32_bf16 v[16:19], v[140:143], v[194:197], v[16:19]
	v_mfma_f32_16x16x32_bf16 v[16:19], v[144:147], v[198:201], v[16:19]
	v_mfma_f32_16x16x32_bf16 v[8:11], v[140:143], v[202:205], v[8:11]
	v_mfma_f32_16x16x32_bf16 v[8:11], v[144:147], v[206:209], v[8:11]
	v_mfma_f32_16x16x32_bf16 v[4:7], v[148:151], v[202:205], v[4:7]
	v_mfma_f32_16x16x32_bf16 v[4:7], v[152:155], v[206:209], v[4:7]
	v_mfma_f32_16x16x32_bf16 v[12:15], v[148:151], v[194:197], v[12:15]
	v_mfma_f32_16x16x32_bf16 v[12:15], v[152:155], v[198:201], v[12:15]
	v_mfma_f32_16x16x32_bf16 v[20:23], v[148:151], v[186:189], v[20:23]
	v_mfma_f32_16x16x32_bf16 v[20:23], v[152:155], v[190:193], v[20:23]
	v_mfma_f32_16x16x32_bf16 v[52:55], v[148:151], v[178:181], v[52:55]
	v_mfma_f32_16x16x32_bf16 v[52:55], v[152:155], v[182:185], v[52:55]
	v_mfma_f32_16x16x32_bf16 v[60:63], v[156:159], v[178:181], v[60:63]
	v_mfma_f32_16x16x32_bf16 v[60:63], v[166:169], v[182:185], v[60:63]
	v_mfma_f32_16x16x32_bf16 v[48:51], v[156:159], v[186:189], v[48:51]
	v_mfma_f32_16x16x32_bf16 v[48:51], v[166:169], v[190:193], v[48:51]
	v_mfma_f32_16x16x32_bf16 v[40:43], v[156:159], v[194:197], v[40:43]
	v_mfma_f32_16x16x32_bf16 v[40:43], v[166:169], v[198:201], v[40:43]
	v_mfma_f32_16x16x32_bf16 v[28:31], v[156:159], v[202:205], v[28:31]
	v_mfma_f32_16x16x32_bf16 v[28:31], v[166:169], v[206:209], v[28:31]
	v_mfma_f32_16x16x32_bf16 v[24:27], v[170:173], v[202:205], v[24:27]
	v_mfma_f32_16x16x32_bf16 v[24:27], v[174:177], v[206:209], v[24:27]
	v_mfma_f32_16x16x32_bf16 v[36:39], v[170:173], v[194:197], v[36:39]
	v_mfma_f32_16x16x32_bf16 v[36:39], v[174:177], v[198:201], v[36:39]
	v_mfma_f32_16x16x32_bf16 v[44:47], v[170:173], v[186:189], v[44:47]
	v_mfma_f32_16x16x32_bf16 v[44:47], v[174:177], v[190:193], v[44:47]
	v_mfma_f32_16x16x32_bf16 v[56:59], v[170:173], v[178:181], v[56:59]
	v_mfma_f32_16x16x32_bf16 v[56:59], v[174:177], v[182:185], v[56:59]
	s_barrier
	s_cmp_ge_u32 s30, s2
	s_cbranch_scc1 .LBB0_1591

;     __device__ __forceinline__ int nt(const Unit& u) const { return (u.pn >> 1) < 2 ? 22 : 20; }
; #define PG8_STAGE(bufoff, gbase, voff) do { _Pragma("unroll") for (int _i = 0; _i < 2; ++_i) \
;         __builtin_amdgcn_global_load_lds((const unsigned*)((const char*)(gbase) + (voff)[_i]), (LAS unsigned*)(lds + (bufoff) + ldsw + _i * 8192), 16, 0, 0); } while (0)
; #define PG8_LDA(dst, b, h) do { _Pragma("unroll") for (int m = 0; m < 4; ++m) _Pragma("unroll") for (int k = 0; k < 2; ++k) dst[m][k] = *(const LAS bf16x8*)(pA + PG8_SA(b, h) + m * 2048 + k * 1024); } while (0)
; #define PG8_LDB(dst, b, h) do { _Pragma("unroll") for (int n = 0; n < 2; ++n) _Pragma("unroll") for (int k = 0; k < 2; ++k) dst[n][k] = *(const LAS bf16x8*)(pB + (PG8_SB(b, h) - 4 * HTB) + n * 2048 + k * 1024); } while (0)
; #define PG8_MMA(ai, bj, At, Bt) do { __builtin_amdgcn_s_setprio(1); _Pragma("unroll") for (int m = 0; m < 4; ++m) _Pragma("unroll") for (int n = 0; n < 2; ++n) _Pragma("unroll") for (int k = 0; k < 2; ++k) \
;         acc[ai][bj][m][n] = __builtin_amdgcn_mfma_f32_16x16x32_bf16(Bt[n][k], At[m][k], acc[ai][bj][m][n], 0, 0, 0); __builtin_amdgcn_s_setprio(0); } while (0)
; #define PG8_WAIT_V(n) asm volatile("s_waitcnt vmcnt(" #n ")" ::: "memory")
; #define PG8_WAIT_L(n) asm volatile("s_waitcnt lgkmcnt(" #n ")" ::: "memory")
; #define PG8_BAR __builtin_amdgcn_s_barrier()
; template <class Desc, class Epi, bool ALIGN_EPI>
; __device__ __forceinline__ void gemm_phase(LAS unsigned char* lds, const Desc& D, const Epi& E, int G, int c) {
;     ...
;         for (int t = 0; t < nt; t += 2) {
;             const bool last = (t == nt - 2);
;             if (last && has_next) PG8_AWAIT(nxt);
;             const char* a1 = cA + (size_t)(t + 1) * kstep;
;             const char* a2 = last ? nA : cA + (size_t)(t + 2) * kstep; const char* b2 = last ? nB : cB + (size_t)(t + 2) * kstep;
;             const char* a3 = a2 + kstep; const char* b3 = b2 + kstep;
;             PG8_LDB(B0, 0, 0); PG8_LDB(B1, 0, 1); PG8_SCHED; PG8_LDA(At, 0, 0); PG8_STAGE(PG8_SA(1, 1), a1 + hstepA, voffA);
;             PG8_WAIT_V(8); PG8_WAIT_L(0); PG8_BAR; PG8_MMA(0, 0, At, B0); PG8_MMA(0, 1, At, B1); PG8_BAR; PG8_SCHED;
;             PG8_LDA(At, 0, 1); PG8_STAGE(PG8_SB(0, 0), b2, voffB); PG8_STAGE(PG8_SB(0, 1), b2 + hstepB, voffB); PG8_STAGE(PG8_SA(0, 0), a2, voffA);
.LBB0_1765:
	s_or_b32 s14, s39, 1
	s_lshl_b64 s[40:41], s[14:15], 7
	s_add_i32 s14, s39, 2
	s_lshl_b64 s[42:43], s[14:15], 7
	s_add_u32 s39, s12, s42
	s_waitcnt lgkmcnt(0)
	ds_read_b128 v[132:135], v248
	ds_read_b128 v[136:139], v248 offset:1024
	ds_read_b128 v[140:143], v248 offset:2048
	ds_read_b128 v[144:147], v248 offset:3072
	ds_read_b128 v[148:151], v248 offset:16384
	ds_read_b128 v[152:155], v248 offset:17408
	ds_read_b128 v[156:159], v248 offset:18432
	ds_read_b128 v[160:163], v248 offset:19456
	s_addc_u32 s78, s13, s43
	s_and_b64 s[30:31], s[20:21], exec
	s_cselect_b32 s31, s49, s78
	s_cselect_b32 s30, s48, s39
	s_add_u32 s39, s16, s42
	s_addc_u32 s42, s17, s43
	s_and_b64 s[20:21], s[20:21], exec
	s_cselect_b32 s21, s51, s42
	s_cselect_b32 s20, s50, s39
	s_add_u32 s39, s12, s40
	s_addc_u32 s41, s13, s41
	s_add_u32 s40, s39, 0x2b0000
	s_addc_u32 s41, s41, 0
	v_lshl_add_u64 v[196:197], s[40:41], 0, v[200:201]
	s_add_i32 m0, s56, 0xc000
	ds_read_b128 v[164:167], v247
	ds_read_b128 v[168:171], v247 offset:1024
	ds_read_b128 v[172:175], v247 offset:2048
	ds_read_b128 v[176:179], v247 offset:3072
	ds_read_b128 v[180:183], v247 offset:4096
	ds_read_b128 v[184:187], v247 offset:5120
	ds_read_b128 v[188:191], v247 offset:6144
	ds_read_b128 v[192:195], v247 offset:7168
	global_load_lds_dwordx4 v[196:197], off
	v_lshl_add_u64 v[196:197], s[40:41], 0, v[204:205]
	s_add_i32 m0, s56, 0xe000
	s_nop 0
	global_load_lds_dwordx4 v[196:197], off
	s_waitcnt vmcnt(8)
	s_waitcnt lgkmcnt(0)
	s_barrier
	v_mfma_f32_16x16x32_bf16 v[128:131], v[132:135], v[164:167], v[128:131]
	v_mfma_f32_16x16x32_bf16 v[128:131], v[136:139], v[168:171], v[128:131]
	v_mfma_f32_16x16x32_bf16 v[120:123], v[132:135], v[172:175], v[120:123]
	v_mfma_f32_16x16x32_bf16 v[120:123], v[136:139], v[176:179], v[120:123]
	v_mfma_f32_16x16x32_bf16 v[112:115], v[132:135], v[180:183], v[112:115]
	v_mfma_f32_16x16x32_bf16 v[112:115], v[136:139], v[184:187], v[112:115]
	v_mfma_f32_16x16x32_bf16 v[104:107], v[132:135], v[188:191], v[104:107]
	v_mfma_f32_16x16x32_bf16 v[104:107], v[136:139], v[192:195], v[104:107]
	v_mfma_f32_16x16x32_bf16 v[100:103], v[140:143], v[188:191], v[100:103]
	v_mfma_f32_16x16x32_bf16 v[100:103], v[144:147], v[192:195], v[100:103]
	v_mfma_f32_16x16x32_bf16 v[108:111], v[140:143], v[180:183], v[108:111]
	v_mfma_f32_16x16x32_bf16 v[108:111], v[144:147], v[184:187], v[108:111]
	v_mfma_f32_16x16x32_bf16 v[116:119], v[140:143], v[172:175], v[116:119]
	v_mfma_f32_16x16x32_bf16 v[116:119], v[144:147], v[176:179], v[116:119]
	v_mfma_f32_16x16x32_bf16 v[124:127], v[140:143], v[164:167], v[124:127]
	v_mfma_f32_16x16x32_bf16 v[124:127], v[144:147], v[168:171], v[124:127]
	v_mfma_f32_16x16x32_bf16 v[96:99], v[148:151], v[164:167], v[96:99]
	v_mfma_f32_16x16x32_bf16 v[96:99], v[152:155], v[168:171], v[96:99]
	v_mfma_f32_16x16x32_bf16 v[88:91], v[148:151], v[172:175], v[88:91]
	v_mfma_f32_16x16x32_bf16 v[88:91], v[152:155], v[176:179], v[88:91]
	v_mfma_f32_16x16x32_bf16 v[64:67], v[148:151], v[180:183], v[64:67]
	v_mfma_f32_16x16x32_bf16 v[64:67], v[152:155], v[184:187], v[64:67]
	v_mfma_f32_16x16x32_bf16 v[32:35], v[148:151], v[188:191], v[32:35]
	v_mfma_f32_16x16x32_bf16 v[32:35], v[152:155], v[192:195], v[32:35]
	v_mfma_f32_16x16x32_bf16 v[20:23], v[156:159], v[188:191], v[20:23]
	v_mfma_f32_16x16x32_bf16 v[20:23], v[160:163], v[192:195], v[20:23]
	v_mfma_f32_16x16x32_bf16 v[52:55], v[156:159], v[180:183], v[52:55]
	v_mfma_f32_16x16x32_bf16 v[52:55], v[160:163], v[184:187], v[52:55]
	v_mfma_f32_16x16x32_bf16 v[80:83], v[156:159], v[172:175], v[80:83]
	v_mfma_f32_16x16x32_bf16 v[80:83], v[160:163], v[176:179], v[80:83]
	v_mfma_f32_16x16x32_bf16 v[92:95], v[156:159], v[164:167], v[92:95]
	v_mfma_f32_16x16x32_bf16 v[92:95], v[160:163], v[168:171], v[92:95]
	s_barrier
	s_mov_b32 m0, s57
	v_lshl_add_u64 v[196:197], s[20:21], 0, v[202:203]
	s_add_u32 s40, s20, 0x2b0000
	ds_read_b128 v[164:167], v247 offset:16384
	ds_read_b128 v[168:171], v247 offset:17408
	ds_read_b128 v[172:175], v247 offset:18432
	ds_read_b128 v[176:179], v247 offset:19456
	ds_read_b128 v[180:183], v247 offset:20480
	ds_read_b128 v[184:187], v247 offset:21504
	ds_read_b128 v[188:191], v247 offset:22528
	ds_read_b128 v[192:195], v247 offset:23552
	global_load_lds_dwordx4 v[196:197], off
	v_lshl_add_u64 v[198:199], s[20:21], 0, v[206:207]
	s_mov_b32 m0, s58
	s_addc_u32 s41, s21, 0
	global_load_lds_dwordx4 v[198:199], off
	v_lshl_add_u64 v[208:209], s[40:41], 0, v[202:203]
	s_mov_b32 m0, s59
	v_lshl_add_u64 v[210:211], s[30:31], 0, v[204:205]
	global_load_lds_dwordx4 v[208:209], off
	v_lshl_add_u64 v[208:209], s[40:41], 0, v[206:207]
	s_mov_b32 m0, s60
	s_nop 0
	global_load_lds_dwordx4 v[208:209], off
	v_lshl_add_u64 v[208:209], s[30:31], 0, v[200:201]
	s_mov_b32 m0, s56
	s_nop 0
	global_load_lds_dwordx4 v[208:209], off
	s_mov_b32 m0, s61
	s_nop 0
	global_load_lds_dwordx4 v[210:211], off
	s_waitcnt vmcnt(8)
	s_waitcnt lgkmcnt(0)
	s_barrier
; #define PG8_STAGE(bufoff, gbase, voff) do { _Pragma("unroll") for (int _i = 0; _i < 2; ++_i) \
;         __builtin_amdgcn_global_load_lds((const unsigned*)((const char*)(gbase) + (voff)[_i]), (LAS unsigned*)(lds + (bufoff) + ldsw + _i * 8192), 16, 0, 0); } while (0)
; #define PG8_LDA(dst, b, h) do { _Pragma("unroll") for (int m = 0; m < 4; ++m) _Pragma("unroll") for (int k = 0; k < 2; ++k) dst[m][k] = *(const LAS bf16x8*)(pA + PG8_SA(b, h) + m * 2048 + k * 1024); } while (0)
; #define PG8_LDB(dst, b, h) do { _Pragma("unroll") for (int n = 0; n < 2; ++n) _Pragma("unroll") for (int k = 0; k < 2; ++k) dst[n][k] = *(const LAS bf16x8*)(pB + (PG8_SB(b, h) - 4 * HTB) + n * 2048 + k * 1024); } while (0)
; #define PG8_MMA(ai, bj, At, Bt) do { __builtin_amdgcn_s_setprio(1); _Pragma("unroll") for (int m = 0; m < 4; ++m) _Pragma("unroll") for (int n = 0; n < 2; ++n) _Pragma("unroll") for (int k = 0; k < 2; ++k) \
;         acc[ai][bj][m][n] = __builtin_amdgcn_mfma_f32_16x16x32_bf16(Bt[n][k], At[m][k], acc[ai][bj][m][n], 0, 0, 0); __builtin_amdgcn_s_setprio(0); } while (0)
; #define PG8_WAIT_V(n) asm volatile("s_waitcnt vmcnt(" #n ")" ::: "memory")
; #define PG8_WAIT_L(n) asm volatile("s_waitcnt lgkmcnt(" #n ")" ::: "memory")
; #define PG8_BAR __builtin_amdgcn_s_barrier()
; #define PG8_SCHED __builtin_amdgcn_sched_barrier(0)
; template <class Desc, class Epi, bool ALIGN_EPI>
; __device__ __forceinline__ void gemm_phase(LAS unsigned char* lds, const Desc& D, const Epi& E, int G, int c) {
;     ...
;             PG8_WAIT_V(8); PG8_WAIT_L(0); PG8_BAR; PG8_MMA(1, 0, At, B0); PG8_MMA(1, 1, At, B1); PG8_BAR; PG8_SCHED;
;             PG8_LDB(B0, 1, 0); PG8_LDB(B1, 1, 1); PG8_SCHED; PG8_LDA(At, 1, 0); PG8_STAGE(PG8_SA(0, 1), a2 + hstepA, voffA);
;             PG8_WAIT_V(8); PG8_WAIT_L(0); PG8_BAR; PG8_MMA(0, 0, At, B0); PG8_MMA(0, 1, At, B1); PG8_BAR; PG8_SCHED;
	v_mfma_f32_16x16x32_bf16 v[84:87], v[132:135], v[164:167], v[84:87]
	v_mfma_f32_16x16x32_bf16 v[84:87], v[136:139], v[168:171], v[84:87]
	v_mfma_f32_16x16x32_bf16 v[72:75], v[132:135], v[172:175], v[72:75]
	v_mfma_f32_16x16x32_bf16 v[72:75], v[136:139], v[176:179], v[72:75]
	v_mfma_f32_16x16x32_bf16 v[60:63], v[132:135], v[180:183], v[60:63]
	v_mfma_f32_16x16x32_bf16 v[60:63], v[136:139], v[184:187], v[60:63]
	v_mfma_f32_16x16x32_bf16 v[48:51], v[132:135], v[188:191], v[48:51]
	v_mfma_f32_16x16x32_bf16 v[48:51], v[136:139], v[192:195], v[48:51]
	v_mfma_f32_16x16x32_bf16 v[44:47], v[140:143], v[188:191], v[44:47]
	v_mfma_f32_16x16x32_bf16 v[44:47], v[144:147], v[192:195], v[44:47]
	v_mfma_f32_16x16x32_bf16 v[56:59], v[140:143], v[180:183], v[56:59]
	v_mfma_f32_16x16x32_bf16 v[56:59], v[144:147], v[184:187], v[56:59]
	v_mfma_f32_16x16x32_bf16 v[68:71], v[140:143], v[172:175], v[68:71]
	v_mfma_f32_16x16x32_bf16 v[68:71], v[144:147], v[176:179], v[68:71]
	v_mfma_f32_16x16x32_bf16 v[76:79], v[140:143], v[164:167], v[76:79]
	v_mfma_f32_16x16x32_bf16 v[76:79], v[144:147], v[168:171], v[76:79]
	v_mfma_f32_16x16x32_bf16 v[40:43], v[148:151], v[164:167], v[40:43]
	v_mfma_f32_16x16x32_bf16 v[40:43], v[152:155], v[168:171], v[40:43]
	v_mfma_f32_16x16x32_bf16 v[28:31], v[148:151], v[172:175], v[28:31]
	v_mfma_f32_16x16x32_bf16 v[28:31], v[152:155], v[176:179], v[28:31]
	v_mfma_f32_16x16x32_bf16 v[16:19], v[148:151], v[180:183], v[16:19]
	v_mfma_f32_16x16x32_bf16 v[16:19], v[152:155], v[184:187], v[16:19]
	v_mfma_f32_16x16x32_bf16 v[8:11], v[148:151], v[188:191], v[8:11]
	v_mfma_f32_16x16x32_bf16 v[8:11], v[152:155], v[192:195], v[8:11]
	v_mfma_f32_16x16x32_bf16 v[4:7], v[156:159], v[188:191], v[4:7]
	v_mfma_f32_16x16x32_bf16 v[4:7], v[160:163], v[192:195], v[4:7]
	v_mfma_f32_16x16x32_bf16 v[12:15], v[156:159], v[180:183], v[12:15]
	v_mfma_f32_16x16x32_bf16 v[12:15], v[160:163], v[184:187], v[12:15]
	v_mfma_f32_16x16x32_bf16 v[24:27], v[156:159], v[172:175], v[24:27]
	v_mfma_f32_16x16x32_bf16 v[24:27], v[160:163], v[176:179], v[24:27]
	v_mfma_f32_16x16x32_bf16 v[36:39], v[156:159], v[164:167], v[36:39]
	v_mfma_f32_16x16x32_bf16 v[36:39], v[160:163], v[168:171], v[36:39]
	s_barrier
	ds_read_b128 v[132:135], v248 offset:32768
	ds_read_b128 v[136:139], v248 offset:33792
	ds_read_b128 v[140:143], v248 offset:34816
	ds_read_b128 v[144:147], v248 offset:35840
	ds_read_b128 v[148:151], v248 offset:49152
	ds_read_b128 v[152:155], v248 offset:50176
	ds_read_b128 v[156:159], v248 offset:51200
	ds_read_b128 v[160:163], v248 offset:52224
	s_add_u32 s30, s30, 0x2b0000
	s_addc_u32 s31, s31, 0
	s_mov_b32 m0, s62
	v_lshl_add_u64 v[212:213], s[30:31], 0, v[200:201]
	ds_read_b128 v[164:167], v247 offset:32768
	ds_read_b128 v[168:171], v247 offset:33792
	ds_read_b128 v[172:175], v247 offset:34816
	ds_read_b128 v[176:179], v247 offset:35840
	ds_read_b128 v[180:183], v247 offset:36864
	ds_read_b128 v[184:187], v247 offset:37888
	ds_read_b128 v[188:191], v247 offset:38912
	ds_read_b128 v[192:195], v247 offset:39936
	global_load_lds_dwordx4 v[212:213], off
	v_lshl_add_u64 v[212:213], s[30:31], 0, v[204:205]
	s_mov_b32 m0, s63
	s_nop 0
	global_load_lds_dwordx4 v[212:213], off
	s_waitcnt vmcnt(8)
	s_waitcnt lgkmcnt(0)
	s_barrier
	v_mfma_f32_16x16x32_bf16 v[128:131], v[132:135], v[164:167], v[128:131]
	v_mfma_f32_16x16x32_bf16 v[128:131], v[136:139], v[168:171], v[128:131]
	v_mfma_f32_16x16x32_bf16 v[120:123], v[132:135], v[172:175], v[120:123]
	v_mfma_f32_16x16x32_bf16 v[120:123], v[136:139], v[176:179], v[120:123]
	v_mfma_f32_16x16x32_bf16 v[112:115], v[132:135], v[180:183], v[112:115]
	v_mfma_f32_16x16x32_bf16 v[112:115], v[136:139], v[184:187], v[112:115]
	v_mfma_f32_16x16x32_bf16 v[104:107], v[132:135], v[188:191], v[104:107]
	v_mfma_f32_16x16x32_bf16 v[104:107], v[136:139], v[192:195], v[104:107]
	v_mfma_f32_16x16x32_bf16 v[100:103], v[140:143], v[188:191], v[100:103]
	v_mfma_f32_16x16x32_bf16 v[100:103], v[144:147], v[192:195], v[100:103]
	v_mfma_f32_16x16x32_bf16 v[108:111], v[140:143], v[180:183], v[108:111]
	v_mfma_f32_16x16x32_bf16 v[108:111], v[144:147], v[184:187], v[108:111]
	v_mfma_f32_16x16x32_bf16 v[116:119], v[140:143], v[172:175], v[116:119]
	v_mfma_f32_16x16x32_bf16 v[116:119], v[144:147], v[176:179], v[116:119]
	v_mfma_f32_16x16x32_bf16 v[124:127], v[140:143], v[164:167], v[124:127]
	v_mfma_f32_16x16x32_bf16 v[124:127], v[144:147], v[168:171], v[124:127]
	v_mfma_f32_16x16x32_bf16 v[96:99], v[148:151], v[164:167], v[96:99]
	v_mfma_f32_16x16x32_bf16 v[96:99], v[152:155], v[168:171], v[96:99]
	v_mfma_f32_16x16x32_bf16 v[88:91], v[148:151], v[172:175], v[88:91]
	v_mfma_f32_16x16x32_bf16 v[88:91], v[152:155], v[176:179], v[88:91]
	v_mfma_f32_16x16x32_bf16 v[64:67], v[148:151], v[180:183], v[64:67]
	v_mfma_f32_16x16x32_bf16 v[64:67], v[152:155], v[184:187], v[64:67]
	v_mfma_f32_16x16x32_bf16 v[32:35], v[148:151], v[188:191], v[32:35]
	v_mfma_f32_16x16x32_bf16 v[32:35], v[152:155], v[192:195], v[32:35]
	v_mfma_f32_16x16x32_bf16 v[20:23], v[156:159], v[188:191], v[20:23]
	v_mfma_f32_16x16x32_bf16 v[20:23], v[160:163], v[192:195], v[20:23]
	v_mfma_f32_16x16x32_bf16 v[52:55], v[156:159], v[180:183], v[52:55]
	v_mfma_f32_16x16x32_bf16 v[52:55], v[160:163], v[184:187], v[52:55]
	v_mfma_f32_16x16x32_bf16 v[80:83], v[156:159], v[172:175], v[80:83]
	v_mfma_f32_16x16x32_bf16 v[80:83], v[160:163], v[176:179], v[80:83]
	v_mfma_f32_16x16x32_bf16 v[92:95], v[156:159], v[164:167], v[92:95]
	v_mfma_f32_16x16x32_bf16 v[92:95], v[160:163], v[168:171], v[92:95]
	s_barrier
; #define PG8_STAGE(bufoff, gbase, voff) do { _Pragma("unroll") for (int _i = 0; _i < 2; ++_i) \
;         __builtin_amdgcn_global_load_lds((const unsigned*)((const char*)(gbase) + (voff)[_i]), (LAS unsigned*)(lds + (bufoff) + ldsw + _i * 8192), 16, 0, 0); } while (0)
; #define PG8_LDA(dst, b, h) do { _Pragma("unroll") for (int m = 0; m < 4; ++m) _Pragma("unroll") for (int k = 0; k < 2; ++k) dst[m][k] = *(const LAS bf16x8*)(pA + PG8_SA(b, h) + m * 2048 + k * 1024); } while (0)
; #define PG8_MMA(ai, bj, At, Bt) do { __builtin_amdgcn_s_setprio(1); _Pragma("unroll") for (int m = 0; m < 4; ++m) _Pragma("unroll") for (int n = 0; n < 2; ++n) _Pragma("unroll") for (int k = 0; k < 2; ++k) \
;         acc[ai][bj][m][n] = __builtin_amdgcn_mfma_f32_16x16x32_bf16(Bt[n][k], At[m][k], acc[ai][bj][m][n], 0, 0, 0); __builtin_amdgcn_s_setprio(0); } while (0)
; #define PG8_WAIT_V(n) asm volatile("s_waitcnt vmcnt(" #n ")" ::: "memory")
; #define PG8_WAIT_L(n) asm volatile("s_waitcnt lgkmcnt(" #n ")" ::: "memory")
; #define PG8_BAR __builtin_amdgcn_s_barrier()
; #define PG8_SCHED __builtin_amdgcn_sched_barrier(0)
; template <class Desc, class Epi, bool ALIGN_EPI>
; __device__ __forceinline__ void gemm_phase(LAS unsigned char* lds, const Desc& D, const Epi& E, int G, int c) {
;     ...
;             PG8_LDA(At, 1, 1); PG8_STAGE(PG8_SB(1, 0), b3, voffB); PG8_STAGE(PG8_SB(1, 1), b3 + hstepB, voffB); PG8_STAGE(PG8_SA(1, 0), a3, voffA);
;             PG8_WAIT_V(8); PG8_WAIT_L(0); PG8_BAR; PG8_MMA(1, 0, At, B0); PG8_MMA(1, 1, At, B1); PG8_BAR; PG8_SCHED;
;         }
	s_mov_b32 m0, s64
	v_lshl_add_u64 v[196:197], v[196:197], 0, s[76:77]
	s_add_u32 s20, s20, 0x2b0080
	ds_read_b128 v[164:167], v247 offset:49152
	ds_read_b128 v[168:171], v247 offset:50176
	ds_read_b128 v[172:175], v247 offset:51200
	ds_read_b128 v[176:179], v247 offset:52224
	ds_read_b128 v[180:183], v247 offset:53248
	ds_read_b128 v[184:187], v247 offset:54272
	ds_read_b128 v[188:191], v247 offset:55296
	ds_read_b128 v[192:195], v247 offset:56320
	global_load_lds_dwordx4 v[196:197], off
	v_lshl_add_u64 v[196:197], v[198:199], 0, s[76:77]
	s_mov_b32 m0, s65
	s_addc_u32 s21, s21, 0
	global_load_lds_dwordx4 v[196:197], off
	v_lshl_add_u64 v[196:197], s[20:21], 0, v[202:203]
	s_mov_b32 m0, s69
	s_nop 0
	global_load_lds_dwordx4 v[196:197], off
	v_lshl_add_u64 v[196:197], s[20:21], 0, v[206:207]
	s_mov_b32 m0, s70
	s_nop 0
	global_load_lds_dwordx4 v[196:197], off
	v_lshl_add_u64 v[196:197], v[208:209], 0, s[76:77]
	s_mov_b32 m0, s66
	s_nop 0
	global_load_lds_dwordx4 v[196:197], off
	v_lshl_add_u64 v[196:197], v[210:211], 0, s[76:77]
	s_mov_b32 m0, s67
	s_nop 0
	global_load_lds_dwordx4 v[196:197], off
	s_waitcnt vmcnt(8)
	s_waitcnt lgkmcnt(0)
	s_barrier
	v_mfma_f32_16x16x32_bf16 v[84:87], v[132:135], v[164:167], v[84:87]
	v_mfma_f32_16x16x32_bf16 v[84:87], v[136:139], v[168:171], v[84:87]
	v_mfma_f32_16x16x32_bf16 v[72:75], v[132:135], v[172:175], v[72:75]
	v_mfma_f32_16x16x32_bf16 v[72:75], v[136:139], v[176:179], v[72:75]
	v_mfma_f32_16x16x32_bf16 v[60:63], v[132:135], v[180:183], v[60:63]
	v_mfma_f32_16x16x32_bf16 v[60:63], v[136:139], v[184:187], v[60:63]
	v_mfma_f32_16x16x32_bf16 v[48:51], v[132:135], v[188:191], v[48:51]
	v_mfma_f32_16x16x32_bf16 v[48:51], v[136:139], v[192:195], v[48:51]
	v_mfma_f32_16x16x32_bf16 v[44:47], v[140:143], v[188:191], v[44:47]
	v_mfma_f32_16x16x32_bf16 v[44:47], v[144:147], v[192:195], v[44:47]
	v_mfma_f32_16x16x32_bf16 v[56:59], v[140:143], v[180:183], v[56:59]
	v_mfma_f32_16x16x32_bf16 v[56:59], v[144:147], v[184:187], v[56:59]
	v_mfma_f32_16x16x32_bf16 v[68:71], v[140:143], v[172:175], v[68:71]
	v_mfma_f32_16x16x32_bf16 v[68:71], v[144:147], v[176:179], v[68:71]
	v_mfma_f32_16x16x32_bf16 v[76:79], v[140:143], v[164:167], v[76:79]
	v_mfma_f32_16x16x32_bf16 v[76:79], v[144:147], v[168:171], v[76:79]
	v_mfma_f32_16x16x32_bf16 v[40:43], v[148:151], v[164:167], v[40:43]
	v_mfma_f32_16x16x32_bf16 v[40:43], v[152:155], v[168:171], v[40:43]
	v_mfma_f32_16x16x32_bf16 v[28:31], v[148:151], v[172:175], v[28:31]
	v_mfma_f32_16x16x32_bf16 v[28:31], v[152:155], v[176:179], v[28:31]
	v_mfma_f32_16x16x32_bf16 v[16:19], v[148:151], v[180:183], v[16:19]
	v_mfma_f32_16x16x32_bf16 v[16:19], v[152:155], v[184:187], v[16:19]
	v_mfma_f32_16x16x32_bf16 v[8:11], v[148:151], v[188:191], v[8:11]
	v_mfma_f32_16x16x32_bf16 v[8:11], v[152:155], v[192:195], v[8:11]
	v_mfma_f32_16x16x32_bf16 v[4:7], v[156:159], v[188:191], v[4:7]
	v_mfma_f32_16x16x32_bf16 v[4:7], v[160:163], v[192:195], v[4:7]
	v_mfma_f32_16x16x32_bf16 v[12:15], v[156:159], v[180:183], v[12:15]
	v_mfma_f32_16x16x32_bf16 v[12:15], v[160:163], v[184:187], v[12:15]
	v_mfma_f32_16x16x32_bf16 v[24:27], v[156:159], v[172:175], v[24:27]
	v_mfma_f32_16x16x32_bf16 v[24:27], v[160:163], v[176:179], v[24:27]
	v_mfma_f32_16x16x32_bf16 v[36:39], v[156:159], v[164:167], v[36:39]
	v_mfma_f32_16x16x32_bf16 v[36:39], v[160:163], v[168:171], v[36:39]
	s_barrier
	s_cmp_ge_u32 s14, s24
	s_mov_b32 s39, s14
	s_cbranch_scc1 .LBB0_1776
